# removed the 36 redundant lgkmcnt(0) waits behind the K-loop barriers (on phase 0 + gate load hoist)
# speedup vs baseline: 1.0018x; 1.0018x over previous
; #define PG8_STAGE(bufoff, gbase, voff) do { _Pragma("unroll") for (int _i = 0; _i < 2; ++_i) \
;         __builtin_amdgcn_global_load_lds((const unsigned*)((const char*)(gbase) + (voff)[_i]), (PG8_LAS unsigned*)(lds + (bufoff) + ldsw + _i * 8192), 16, 0, 0); } while (0)
; #define PG8_LDA(dst, b, h) do { _Pragma("unroll") for (int m = 0; m < 4; ++m) _Pragma("unroll") for (int k = 0; k < 2; ++k) dst[m][k] = *(const PG8_LAS bf16x8*)(lds + PG8_SA(b, h) + aoff + m * 2048 + k * 1024); } while (0)
; #define PG8_LDB(dst, b, h) do { _Pragma("unroll") for (int n = 0; n < 2; ++n) _Pragma("unroll") for (int k = 0; k < 2; ++k) dst[n][k] = *(const PG8_LAS bf16x8*)(lds + PG8_SB(b, h) + boff + n * 2048 + k * 1024); } while (0)
; #define PG8_MMA(ai, bj, At, Bt) do { __builtin_amdgcn_s_setprio(1); _Pragma("unroll") for (int m = 0; m < 4; ++m) _Pragma("unroll") for (int n = 0; n < 2; ++n) _Pragma("unroll") for (int k = 0; k < 2; ++k) \
;         acc[ai][bj][m][n] = __builtin_amdgcn_mfma_f32_16x16x32_bf16(Bt[n][k], At[m][k], acc[ai][bj][m][n], 0, 0, 0); __builtin_amdgcn_s_setprio(0); } while (0)
; #define PG8_WAIT_V(n) asm volatile("s_waitcnt vmcnt(" #n ")" ::: "memory")
; template <class Epi, class Sched, bool ALIGN_EPI = false, bool SP2 = false>
; __device__ __forceinline__ void gemm_phase(PG8_LAS unsigned char* lds, const Gemm g, const Sched& S, const Epi& E) {
;     ...
;             PG8_LDB(B0, 0, 0); PG8_LDB(B1, 0, 1); PG8_SCHED; PG8_LDA(At, 0, 0); PG8_STAGE(PG8_SA(1, 1), a1 + hstepA, voffA);
;             PG8_WAIT_V(8); PG8_WAIT_L(0); PG8_BAR; PG8_MMA(0, 0, At, B0); PG8_MMA(0, 1, At, B1); PG8_BAR; PG8_SCHED;
;             PG8_LDA(At, 0, 1); PG8_STAGE(PG8_SB(0, 0), b2, voffB); PG8_STAGE(PG8_SB(0, 1), b2 + hstepB, voffB); PG8_STAGE(PG8_SA(0, 0), a2, voffA);
;             PG8_WAIT_V(8); PG8_WAIT_L(0); PG8_BAR; PG8_MMA(1, 0, At, B0); PG8_MMA(1, 1, At, B1); PG8_BAR; PG8_SCHED;
;             PG8_LDB(B0, 1, 0); PG8_LDB(B1, 1, 1); PG8_SCHED; PG8_LDA(At, 1, 0); PG8_STAGE(PG8_SA(0, 1), a2 + hstepA, voffA);
;             PG8_WAIT_V(8); PG8_WAIT_L(0); PG8_BAR; PG8_MMA(0, 0, At, B0); PG8_MMA(0, 1, At, B1); PG8_BAR; PG8_SCHED;
;             PG8_LDA(At, 1, 1); PG8_STAGE(PG8_SB(1, 0), b3, voffB); PG8_STAGE(PG8_SB(1, 1), b3 + hstepB, voffB); PG8_STAGE(PG8_SA(1, 0), a3, voffA);
;             PG8_WAIT_V(8); PG8_WAIT_L(0); PG8_BAR; PG8_MMA(1, 0, At, B0); PG8_MMA(1, 1, At, B1); PG8_BAR; PG8_SCHED;
.LBB0_188:
	ds_read_b128 v[148:151], v160
	ds_read_b128 v[152:155], v160 offset:1024
	ds_read_b128 v[164:167], v160 offset:2048
	ds_read_b128 v[168:171], v160 offset:3072
	ds_read_b128 v[172:175], v161
	ds_read_b128 v[176:179], v161 offset:1024
	ds_read_b128 v[180:183], v161 offset:2048
	ds_read_b128 v[196:199], v161 offset:3072
	s_add_u32 s30, s28, 0xfff00080
	s_addc_u32 s31, s29, -1
	s_cmp_eq_u32 s57, 60
	s_cselect_b32 s35, s15, s31
	s_cselect_b32 s34, s53, s30
	s_cselect_b32 s31, s13, s56
	s_cselect_b32 s30, s54, s55
	v_lshl_add_u64 v[184:185], s[28:29], 0, v[140:141]
	s_add_i32 m0, s40, 0xc000
	ds_read_b128 v[200:203], v162
	ds_read_b128 v[204:207], v162 offset:1024
	ds_read_b128 v[208:211], v162 offset:2048
	ds_read_b128 v[212:215], v162 offset:3072
	ds_read_b128 v[216:219], v162 offset:4096
	ds_read_b128 v[220:223], v162 offset:5120
	ds_read_b128 v[224:227], v162 offset:6144
	ds_read_b128 v[228:231], v162 offset:7168
	global_load_lds_dwordx4 v[184:185], off
	v_lshl_add_u64 v[184:185], s[28:29], 0, v[142:143]
	s_add_i32 m0, s40, 0xe000
	s_nop 0
	global_load_lds_dwordx4 v[184:185], off
	s_waitcnt vmcnt(8)
	s_waitcnt lgkmcnt(0)
	s_barrier
	s_setprio 1
	v_mfma_f32_16x16x32_bf16 v[126:129], v[148:151], v[200:203], v[126:129]
	v_mfma_f32_16x16x32_bf16 v[122:125], v[164:167], v[200:203], v[122:125]
	v_mfma_f32_16x16x32_bf16 v[114:117], v[148:151], v[208:211], v[114:117]
	v_mfma_f32_16x16x32_bf16 v[106:109], v[164:167], v[208:211], v[106:109]
	v_mfma_f32_16x16x32_bf16 v[98:101], v[148:151], v[216:219], v[98:101]
	v_mfma_f32_16x16x32_bf16 v[90:93], v[164:167], v[216:219], v[90:93]
	v_mfma_f32_16x16x32_bf16 v[82:85], v[148:151], v[224:227], v[82:85]
	v_mfma_f32_16x16x32_bf16 v[74:77], v[164:167], v[224:227], v[74:77]
	v_mfma_f32_16x16x32_bf16 v[126:129], v[152:155], v[204:207], v[126:129]
	v_mfma_f32_16x16x32_bf16 v[122:125], v[168:171], v[204:207], v[122:125]
	v_mfma_f32_16x16x32_bf16 v[114:117], v[152:155], v[212:215], v[114:117]
	v_mfma_f32_16x16x32_bf16 v[106:109], v[168:171], v[212:215], v[106:109]
	v_mfma_f32_16x16x32_bf16 v[98:101], v[152:155], v[220:223], v[98:101]
	v_mfma_f32_16x16x32_bf16 v[90:93], v[168:171], v[220:223], v[90:93]
	v_mfma_f32_16x16x32_bf16 v[82:85], v[152:155], v[228:231], v[82:85]
	v_mfma_f32_16x16x32_bf16 v[74:77], v[168:171], v[228:231], v[74:77]
	s_setprio 0
	s_setprio 1
	v_mfma_f32_16x16x32_bf16 v[118:121], v[172:175], v[200:203], v[118:121]
	v_mfma_f32_16x16x32_bf16 v[110:113], v[180:183], v[200:203], v[110:113]
	v_mfma_f32_16x16x32_bf16 v[102:105], v[172:175], v[208:211], v[102:105]
	v_mfma_f32_16x16x32_bf16 v[94:97], v[180:183], v[208:211], v[94:97]
	v_mfma_f32_16x16x32_bf16 v[86:89], v[172:175], v[216:219], v[86:89]
	v_mfma_f32_16x16x32_bf16 v[78:81], v[180:183], v[216:219], v[78:81]
	v_mfma_f32_16x16x32_bf16 v[70:73], v[172:175], v[224:227], v[70:73]
	v_mfma_f32_16x16x32_bf16 v[66:69], v[180:183], v[224:227], v[66:69]
	v_mfma_f32_16x16x32_bf16 v[118:121], v[176:179], v[204:207], v[118:121]
	v_mfma_f32_16x16x32_bf16 v[110:113], v[196:199], v[204:207], v[110:113]
	v_mfma_f32_16x16x32_bf16 v[102:105], v[176:179], v[212:215], v[102:105]
	v_mfma_f32_16x16x32_bf16 v[94:97], v[196:199], v[212:215], v[94:97]
	v_mfma_f32_16x16x32_bf16 v[86:89], v[176:179], v[220:223], v[86:89]
	v_mfma_f32_16x16x32_bf16 v[78:81], v[196:199], v[220:223], v[78:81]
	v_mfma_f32_16x16x32_bf16 v[70:73], v[176:179], v[228:231], v[70:73]
	v_mfma_f32_16x16x32_bf16 v[66:69], v[196:199], v[228:231], v[66:69]
	s_setprio 0
	s_barrier
	s_add_i32 s58, s48, s27
	v_lshl_add_u64 v[184:185], s[30:31], 0, v[132:133]
	s_mov_b32 m0, s58
	ds_read_b128 v[200:203], v162 offset:16384
	ds_read_b128 v[204:207], v162 offset:17408
	ds_read_b128 v[208:211], v162 offset:18432
	ds_read_b128 v[212:215], v162 offset:19456
	ds_read_b128 v[216:219], v162 offset:20480
	ds_read_b128 v[220:223], v162 offset:21504
	ds_read_b128 v[224:227], v162 offset:22528
	ds_read_b128 v[228:231], v162 offset:23552
	global_load_lds_dwordx4 v[184:185], off
	s_add_i32 m0, s58, 0x2000
	s_add_u32 s58, s30, 0x100000
	v_lshl_add_u64 v[188:189], s[30:31], 0, v[136:137]
	s_addc_u32 s59, s31, 0
	s_add_i32 s60, s49, s27
	global_load_lds_dwordx4 v[188:189], off
	v_lshl_add_u64 v[232:233], s[58:59], 0, v[132:133]
	s_mov_b32 m0, s60
	v_lshl_add_u64 v[234:235], s[34:35], 0, v[134:135]
	global_load_lds_dwordx4 v[232:233], off
	v_lshl_add_u64 v[232:233], s[58:59], 0, v[136:137]
	s_add_i32 m0, s60, 0x2000
	s_nop 0
	global_load_lds_dwordx4 v[232:233], off
	v_lshl_add_u64 v[232:233], s[34:35], 0, v[130:131]
	s_mov_b32 m0, s40
	s_nop 0
	global_load_lds_dwordx4 v[232:233], off
	s_mov_b32 m0, s41
	s_nop 0
	global_load_lds_dwordx4 v[234:235], off
	s_waitcnt vmcnt(8)
	s_waitcnt lgkmcnt(0)
	s_barrier
; #define PG8_STAGE(bufoff, gbase, voff) do { _Pragma("unroll") for (int _i = 0; _i < 2; ++_i) \
;         __builtin_amdgcn_global_load_lds((const unsigned*)((const char*)(gbase) + (voff)[_i]), (PG8_LAS unsigned*)(lds + (bufoff) + ldsw + _i * 8192), 16, 0, 0); } while (0)
; #define PG8_LDA(dst, b, h) do { _Pragma("unroll") for (int m = 0; m < 4; ++m) _Pragma("unroll") for (int k = 0; k < 2; ++k) dst[m][k] = *(const PG8_LAS bf16x8*)(lds + PG8_SA(b, h) + aoff + m * 2048 + k * 1024); } while (0)
; #define PG8_LDB(dst, b, h) do { _Pragma("unroll") for (int n = 0; n < 2; ++n) _Pragma("unroll") for (int k = 0; k < 2; ++k) dst[n][k] = *(const PG8_LAS bf16x8*)(lds + PG8_SB(b, h) + boff + n * 2048 + k * 1024); } while (0)
; #define PG8_MMA(ai, bj, At, Bt) do { __builtin_amdgcn_s_setprio(1); _Pragma("unroll") for (int m = 0; m < 4; ++m) _Pragma("unroll") for (int n = 0; n < 2; ++n) _Pragma("unroll") for (int k = 0; k < 2; ++k) \
;         acc[ai][bj][m][n] = __builtin_amdgcn_mfma_f32_16x16x32_bf16(Bt[n][k], At[m][k], acc[ai][bj][m][n], 0, 0, 0); __builtin_amdgcn_s_setprio(0); } while (0)
; #define PG8_WAIT_V(n) asm volatile("s_waitcnt vmcnt(" #n ")" ::: "memory")
; #define PG8_WAIT_L(n) asm volatile("s_waitcnt lgkmcnt(" #n ")" ::: "memory")
; #define PG8_BAR __builtin_amdgcn_s_barrier()
; #define PG8_SCHED __builtin_amdgcn_sched_barrier(0)
; template <class Epi, class Sched, bool ALIGN_EPI = false, bool SP2 = false>
; __device__ __forceinline__ void gemm_phase(PG8_LAS unsigned char* lds, const Gemm g, const Sched& S, const Epi& E) {
;     ...
;             PG8_WAIT_V(8); PG8_WAIT_L(0); PG8_BAR; PG8_MMA(0, 0, At, B0); PG8_MMA(0, 1, At, B1); PG8_BAR; PG8_SCHED;
;             PG8_LDA(At, 0, 1); PG8_STAGE(PG8_SB(0, 0), b2, voffB); PG8_STAGE(PG8_SB(0, 1), b2 + hstepB, voffB); PG8_STAGE(PG8_SA(0, 0), a2, voffA);
;             PG8_WAIT_V(8); PG8_WAIT_L(0); PG8_BAR; PG8_MMA(1, 0, At, B0); PG8_MMA(1, 1, At, B1); PG8_BAR; PG8_SCHED;
;             PG8_LDB(B0, 1, 0); PG8_LDB(B1, 1, 1); PG8_SCHED; PG8_LDA(At, 1, 0); PG8_STAGE(PG8_SA(0, 1), a2 + hstepA, voffA);
;             PG8_WAIT_V(8); PG8_WAIT_L(0); PG8_BAR; PG8_MMA(0, 0, At, B0); PG8_MMA(0, 1, At, B1); PG8_BAR; PG8_SCHED;
	s_setprio 1
	v_mfma_f32_16x16x32_bf16 v[62:65], v[148:151], v[200:203], v[62:65]
	v_mfma_f32_16x16x32_bf16 v[58:61], v[164:167], v[200:203], v[58:61]
	v_mfma_f32_16x16x32_bf16 v[50:53], v[148:151], v[208:211], v[50:53]
	v_mfma_f32_16x16x32_bf16 v[42:45], v[164:167], v[208:211], v[42:45]
	v_mfma_f32_16x16x32_bf16 v[34:37], v[148:151], v[216:219], v[34:37]
	v_mfma_f32_16x16x32_bf16 v[26:29], v[164:167], v[216:219], v[26:29]
	v_mfma_f32_16x16x32_bf16 v[18:21], v[148:151], v[224:227], v[18:21]
	v_mfma_f32_16x16x32_bf16 v[10:13], v[164:167], v[224:227], v[10:13]
	v_mfma_f32_16x16x32_bf16 v[62:65], v[152:155], v[204:207], v[62:65]
	v_mfma_f32_16x16x32_bf16 v[58:61], v[168:171], v[204:207], v[58:61]
	v_mfma_f32_16x16x32_bf16 v[50:53], v[152:155], v[212:215], v[50:53]
	v_mfma_f32_16x16x32_bf16 v[42:45], v[168:171], v[212:215], v[42:45]
	v_mfma_f32_16x16x32_bf16 v[34:37], v[152:155], v[220:223], v[34:37]
	v_mfma_f32_16x16x32_bf16 v[26:29], v[168:171], v[220:223], v[26:29]
	v_mfma_f32_16x16x32_bf16 v[18:21], v[152:155], v[228:231], v[18:21]
	v_mfma_f32_16x16x32_bf16 v[10:13], v[168:171], v[228:231], v[10:13]
	s_setprio 0
	s_setprio 1
	v_mfma_f32_16x16x32_bf16 v[54:57], v[172:175], v[200:203], v[54:57]
	v_mfma_f32_16x16x32_bf16 v[46:49], v[180:183], v[200:203], v[46:49]
	v_mfma_f32_16x16x32_bf16 v[38:41], v[172:175], v[208:211], v[38:41]
	v_mfma_f32_16x16x32_bf16 v[30:33], v[180:183], v[208:211], v[30:33]
	v_mfma_f32_16x16x32_bf16 v[22:25], v[172:175], v[216:219], v[22:25]
	v_mfma_f32_16x16x32_bf16 v[14:17], v[180:183], v[216:219], v[14:17]
	v_mfma_f32_16x16x32_bf16 v[6:9], v[172:175], v[224:227], v[6:9]
	v_mfma_f32_16x16x32_bf16 v[2:5], v[180:183], v[224:227], v[2:5]
	v_mfma_f32_16x16x32_bf16 v[54:57], v[176:179], v[204:207], v[54:57]
	v_mfma_f32_16x16x32_bf16 v[46:49], v[196:199], v[204:207], v[46:49]
	v_mfma_f32_16x16x32_bf16 v[38:41], v[176:179], v[212:215], v[38:41]
	v_mfma_f32_16x16x32_bf16 v[30:33], v[196:199], v[212:215], v[30:33]
	v_mfma_f32_16x16x32_bf16 v[22:25], v[176:179], v[220:223], v[22:25]
	v_mfma_f32_16x16x32_bf16 v[14:17], v[196:199], v[220:223], v[14:17]
	v_mfma_f32_16x16x32_bf16 v[6:9], v[176:179], v[228:231], v[6:9]
	v_mfma_f32_16x16x32_bf16 v[2:5], v[196:199], v[228:231], v[2:5]
	s_setprio 0
	s_barrier
	s_add_i32 s58, 0, 0x18000
	v_add_u32_e32 v138, s58, v156
	s_add_i32 s59, 0, 0x1c000
	ds_read_b128 v[148:151], v138
	ds_read_b128 v[152:155], v138 offset:1024
	ds_read_b128 v[164:167], v138 offset:2048
	ds_read_b128 v[168:171], v138 offset:3072
	v_add_u32_e32 v138, s59, v156
	ds_read_b128 v[172:175], v138
	ds_read_b128 v[176:179], v138 offset:1024
	ds_read_b128 v[180:183], v138 offset:2048
	ds_read_b128 v[196:199], v138 offset:3072
	s_add_u32 s34, s34, 0x100000
	s_addc_u32 s35, s35, 0
	s_mov_b32 m0, s42
	v_lshl_add_u64 v[236:237], s[34:35], 0, v[130:131]
	ds_read_b128 v[200:203], v162 offset:32768
	ds_read_b128 v[204:207], v162 offset:33792
	ds_read_b128 v[208:211], v162 offset:34816
	ds_read_b128 v[212:215], v162 offset:35840
	ds_read_b128 v[216:219], v162 offset:36864
	ds_read_b128 v[220:223], v162 offset:37888
	ds_read_b128 v[224:227], v162 offset:38912
	ds_read_b128 v[228:231], v162 offset:39936
	global_load_lds_dwordx4 v[236:237], off
	v_lshl_add_u64 v[236:237], s[34:35], 0, v[134:135]
	s_mov_b32 m0, s43
	s_nop 0
	global_load_lds_dwordx4 v[236:237], off
	s_waitcnt vmcnt(8)
	s_waitcnt lgkmcnt(0)
	s_barrier
	s_setprio 1
	v_mfma_f32_16x16x32_bf16 v[126:129], v[148:151], v[200:203], v[126:129]
	v_mfma_f32_16x16x32_bf16 v[122:125], v[164:167], v[200:203], v[122:125]
	v_mfma_f32_16x16x32_bf16 v[114:117], v[148:151], v[208:211], v[114:117]
	v_mfma_f32_16x16x32_bf16 v[106:109], v[164:167], v[208:211], v[106:109]
	v_mfma_f32_16x16x32_bf16 v[98:101], v[148:151], v[216:219], v[98:101]
	v_mfma_f32_16x16x32_bf16 v[90:93], v[164:167], v[216:219], v[90:93]
	v_mfma_f32_16x16x32_bf16 v[82:85], v[148:151], v[224:227], v[82:85]
	v_mfma_f32_16x16x32_bf16 v[74:77], v[164:167], v[224:227], v[74:77]
	v_mfma_f32_16x16x32_bf16 v[126:129], v[152:155], v[204:207], v[126:129]
	v_mfma_f32_16x16x32_bf16 v[122:125], v[168:171], v[204:207], v[122:125]
	v_mfma_f32_16x16x32_bf16 v[114:117], v[152:155], v[212:215], v[114:117]
	v_mfma_f32_16x16x32_bf16 v[106:109], v[168:171], v[212:215], v[106:109]
	v_mfma_f32_16x16x32_bf16 v[98:101], v[152:155], v[220:223], v[98:101]
	v_mfma_f32_16x16x32_bf16 v[90:93], v[168:171], v[220:223], v[90:93]
	v_mfma_f32_16x16x32_bf16 v[82:85], v[152:155], v[228:231], v[82:85]
	v_mfma_f32_16x16x32_bf16 v[74:77], v[168:171], v[228:231], v[74:77]
	s_setprio 0
	s_setprio 1
	v_mfma_f32_16x16x32_bf16 v[118:121], v[172:175], v[200:203], v[118:121]
	v_mfma_f32_16x16x32_bf16 v[110:113], v[180:183], v[200:203], v[110:113]
	v_mfma_f32_16x16x32_bf16 v[102:105], v[172:175], v[208:211], v[102:105]
	v_mfma_f32_16x16x32_bf16 v[94:97], v[180:183], v[208:211], v[94:97]
	v_mfma_f32_16x16x32_bf16 v[86:89], v[172:175], v[216:219], v[86:89]
	v_mfma_f32_16x16x32_bf16 v[78:81], v[180:183], v[216:219], v[78:81]
	v_mfma_f32_16x16x32_bf16 v[70:73], v[172:175], v[224:227], v[70:73]
	v_mfma_f32_16x16x32_bf16 v[66:69], v[180:183], v[224:227], v[66:69]
	v_mfma_f32_16x16x32_bf16 v[118:121], v[176:179], v[204:207], v[118:121]
	v_mfma_f32_16x16x32_bf16 v[110:113], v[196:199], v[204:207], v[110:113]
	v_mfma_f32_16x16x32_bf16 v[102:105], v[176:179], v[212:215], v[102:105]
	v_mfma_f32_16x16x32_bf16 v[94:97], v[196:199], v[212:215], v[94:97]
	v_mfma_f32_16x16x32_bf16 v[86:89], v[176:179], v[220:223], v[86:89]
	v_mfma_f32_16x16x32_bf16 v[78:81], v[196:199], v[220:223], v[78:81]
	v_mfma_f32_16x16x32_bf16 v[70:73], v[176:179], v[228:231], v[70:73]
	v_mfma_f32_16x16x32_bf16 v[66:69], v[196:199], v[228:231], v[66:69]
	s_setprio 0
	s_barrier
; #define PG8_STAGE(bufoff, gbase, voff) do { _Pragma("unroll") for (int _i = 0; _i < 2; ++_i) \
;         __builtin_amdgcn_global_load_lds((const unsigned*)((const char*)(gbase) + (voff)[_i]), (PG8_LAS unsigned*)(lds + (bufoff) + ldsw + _i * 8192), 16, 0, 0); } while (0)
; #define PG8_LDA(dst, b, h) do { _Pragma("unroll") for (int m = 0; m < 4; ++m) _Pragma("unroll") for (int k = 0; k < 2; ++k) dst[m][k] = *(const PG8_LAS bf16x8*)(lds + PG8_SA(b, h) + aoff + m * 2048 + k * 1024); } while (0)
; #define PG8_MMA(ai, bj, At, Bt) do { __builtin_amdgcn_s_setprio(1); _Pragma("unroll") for (int m = 0; m < 4; ++m) _Pragma("unroll") for (int n = 0; n < 2; ++n) _Pragma("unroll") for (int k = 0; k < 2; ++k) \
;         acc[ai][bj][m][n] = __builtin_amdgcn_mfma_f32_16x16x32_bf16(Bt[n][k], At[m][k], acc[ai][bj][m][n], 0, 0, 0); __builtin_amdgcn_s_setprio(0); } while (0)
; #define PG8_WAIT_V(n) asm volatile("s_waitcnt vmcnt(" #n ")" ::: "memory")
; #define PG8_WAIT_L(n) asm volatile("s_waitcnt lgkmcnt(" #n ")" ::: "memory")
; #define PG8_BAR __builtin_amdgcn_s_barrier()
; #define PG8_SCHED __builtin_amdgcn_sched_barrier(0)
; template <class Epi, class Sched, bool ALIGN_EPI = false, bool SP2 = false>
; __device__ __forceinline__ void gemm_phase(PG8_LAS unsigned char* lds, const Gemm g, const Sched& S, const Epi& E) {
;     ...
;         for (int t = 0; t < nt; t += 2) {
;     ...
;             PG8_LDA(At, 1, 1); PG8_STAGE(PG8_SB(1, 0), b3, voffB); PG8_STAGE(PG8_SB(1, 1), b3 + hstepB, voffB); PG8_STAGE(PG8_SA(1, 0), a3, voffA);
;             PG8_WAIT_V(8); PG8_WAIT_L(0); PG8_BAR; PG8_MMA(1, 0, At, B0); PG8_MMA(1, 1, At, B1); PG8_BAR; PG8_SCHED;
	s_add_i32 s34, s58, s27
	v_lshl_add_u64 v[184:185], v[184:185], 0, s[8:9]
	s_mov_b32 m0, s34
	ds_read_b128 v[200:203], v162 offset:49152
	ds_read_b128 v[204:207], v162 offset:50176
	ds_read_b128 v[208:211], v162 offset:51200
	ds_read_b128 v[212:215], v162 offset:52224
	ds_read_b128 v[216:219], v162 offset:53248
	ds_read_b128 v[220:223], v162 offset:54272
	ds_read_b128 v[224:227], v162 offset:55296
	ds_read_b128 v[228:231], v162 offset:56320
	global_load_lds_dwordx4 v[184:185], off
	s_add_i32 m0, s34, 0x2000
	s_add_u32 s30, s30, 0x100080
	v_lshl_add_u64 v[184:185], v[188:189], 0, s[8:9]
	s_addc_u32 s31, s31, 0
	s_add_i32 s34, s59, s27
	global_load_lds_dwordx4 v[184:185], off
	v_lshl_add_u64 v[184:185], s[30:31], 0, v[132:133]
	s_mov_b32 m0, s34
	s_nop 0
	global_load_lds_dwordx4 v[184:185], off
	v_lshl_add_u64 v[184:185], s[30:31], 0, v[136:137]
	s_add_i32 m0, s34, 0x2000
	s_nop 0
	global_load_lds_dwordx4 v[184:185], off
	v_lshl_add_u64 v[184:185], v[232:233], 0, s[8:9]
	s_mov_b32 m0, s44
	s_nop 0
	global_load_lds_dwordx4 v[184:185], off
	v_lshl_add_u64 v[184:185], v[234:235], 0, s[8:9]
	s_mov_b32 m0, s45
	s_nop 0
	global_load_lds_dwordx4 v[184:185], off
	s_waitcnt vmcnt(8)
	s_waitcnt lgkmcnt(0)
	s_barrier
	s_setprio 1
	v_mfma_f32_16x16x32_bf16 v[62:65], v[148:151], v[200:203], v[62:65]
	v_mfma_f32_16x16x32_bf16 v[58:61], v[164:167], v[200:203], v[58:61]
	v_mfma_f32_16x16x32_bf16 v[50:53], v[148:151], v[208:211], v[50:53]
	v_mfma_f32_16x16x32_bf16 v[42:45], v[164:167], v[208:211], v[42:45]
	v_mfma_f32_16x16x32_bf16 v[34:37], v[148:151], v[216:219], v[34:37]
	v_mfma_f32_16x16x32_bf16 v[26:29], v[164:167], v[216:219], v[26:29]
	v_mfma_f32_16x16x32_bf16 v[18:21], v[148:151], v[224:227], v[18:21]
	v_mfma_f32_16x16x32_bf16 v[10:13], v[164:167], v[224:227], v[10:13]
	v_mfma_f32_16x16x32_bf16 v[62:65], v[152:155], v[204:207], v[62:65]
	v_mfma_f32_16x16x32_bf16 v[58:61], v[168:171], v[204:207], v[58:61]
	v_mfma_f32_16x16x32_bf16 v[50:53], v[152:155], v[212:215], v[50:53]
	v_mfma_f32_16x16x32_bf16 v[42:45], v[168:171], v[212:215], v[42:45]
	v_mfma_f32_16x16x32_bf16 v[34:37], v[152:155], v[220:223], v[34:37]
	v_mfma_f32_16x16x32_bf16 v[26:29], v[168:171], v[220:223], v[26:29]
	v_mfma_f32_16x16x32_bf16 v[18:21], v[152:155], v[228:231], v[18:21]
	v_mfma_f32_16x16x32_bf16 v[10:13], v[168:171], v[228:231], v[10:13]
	s_setprio 0
	s_setprio 1
	v_mfma_f32_16x16x32_bf16 v[54:57], v[172:175], v[200:203], v[54:57]
	v_mfma_f32_16x16x32_bf16 v[46:49], v[180:183], v[200:203], v[46:49]
	v_mfma_f32_16x16x32_bf16 v[38:41], v[172:175], v[208:211], v[38:41]
	v_mfma_f32_16x16x32_bf16 v[30:33], v[180:183], v[208:211], v[30:33]
	v_mfma_f32_16x16x32_bf16 v[22:25], v[172:175], v[216:219], v[22:25]
	v_mfma_f32_16x16x32_bf16 v[14:17], v[180:183], v[216:219], v[14:17]
	v_mfma_f32_16x16x32_bf16 v[6:9], v[172:175], v[224:227], v[6:9]
	v_mfma_f32_16x16x32_bf16 v[2:5], v[180:183], v[224:227], v[2:5]
	v_mfma_f32_16x16x32_bf16 v[54:57], v[176:179], v[204:207], v[54:57]
	v_mfma_f32_16x16x32_bf16 v[46:49], v[196:199], v[204:207], v[46:49]
	v_mfma_f32_16x16x32_bf16 v[38:41], v[176:179], v[212:215], v[38:41]
	v_mfma_f32_16x16x32_bf16 v[30:33], v[196:199], v[212:215], v[30:33]
	v_mfma_f32_16x16x32_bf16 v[22:25], v[176:179], v[220:223], v[22:25]
	v_mfma_f32_16x16x32_bf16 v[14:17], v[196:199], v[220:223], v[14:17]
	v_mfma_f32_16x16x32_bf16 v[6:9], v[176:179], v[228:231], v[6:9]
	v_mfma_f32_16x16x32_bf16 v[2:5], v[196:199], v[228:231], v[2:5]
	s_setprio 0
	s_barrier
	s_add_i32 s57, s57, 2
	s_add_u32 s28, s28, 0x100
	s_addc_u32 s29, s29, 0
	s_add_u32 s55, s55, 0x100
	s_addc_u32 s56, s56, 0
	s_cmp_gt_u32 s57, 61
	s_cbranch_scc0 .LBB0_188
	s_and_b64 vcc, exec, s[10:11]
	s_cbranch_vccz .LBB0_191
	s_barrier

; #define PG8_STAGE(bufoff, gbase, voff) do { _Pragma("unroll") for (int _i = 0; _i < 2; ++_i) \
;         __builtin_amdgcn_global_load_lds((const unsigned*)((const char*)(gbase) + (voff)[_i]), (PG8_LAS unsigned*)(lds + (bufoff) + ldsw + _i * 8192), 16, 0, 0); } while (0)
; #define PG8_LDA(dst, b, h) do { _Pragma("unroll") for (int m = 0; m < 4; ++m) _Pragma("unroll") for (int k = 0; k < 2; ++k) dst[m][k] = *(const PG8_LAS bf16x8*)(lds + PG8_SA(b, h) + aoff + m * 2048 + k * 1024); } while (0)
; #define PG8_LDB(dst, b, h) do { _Pragma("unroll") for (int n = 0; n < 2; ++n) _Pragma("unroll") for (int k = 0; k < 2; ++k) dst[n][k] = *(const PG8_LAS bf16x8*)(lds + PG8_SB(b, h) + boff + n * 2048 + k * 1024); } while (0)
; #define PG8_MMA(ai, bj, At, Bt) do { __builtin_amdgcn_s_setprio(1); _Pragma("unroll") for (int m = 0; m < 4; ++m) _Pragma("unroll") for (int n = 0; n < 2; ++n) _Pragma("unroll") for (int k = 0; k < 2; ++k) \
;         acc[ai][bj][m][n] = __builtin_amdgcn_mfma_f32_16x16x32_bf16(Bt[n][k], At[m][k], acc[ai][bj][m][n], 0, 0, 0); __builtin_amdgcn_s_setprio(0); } while (0)
; #define PG8_WAIT_V(n) asm volatile("s_waitcnt vmcnt(" #n ")" ::: "memory")
; #define PG8_WAIT_L(n) asm volatile("s_waitcnt lgkmcnt(" #n ")" ::: "memory")
; #define PG8_BAR __builtin_amdgcn_s_barrier()
; #define PG8_SCHED __builtin_amdgcn_sched_barrier(0)
; template <class Epi, class Sched, bool ALIGN_EPI = false, bool SP2 = false>
; __device__ __forceinline__ void gemm_phase(PG8_LAS unsigned char* lds, const Gemm g, const Sched& S, const Epi& E) {
;     ...
;             PG8_LDB(B0, 0, 0); PG8_LDB(B1, 0, 1); PG8_SCHED; PG8_LDA(At, 0, 0); PG8_STAGE(PG8_SA(1, 1), a1 + hstepA, voffA);
;             PG8_WAIT_V(8); PG8_WAIT_L(0); PG8_BAR; PG8_MMA(0, 0, At, B0); PG8_MMA(0, 1, At, B1); PG8_BAR; PG8_SCHED;
;             PG8_LDA(At, 0, 1); PG8_STAGE(PG8_SB(0, 0), b2, voffB); PG8_STAGE(PG8_SB(0, 1), b2 + hstepB, voffB); PG8_STAGE(PG8_SA(0, 0), a2, voffA);
;             PG8_WAIT_V(8); PG8_WAIT_L(0); PG8_BAR; PG8_MMA(1, 0, At, B0); PG8_MMA(1, 1, At, B1); PG8_BAR; PG8_SCHED;
.LBB0_642:
	v_add_u32_e32 v3, s54, v189
	ds_read_b128 v[136:139], v3
	ds_read_b128 v[140:143], v3 offset:1024
	ds_read_b128 v[144:147], v3 offset:2048
	ds_read_b128 v[148:151], v3 offset:3072
	v_add_u32_e32 v3, s55, v189
	ds_read_b128 v[152:155], v3
	ds_read_b128 v[174:177], v3 offset:1024
	ds_read_b128 v[178:181], v3 offset:2048
	ds_read_b128 v[182:185], v3 offset:3072
	s_add_u32 s6, s38, 0xffe00080
	s_addc_u32 s7, s39, -1
	s_cmp_eq_u32 s62, 0
	s_cselect_b32 s8, s58, s6
	s_cselect_b32 s6, s59, s60
	s_cselect_b32 s9, s27, s7
	s_cselect_b32 s7, s25, s61
	v_lshl_add_u64 v[4:5], s[38:39], 0, v[166:167]
	s_add_i32 m0, s35, 0xc000
	ds_read_b128 v[196:199], v210
	ds_read_b128 v[200:203], v210 offset:1024
	ds_read_b128 v[204:207], v210 offset:2048
	ds_read_b128 v[212:215], v210 offset:3072
	ds_read_b128 v[216:219], v210 offset:4096
	ds_read_b128 v[220:223], v210 offset:5120
	ds_read_b128 v[224:227], v210 offset:6144
	ds_read_b128 v[228:231], v210 offset:7168
	global_load_lds_dwordx4 v[4:5], off
	v_lshl_add_u64 v[4:5], s[38:39], 0, v[168:169]
	s_add_i32 m0, s35, 0xe000
	s_nop 0
	global_load_lds_dwordx4 v[4:5], off
	s_waitcnt vmcnt(8)
	s_waitcnt lgkmcnt(0)
	s_barrier
	s_setprio 1
	v_mfma_f32_16x16x32_bf16 v[130:133], v[136:139], v[196:199], v[130:133]
	v_mfma_f32_16x16x32_bf16 v[126:129], v[144:147], v[196:199], v[126:129]
	v_mfma_f32_16x16x32_bf16 v[114:117], v[136:139], v[204:207], v[114:117]
	v_mfma_f32_16x16x32_bf16 v[110:113], v[144:147], v[204:207], v[110:113]
	v_mfma_f32_16x16x32_bf16 v[98:101], v[136:139], v[216:219], v[98:101]
	v_mfma_f32_16x16x32_bf16 v[94:97], v[144:147], v[216:219], v[94:97]
	v_mfma_f32_16x16x32_bf16 v[82:85], v[136:139], v[224:227], v[82:85]
	v_mfma_f32_16x16x32_bf16 v[78:81], v[144:147], v[224:227], v[78:81]
	v_mfma_f32_16x16x32_bf16 v[130:133], v[140:143], v[200:203], v[130:133]
	v_mfma_f32_16x16x32_bf16 v[126:129], v[148:151], v[200:203], v[126:129]
	v_mfma_f32_16x16x32_bf16 v[114:117], v[140:143], v[212:215], v[114:117]
	v_mfma_f32_16x16x32_bf16 v[110:113], v[148:151], v[212:215], v[110:113]
	v_mfma_f32_16x16x32_bf16 v[98:101], v[140:143], v[220:223], v[98:101]
	v_mfma_f32_16x16x32_bf16 v[94:97], v[148:151], v[220:223], v[94:97]
	v_mfma_f32_16x16x32_bf16 v[82:85], v[140:143], v[228:231], v[82:85]
	v_mfma_f32_16x16x32_bf16 v[78:81], v[148:151], v[228:231], v[78:81]
	s_setprio 0
	s_setprio 1
	v_mfma_f32_16x16x32_bf16 v[122:125], v[152:155], v[196:199], v[122:125]
	v_mfma_f32_16x16x32_bf16 v[118:121], v[178:181], v[196:199], v[118:121]
	v_mfma_f32_16x16x32_bf16 v[106:109], v[152:155], v[204:207], v[106:109]
	v_mfma_f32_16x16x32_bf16 v[102:105], v[178:181], v[204:207], v[102:105]
	v_mfma_f32_16x16x32_bf16 v[90:93], v[152:155], v[216:219], v[90:93]
	v_mfma_f32_16x16x32_bf16 v[86:89], v[178:181], v[216:219], v[86:89]
	v_mfma_f32_16x16x32_bf16 v[74:77], v[152:155], v[224:227], v[74:77]
	v_mfma_f32_16x16x32_bf16 v[70:73], v[178:181], v[224:227], v[70:73]
	v_mfma_f32_16x16x32_bf16 v[122:125], v[174:177], v[200:203], v[122:125]
	v_mfma_f32_16x16x32_bf16 v[118:121], v[182:185], v[200:203], v[118:121]
	v_mfma_f32_16x16x32_bf16 v[106:109], v[174:177], v[212:215], v[106:109]
	v_mfma_f32_16x16x32_bf16 v[102:105], v[182:185], v[212:215], v[102:105]
	v_mfma_f32_16x16x32_bf16 v[90:93], v[174:177], v[220:223], v[90:93]
	v_mfma_f32_16x16x32_bf16 v[86:89], v[182:185], v[220:223], v[86:89]
	v_mfma_f32_16x16x32_bf16 v[74:77], v[174:177], v[228:231], v[74:77]
	v_mfma_f32_16x16x32_bf16 v[70:73], v[182:185], v[228:231], v[70:73]
	s_setprio 0
	s_barrier
	s_add_i32 s40, s54, s45
	v_lshl_add_u64 v[156:157], s[6:7], 0, v[160:161]
	s_mov_b32 m0, s40
	ds_read_b128 v[196:199], v210 offset:16384
	ds_read_b128 v[200:203], v210 offset:17408
	ds_read_b128 v[204:207], v210 offset:18432
	ds_read_b128 v[212:215], v210 offset:19456
	ds_read_b128 v[216:219], v210 offset:20480
	ds_read_b128 v[220:223], v210 offset:21504
	ds_read_b128 v[224:227], v210 offset:22528
	ds_read_b128 v[228:231], v210 offset:23552
	global_load_lds_dwordx4 v[156:157], off
	s_add_i32 m0, s40, 0x2000
	s_add_u32 s40, s6, 0x200000
	v_lshl_add_u64 v[232:233], s[6:7], 0, v[164:165]
	s_addc_u32 s41, s7, 0
	s_add_i32 s64, s55, s45
	global_load_lds_dwordx4 v[232:233], off
	v_lshl_add_u64 v[4:5], s[40:41], 0, v[160:161]
	s_mov_b32 m0, s64
	v_lshl_add_u64 v[234:235], s[8:9], 0, v[158:159]
	global_load_lds_dwordx4 v[4:5], off
	v_lshl_add_u64 v[4:5], s[40:41], 0, v[164:165]
	s_add_i32 m0, s64, 0x2000
	v_lshl_add_u64 v[236:237], s[8:9], 0, v[162:163]
	global_load_lds_dwordx4 v[4:5], off
	s_mov_b32 m0, s35
	s_nop 0
	global_load_lds_dwordx4 v[234:235], off
	s_mov_b32 m0, s37
	s_nop 0
	global_load_lds_dwordx4 v[236:237], off
	s_waitcnt vmcnt(8)
	s_waitcnt lgkmcnt(0)
	s_barrier
; #define PG8_STAGE(bufoff, gbase, voff) do { _Pragma("unroll") for (int _i = 0; _i < 2; ++_i) \
;         __builtin_amdgcn_global_load_lds((const unsigned*)((const char*)(gbase) + (voff)[_i]), (PG8_LAS unsigned*)(lds + (bufoff) + ldsw + _i * 8192), 16, 0, 0); } while (0)
; #define PG8_LDA(dst, b, h) do { _Pragma("unroll") for (int m = 0; m < 4; ++m) _Pragma("unroll") for (int k = 0; k < 2; ++k) dst[m][k] = *(const PG8_LAS bf16x8*)(lds + PG8_SA(b, h) + aoff + m * 2048 + k * 1024); } while (0)
; #define PG8_LDB(dst, b, h) do { _Pragma("unroll") for (int n = 0; n < 2; ++n) _Pragma("unroll") for (int k = 0; k < 2; ++k) dst[n][k] = *(const PG8_LAS bf16x8*)(lds + PG8_SB(b, h) + boff + n * 2048 + k * 1024); } while (0)
; #define PG8_MMA(ai, bj, At, Bt) do { __builtin_amdgcn_s_setprio(1); _Pragma("unroll") for (int m = 0; m < 4; ++m) _Pragma("unroll") for (int n = 0; n < 2; ++n) _Pragma("unroll") for (int k = 0; k < 2; ++k) \
;         acc[ai][bj][m][n] = __builtin_amdgcn_mfma_f32_16x16x32_bf16(Bt[n][k], At[m][k], acc[ai][bj][m][n], 0, 0, 0); __builtin_amdgcn_s_setprio(0); } while (0)
; #define PG8_WAIT_V(n) asm volatile("s_waitcnt vmcnt(" #n ")" ::: "memory")
; #define PG8_WAIT_L(n) asm volatile("s_waitcnt lgkmcnt(" #n ")" ::: "memory")
; #define PG8_BAR __builtin_amdgcn_s_barrier()
; #define PG8_SCHED __builtin_amdgcn_sched_barrier(0)
; template <class Epi, class Sched, bool ALIGN_EPI = false, bool SP2 = false>
; __device__ __forceinline__ void gemm_phase(PG8_LAS unsigned char* lds, const Gemm g, const Sched& S, const Epi& E) {
;     ...
;             PG8_WAIT_V(8); PG8_WAIT_L(0); PG8_BAR; PG8_MMA(1, 0, At, B0); PG8_MMA(1, 1, At, B1); PG8_BAR; PG8_SCHED;
;             PG8_LDB(B0, 1, 0); PG8_LDB(B1, 1, 1); PG8_SCHED; PG8_LDA(At, 1, 0); PG8_STAGE(PG8_SA(0, 1), a2 + hstepA, voffA);
;             PG8_WAIT_V(8); PG8_WAIT_L(0); PG8_BAR; PG8_MMA(0, 0, At, B0); PG8_MMA(0, 1, At, B1); PG8_BAR; PG8_SCHED;
	s_setprio 1
	v_mfma_f32_16x16x32_bf16 v[66:69], v[136:139], v[196:199], v[66:69]
	v_mfma_f32_16x16x32_bf16 v[62:65], v[144:147], v[196:199], v[62:65]
	v_mfma_f32_16x16x32_bf16 v[50:53], v[136:139], v[204:207], v[50:53]
	v_mfma_f32_16x16x32_bf16 v[46:49], v[144:147], v[204:207], v[46:49]
	v_mfma_f32_16x16x32_bf16 v[34:37], v[136:139], v[216:219], v[34:37]
	v_mfma_f32_16x16x32_bf16 v[30:33], v[144:147], v[216:219], v[30:33]
	v_mfma_f32_16x16x32_bf16 v[18:21], v[136:139], v[224:227], v[18:21]
	v_mfma_f32_16x16x32_bf16 v[14:17], v[144:147], v[224:227], v[14:17]
	v_mfma_f32_16x16x32_bf16 v[66:69], v[140:143], v[200:203], v[66:69]
	v_mfma_f32_16x16x32_bf16 v[62:65], v[148:151], v[200:203], v[62:65]
	v_mfma_f32_16x16x32_bf16 v[50:53], v[140:143], v[212:215], v[50:53]
	v_mfma_f32_16x16x32_bf16 v[46:49], v[148:151], v[212:215], v[46:49]
	v_mfma_f32_16x16x32_bf16 v[34:37], v[140:143], v[220:223], v[34:37]
	v_mfma_f32_16x16x32_bf16 v[30:33], v[148:151], v[220:223], v[30:33]
	v_mfma_f32_16x16x32_bf16 v[18:21], v[140:143], v[228:231], v[18:21]
	v_mfma_f32_16x16x32_bf16 v[14:17], v[148:151], v[228:231], v[14:17]
	s_setprio 0
	s_setprio 1
	v_mfma_f32_16x16x32_bf16 v[58:61], v[152:155], v[196:199], v[58:61]
	v_mfma_f32_16x16x32_bf16 v[54:57], v[178:181], v[196:199], v[54:57]
	v_mfma_f32_16x16x32_bf16 v[42:45], v[152:155], v[204:207], v[42:45]
	v_mfma_f32_16x16x32_bf16 v[38:41], v[178:181], v[204:207], v[38:41]
	v_mfma_f32_16x16x32_bf16 v[26:29], v[152:155], v[216:219], v[26:29]
	v_mfma_f32_16x16x32_bf16 v[22:25], v[178:181], v[216:219], v[22:25]
	v_mfma_f32_16x16x32_bf16 v[10:13], v[152:155], v[224:227], v[10:13]
	v_mfma_f32_16x16x32_bf16 v[4:7], v[178:181], v[224:227], v[6:9]
	v_mfma_f32_16x16x32_bf16 v[58:61], v[174:177], v[200:203], v[58:61]
	v_mfma_f32_16x16x32_bf16 v[54:57], v[182:185], v[200:203], v[54:57]
	v_mfma_f32_16x16x32_bf16 v[42:45], v[174:177], v[212:215], v[42:45]
	v_mfma_f32_16x16x32_bf16 v[38:41], v[182:185], v[212:215], v[38:41]
	v_mfma_f32_16x16x32_bf16 v[26:29], v[174:177], v[220:223], v[26:29]
	v_mfma_f32_16x16x32_bf16 v[22:25], v[182:185], v[220:223], v[22:25]
	v_mfma_f32_16x16x32_bf16 v[10:13], v[174:177], v[228:231], v[10:13]
	v_mfma_f32_16x16x32_bf16 v[4:7], v[182:185], v[228:231], v[4:7]
	s_setprio 0
	s_barrier
	s_add_i32 s40, 0, 0x18000
	v_add_u32_e32 v3, s40, v189
	s_add_i32 s41, 0, 0x1c000
	ds_read_b128 v[136:139], v3
	ds_read_b128 v[140:143], v3 offset:1024
	ds_read_b128 v[144:147], v3 offset:2048
	ds_read_b128 v[148:151], v3 offset:3072
	v_add_u32_e32 v3, s41, v189
	ds_read_b128 v[152:155], v3
	ds_read_b128 v[174:177], v3 offset:1024
	ds_read_b128 v[178:181], v3 offset:2048
	ds_read_b128 v[182:185], v3 offset:3072
	s_add_u32 s8, s8, 0x200000
	s_addc_u32 s9, s9, 0
	s_mov_b32 m0, s46
	v_lshl_add_u64 v[8:9], s[8:9], 0, v[158:159]
	ds_read_b128 v[196:199], v210 offset:32768
	ds_read_b128 v[200:203], v210 offset:33792
	ds_read_b128 v[204:207], v210 offset:34816
	ds_read_b128 v[212:215], v210 offset:35840
	ds_read_b128 v[216:219], v210 offset:36864
	ds_read_b128 v[220:223], v210 offset:37888
	ds_read_b128 v[224:227], v210 offset:38912
	ds_read_b128 v[228:231], v210 offset:39936
	global_load_lds_dwordx4 v[8:9], off
	v_lshl_add_u64 v[8:9], s[8:9], 0, v[162:163]
	s_mov_b32 m0, s47
	s_nop 0
	global_load_lds_dwordx4 v[8:9], off
	s_waitcnt vmcnt(8)
	s_waitcnt lgkmcnt(0)
	s_barrier
	s_setprio 1
	v_mfma_f32_16x16x32_bf16 v[130:133], v[136:139], v[196:199], v[130:133]
	v_mfma_f32_16x16x32_bf16 v[126:129], v[144:147], v[196:199], v[126:129]
	v_mfma_f32_16x16x32_bf16 v[114:117], v[136:139], v[204:207], v[114:117]
	v_mfma_f32_16x16x32_bf16 v[110:113], v[144:147], v[204:207], v[110:113]
	v_mfma_f32_16x16x32_bf16 v[98:101], v[136:139], v[216:219], v[98:101]
	v_mfma_f32_16x16x32_bf16 v[94:97], v[144:147], v[216:219], v[94:97]
	v_mfma_f32_16x16x32_bf16 v[82:85], v[136:139], v[224:227], v[82:85]
	v_mfma_f32_16x16x32_bf16 v[78:81], v[144:147], v[224:227], v[78:81]
	v_mfma_f32_16x16x32_bf16 v[130:133], v[140:143], v[200:203], v[130:133]
	v_mfma_f32_16x16x32_bf16 v[126:129], v[148:151], v[200:203], v[126:129]
	v_mfma_f32_16x16x32_bf16 v[114:117], v[140:143], v[212:215], v[114:117]
	v_mfma_f32_16x16x32_bf16 v[110:113], v[148:151], v[212:215], v[110:113]
	v_mfma_f32_16x16x32_bf16 v[98:101], v[140:143], v[220:223], v[98:101]
	v_mfma_f32_16x16x32_bf16 v[94:97], v[148:151], v[220:223], v[94:97]
	v_mfma_f32_16x16x32_bf16 v[82:85], v[140:143], v[228:231], v[82:85]
	v_mfma_f32_16x16x32_bf16 v[78:81], v[148:151], v[228:231], v[78:81]
	s_setprio 0
	s_setprio 1
	v_mfma_f32_16x16x32_bf16 v[122:125], v[152:155], v[196:199], v[122:125]
	v_mfma_f32_16x16x32_bf16 v[118:121], v[178:181], v[196:199], v[118:121]
	v_mfma_f32_16x16x32_bf16 v[106:109], v[152:155], v[204:207], v[106:109]
	v_mfma_f32_16x16x32_bf16 v[102:105], v[178:181], v[204:207], v[102:105]
	v_mfma_f32_16x16x32_bf16 v[90:93], v[152:155], v[216:219], v[90:93]
	v_mfma_f32_16x16x32_bf16 v[86:89], v[178:181], v[216:219], v[86:89]
	v_mfma_f32_16x16x32_bf16 v[74:77], v[152:155], v[224:227], v[74:77]
	v_mfma_f32_16x16x32_bf16 v[70:73], v[178:181], v[224:227], v[70:73]
	v_mfma_f32_16x16x32_bf16 v[122:125], v[174:177], v[200:203], v[122:125]
	v_mfma_f32_16x16x32_bf16 v[118:121], v[182:185], v[200:203], v[118:121]
	v_mfma_f32_16x16x32_bf16 v[106:109], v[174:177], v[212:215], v[106:109]
	v_mfma_f32_16x16x32_bf16 v[102:105], v[182:185], v[212:215], v[102:105]
	v_mfma_f32_16x16x32_bf16 v[90:93], v[174:177], v[220:223], v[90:93]
	v_mfma_f32_16x16x32_bf16 v[86:89], v[182:185], v[220:223], v[86:89]
	v_mfma_f32_16x16x32_bf16 v[74:77], v[174:177], v[228:231], v[74:77]
	v_mfma_f32_16x16x32_bf16 v[70:73], v[182:185], v[228:231], v[70:73]
	s_setprio 0
	s_barrier
; #define PG8_STAGE(bufoff, gbase, voff) do { _Pragma("unroll") for (int _i = 0; _i < 2; ++_i) \
;         __builtin_amdgcn_global_load_lds((const unsigned*)((const char*)(gbase) + (voff)[_i]), (PG8_LAS unsigned*)(lds + (bufoff) + ldsw + _i * 8192), 16, 0, 0); } while (0)
; #define PG8_LDA(dst, b, h) do { _Pragma("unroll") for (int m = 0; m < 4; ++m) _Pragma("unroll") for (int k = 0; k < 2; ++k) dst[m][k] = *(const PG8_LAS bf16x8*)(lds + PG8_SA(b, h) + aoff + m * 2048 + k * 1024); } while (0)
; #define PG8_MMA(ai, bj, At, Bt) do { __builtin_amdgcn_s_setprio(1); _Pragma("unroll") for (int m = 0; m < 4; ++m) _Pragma("unroll") for (int n = 0; n < 2; ++n) _Pragma("unroll") for (int k = 0; k < 2; ++k) \
;         acc[ai][bj][m][n] = __builtin_amdgcn_mfma_f32_16x16x32_bf16(Bt[n][k], At[m][k], acc[ai][bj][m][n], 0, 0, 0); __builtin_amdgcn_s_setprio(0); } while (0)
; #define PG8_WAIT_V(n) asm volatile("s_waitcnt vmcnt(" #n ")" ::: "memory")
; #define PG8_WAIT_L(n) asm volatile("s_waitcnt lgkmcnt(" #n ")" ::: "memory")
; #define PG8_BAR __builtin_amdgcn_s_barrier()
; #define PG8_SCHED __builtin_amdgcn_sched_barrier(0)
; template <class Epi, class Sched, bool ALIGN_EPI = false, bool SP2 = false>
; __device__ __forceinline__ void gemm_phase(PG8_LAS unsigned char* lds, const Gemm g, const Sched& S, const Epi& E) {
;     ...
;         for (int t = 0; t < nt; t += 2) {
;     ...
;             PG8_LDA(At, 1, 1); PG8_STAGE(PG8_SB(1, 0), b3, voffB); PG8_STAGE(PG8_SB(1, 1), b3 + hstepB, voffB); PG8_STAGE(PG8_SA(1, 0), a3, voffA);
;             PG8_WAIT_V(8); PG8_WAIT_L(0); PG8_BAR; PG8_MMA(1, 0, At, B0); PG8_MMA(1, 1, At, B1); PG8_BAR; PG8_SCHED;
	s_add_i32 s8, s40, s45
	v_lshl_add_u64 v[8:9], v[156:157], 0, s[20:21]
	s_mov_b32 m0, s8
	ds_read_b128 v[196:199], v210 offset:49152
	ds_read_b128 v[200:203], v210 offset:50176
	ds_read_b128 v[204:207], v210 offset:51200
	ds_read_b128 v[212:215], v210 offset:52224
	ds_read_b128 v[216:219], v210 offset:53248
	ds_read_b128 v[220:223], v210 offset:54272
	ds_read_b128 v[224:227], v210 offset:55296
	ds_read_b128 v[228:231], v210 offset:56320
	global_load_lds_dwordx4 v[8:9], off
	s_add_i32 m0, s8, 0x2000
	s_add_u32 s6, s6, 0x200080
	v_lshl_add_u64 v[8:9], v[232:233], 0, s[20:21]
	s_addc_u32 s7, s7, 0
	s_add_i32 s8, s41, s45
	global_load_lds_dwordx4 v[8:9], off
	v_lshl_add_u64 v[8:9], s[6:7], 0, v[160:161]
	s_mov_b32 m0, s8
	s_nop 0
	global_load_lds_dwordx4 v[8:9], off
	v_lshl_add_u64 v[8:9], s[6:7], 0, v[164:165]
	s_add_i32 m0, s8, 0x2000
	s_nop 0
	global_load_lds_dwordx4 v[8:9], off
	v_lshl_add_u64 v[8:9], v[234:235], 0, s[20:21]
	s_mov_b32 m0, s49
	s_nop 0
	global_load_lds_dwordx4 v[8:9], off
	v_lshl_add_u64 v[8:9], v[236:237], 0, s[20:21]
	s_mov_b32 m0, s50
	s_nop 0
	global_load_lds_dwordx4 v[8:9], off
	s_waitcnt vmcnt(8)
	s_waitcnt lgkmcnt(0)
	s_barrier
	s_setprio 1
	v_mfma_f32_16x16x32_bf16 v[66:69], v[136:139], v[196:199], v[66:69]
	v_mfma_f32_16x16x32_bf16 v[62:65], v[144:147], v[196:199], v[62:65]
	v_mfma_f32_16x16x32_bf16 v[50:53], v[136:139], v[204:207], v[50:53]
	v_mfma_f32_16x16x32_bf16 v[46:49], v[144:147], v[204:207], v[46:49]
	v_mfma_f32_16x16x32_bf16 v[34:37], v[136:139], v[216:219], v[34:37]
	v_mfma_f32_16x16x32_bf16 v[30:33], v[144:147], v[216:219], v[30:33]
	v_mfma_f32_16x16x32_bf16 v[18:21], v[136:139], v[224:227], v[18:21]
	v_mfma_f32_16x16x32_bf16 v[14:17], v[144:147], v[224:227], v[14:17]
	v_mfma_f32_16x16x32_bf16 v[66:69], v[140:143], v[200:203], v[66:69]
	v_mfma_f32_16x16x32_bf16 v[62:65], v[148:151], v[200:203], v[62:65]
	v_mfma_f32_16x16x32_bf16 v[50:53], v[140:143], v[212:215], v[50:53]
	v_mfma_f32_16x16x32_bf16 v[46:49], v[148:151], v[212:215], v[46:49]
	v_mfma_f32_16x16x32_bf16 v[34:37], v[140:143], v[220:223], v[34:37]
	v_mfma_f32_16x16x32_bf16 v[30:33], v[148:151], v[220:223], v[30:33]
	v_mfma_f32_16x16x32_bf16 v[18:21], v[140:143], v[228:231], v[18:21]
	v_mfma_f32_16x16x32_bf16 v[14:17], v[148:151], v[228:231], v[14:17]
	s_setprio 0
	s_setprio 1
	v_mfma_f32_16x16x32_bf16 v[58:61], v[152:155], v[196:199], v[58:61]
	v_mfma_f32_16x16x32_bf16 v[54:57], v[178:181], v[196:199], v[54:57]
	v_mfma_f32_16x16x32_bf16 v[42:45], v[152:155], v[204:207], v[42:45]
	v_mfma_f32_16x16x32_bf16 v[38:41], v[178:181], v[204:207], v[38:41]
	v_mfma_f32_16x16x32_bf16 v[26:29], v[152:155], v[216:219], v[26:29]
	v_mfma_f32_16x16x32_bf16 v[22:25], v[178:181], v[216:219], v[22:25]
	v_mfma_f32_16x16x32_bf16 v[8:11], v[152:155], v[224:227], v[10:13]
	v_mfma_f32_16x16x32_bf16 v[4:7], v[178:181], v[224:227], v[4:7]
	v_mfma_f32_16x16x32_bf16 v[58:61], v[174:177], v[200:203], v[58:61]
	v_mfma_f32_16x16x32_bf16 v[54:57], v[182:185], v[200:203], v[54:57]
	v_mfma_f32_16x16x32_bf16 v[42:45], v[174:177], v[212:215], v[42:45]
	v_mfma_f32_16x16x32_bf16 v[38:41], v[182:185], v[212:215], v[38:41]
	v_mfma_f32_16x16x32_bf16 v[26:29], v[174:177], v[220:223], v[26:29]
	v_mfma_f32_16x16x32_bf16 v[22:25], v[182:185], v[220:223], v[22:25]
	v_mfma_f32_16x16x32_bf16 v[10:13], v[174:177], v[228:231], v[8:11]
	v_mfma_f32_16x16x32_bf16 v[6:9], v[182:185], v[228:231], v[4:7]
	s_setprio 0
	s_barrier
	s_add_i32 s6, s63, 2
	s_addk_i32 s62, 0x80
	s_add_u32 s38, s38, 0x100
	s_addc_u32 s39, s39, 0
	s_add_u32 s60, s60, 0x100
	s_addc_u32 s61, s61, 0
	s_cmpk_gt_u32 s63, 0x7d
	s_cbranch_scc1 .LBB0_649
	s_mov_b32 s63, s6
	s_cmp_lt_i32 s63, 2
	s_cbranch_scc1 .LBB0_637

; #define PG8_STAGE(bufoff, gbase, voff) do { _Pragma("unroll") for (int _i = 0; _i < 2; ++_i) \
;         __builtin_amdgcn_global_load_lds((const unsigned*)((const char*)(gbase) + (voff)[_i]), (PG8_LAS unsigned*)(lds + (bufoff) + ldsw + _i * 8192), 16, 0, 0); } while (0)
; #define PG8_LDA(dst, b, h) do { _Pragma("unroll") for (int m = 0; m < 4; ++m) _Pragma("unroll") for (int k = 0; k < 2; ++k) dst[m][k] = *(const PG8_LAS bf16x8*)(lds + PG8_SA(b, h) + aoff + m * 2048 + k * 1024); } while (0)
; #define PG8_LDB(dst, b, h) do { _Pragma("unroll") for (int n = 0; n < 2; ++n) _Pragma("unroll") for (int k = 0; k < 2; ++k) dst[n][k] = *(const PG8_LAS bf16x8*)(lds + PG8_SB(b, h) + boff + n * 2048 + k * 1024); } while (0)
; #define PG8_MMA(ai, bj, At, Bt) do { __builtin_amdgcn_s_setprio(1); _Pragma("unroll") for (int m = 0; m < 4; ++m) _Pragma("unroll") for (int n = 0; n < 2; ++n) _Pragma("unroll") for (int k = 0; k < 2; ++k) \
;         acc[ai][bj][m][n] = __builtin_amdgcn_mfma_f32_16x16x32_bf16(Bt[n][k], At[m][k], acc[ai][bj][m][n], 0, 0, 0); __builtin_amdgcn_s_setprio(0); } while (0)
; #define PG8_WAIT_V(n) asm volatile("s_waitcnt vmcnt(" #n ")" ::: "memory")
; #define PG8_WAIT_L(n) asm volatile("s_waitcnt lgkmcnt(" #n ")" ::: "memory")
; #define PG8_BAR __builtin_amdgcn_s_barrier()
; template <class Epi, class Sched, bool ALIGN_EPI = false, bool SP2 = false>
; __device__ __forceinline__ void gemm_phase(PG8_LAS unsigned char* lds, const Gemm g, const Sched& S, const Epi& E) {
;     ...
;             const char* a1 = cA + (size_t)(t + 1) * kstep;
;             const char* a2 = last ? nA : cA + (size_t)(t + 2) * kstep; const char* b2 = last ? nB : cB + (size_t)(t + 2) * kstep;
;             const char* a3 = a2 + kstep; const char* b3 = b2 + kstep;
;             if (last && has_next) S.a_ready(nxt);
;             if constexpr (SP2) {
;             PG8_LDB(B0, 0, 0); PG8_LDB(B1, 0, 1); PG8_SCHED; PG8_LDA(At, 0, 0); PG8_STAGE(PG8_SA(1, 1), a1 + hstepA, voffA);
;             PG8_WAIT_V(8); PG8_WAIT_L(0); PG8_BAR; PG8_MMA(0, 0, At, B0); PG8_MMA(0, 1, At, B1); PG8_BAR; PG8_SCHED;
;             PG8_LDA(At, 0, 1); PG8_STAGE(PG8_SB(0, 0), b2, voffB); PG8_STAGE(PG8_SB(0, 1), b2 + hstepB, voffB); PG8_STAGE(PG8_SA(0, 0), a2, voffA);
;             PG8_WAIT_V(8); PG8_WAIT_L(0); PG8_BAR; PG8_MMA(1, 0, At, B0); PG8_MMA(1, 1, At, B1); PG8_BAR; PG8_SCHED;
.LBB0_741:
	ds_read_b128 v[148:151], v158
	ds_read_b128 v[162:165], v158 offset:1024
	ds_read_b128 v[166:169], v158 offset:2048
	ds_read_b128 v[170:173], v158 offset:3072
	ds_read_b128 v[174:177], v159
	ds_read_b128 v[178:181], v159 offset:1024
	ds_read_b128 v[182:185], v159 offset:2048
	ds_read_b128 v[196:199], v159 offset:3072
	s_add_u32 s40, s38, 0xfff00080
	s_addc_u32 s41, s39, -1
	s_cmp_eq_u32 s67, 60
	s_cselect_b32 s43, s27, s41
	s_cselect_b32 s42, s63, s40
	s_cselect_b32 s41, s25, s66
	s_cselect_b32 s40, s64, s65
	v_lshl_add_u64 v[152:153], s[38:39], 0, v[140:141]
	s_add_i32 m0, s48, 0xc000
	ds_read_b128 v[200:203], v160
	ds_read_b128 v[204:207], v160 offset:1024
	ds_read_b128 v[208:211], v160 offset:2048
	ds_read_b128 v[212:215], v160 offset:3072
	ds_read_b128 v[216:219], v160 offset:4096
	ds_read_b128 v[220:223], v160 offset:5120
	ds_read_b128 v[224:227], v160 offset:6144
	ds_read_b128 v[228:231], v160 offset:7168
	global_load_lds_dwordx4 v[152:153], off
	v_lshl_add_u64 v[152:153], s[38:39], 0, v[142:143]
	s_add_i32 m0, s48, 0xe000
	s_nop 0
	global_load_lds_dwordx4 v[152:153], off
	s_waitcnt vmcnt(8)
	s_waitcnt lgkmcnt(0)
	s_barrier
	s_setprio 1
	v_mfma_f32_16x16x32_bf16 v[126:129], v[148:151], v[200:203], v[126:129]
	v_mfma_f32_16x16x32_bf16 v[122:125], v[166:169], v[200:203], v[122:125]
	v_mfma_f32_16x16x32_bf16 v[110:113], v[148:151], v[208:211], v[110:113]
	v_mfma_f32_16x16x32_bf16 v[106:109], v[166:169], v[208:211], v[106:109]
	v_mfma_f32_16x16x32_bf16 v[94:97], v[148:151], v[216:219], v[94:97]
	v_mfma_f32_16x16x32_bf16 v[90:93], v[166:169], v[216:219], v[90:93]
	v_mfma_f32_16x16x32_bf16 v[78:81], v[148:151], v[224:227], v[78:81]
	v_mfma_f32_16x16x32_bf16 v[74:77], v[166:169], v[224:227], v[74:77]
	v_mfma_f32_16x16x32_bf16 v[126:129], v[162:165], v[204:207], v[126:129]
	v_mfma_f32_16x16x32_bf16 v[122:125], v[170:173], v[204:207], v[122:125]
	v_mfma_f32_16x16x32_bf16 v[110:113], v[162:165], v[212:215], v[110:113]
	v_mfma_f32_16x16x32_bf16 v[106:109], v[170:173], v[212:215], v[106:109]
	v_mfma_f32_16x16x32_bf16 v[94:97], v[162:165], v[220:223], v[94:97]
	v_mfma_f32_16x16x32_bf16 v[90:93], v[170:173], v[220:223], v[90:93]
	v_mfma_f32_16x16x32_bf16 v[78:81], v[162:165], v[228:231], v[78:81]
	v_mfma_f32_16x16x32_bf16 v[74:77], v[170:173], v[228:231], v[74:77]
	s_setprio 0
	s_setprio 1
	v_mfma_f32_16x16x32_bf16 v[118:121], v[174:177], v[200:203], v[118:121]
	v_mfma_f32_16x16x32_bf16 v[114:117], v[182:185], v[200:203], v[114:117]
	v_mfma_f32_16x16x32_bf16 v[102:105], v[174:177], v[208:211], v[102:105]
	v_mfma_f32_16x16x32_bf16 v[98:101], v[182:185], v[208:211], v[98:101]
	v_mfma_f32_16x16x32_bf16 v[86:89], v[174:177], v[216:219], v[86:89]
	v_mfma_f32_16x16x32_bf16 v[82:85], v[182:185], v[216:219], v[82:85]
	v_mfma_f32_16x16x32_bf16 v[70:73], v[174:177], v[224:227], v[70:73]
	v_mfma_f32_16x16x32_bf16 v[66:69], v[182:185], v[224:227], v[66:69]
	v_mfma_f32_16x16x32_bf16 v[118:121], v[178:181], v[204:207], v[118:121]
	v_mfma_f32_16x16x32_bf16 v[114:117], v[196:199], v[204:207], v[114:117]
	v_mfma_f32_16x16x32_bf16 v[102:105], v[178:181], v[212:215], v[102:105]
	v_mfma_f32_16x16x32_bf16 v[98:101], v[196:199], v[212:215], v[98:101]
	v_mfma_f32_16x16x32_bf16 v[86:89], v[178:181], v[220:223], v[86:89]
	v_mfma_f32_16x16x32_bf16 v[82:85], v[196:199], v[220:223], v[82:85]
	v_mfma_f32_16x16x32_bf16 v[70:73], v[178:181], v[228:231], v[70:73]
	v_mfma_f32_16x16x32_bf16 v[66:69], v[196:199], v[228:231], v[66:69]
	s_setprio 0
	s_barrier
	s_add_i32 s68, s55, s37
	v_lshl_add_u64 v[152:153], s[40:41], 0, v[132:133]
	s_mov_b32 m0, s68
	ds_read_b128 v[200:203], v160 offset:16384
	ds_read_b128 v[204:207], v160 offset:17408
	ds_read_b128 v[208:211], v160 offset:18432
	ds_read_b128 v[212:215], v160 offset:19456
	ds_read_b128 v[216:219], v160 offset:20480
	ds_read_b128 v[220:223], v160 offset:21504
	ds_read_b128 v[224:227], v160 offset:22528
	ds_read_b128 v[228:231], v160 offset:23552
	global_load_lds_dwordx4 v[152:153], off
	s_add_i32 m0, s68, 0x2000
	s_add_u32 s68, s40, 0x100000
	v_lshl_add_u64 v[232:233], s[40:41], 0, v[136:137]
	s_addc_u32 s69, s41, 0
	s_add_i32 s70, s56, s37
	global_load_lds_dwordx4 v[232:233], off
	v_lshl_add_u64 v[234:235], s[68:69], 0, v[132:133]
	s_mov_b32 m0, s70
	v_lshl_add_u64 v[236:237], s[42:43], 0, v[134:135]
	global_load_lds_dwordx4 v[234:235], off
	v_lshl_add_u64 v[234:235], s[68:69], 0, v[136:137]
	s_add_i32 m0, s70, 0x2000
	s_nop 0
	global_load_lds_dwordx4 v[234:235], off
	v_lshl_add_u64 v[234:235], s[42:43], 0, v[130:131]
	s_mov_b32 m0, s48
	s_nop 0
	global_load_lds_dwordx4 v[234:235], off
	s_mov_b32 m0, s49
	s_nop 0
	global_load_lds_dwordx4 v[236:237], off
	s_waitcnt vmcnt(8)
	s_waitcnt lgkmcnt(0)
	s_barrier
; #define PG8_STAGE(bufoff, gbase, voff) do { _Pragma("unroll") for (int _i = 0; _i < 2; ++_i) \
;         __builtin_amdgcn_global_load_lds((const unsigned*)((const char*)(gbase) + (voff)[_i]), (PG8_LAS unsigned*)(lds + (bufoff) + ldsw + _i * 8192), 16, 0, 0); } while (0)
; #define PG8_LDA(dst, b, h) do { _Pragma("unroll") for (int m = 0; m < 4; ++m) _Pragma("unroll") for (int k = 0; k < 2; ++k) dst[m][k] = *(const PG8_LAS bf16x8*)(lds + PG8_SA(b, h) + aoff + m * 2048 + k * 1024); } while (0)
; #define PG8_LDB(dst, b, h) do { _Pragma("unroll") for (int n = 0; n < 2; ++n) _Pragma("unroll") for (int k = 0; k < 2; ++k) dst[n][k] = *(const PG8_LAS bf16x8*)(lds + PG8_SB(b, h) + boff + n * 2048 + k * 1024); } while (0)
; #define PG8_MMA(ai, bj, At, Bt) do { __builtin_amdgcn_s_setprio(1); _Pragma("unroll") for (int m = 0; m < 4; ++m) _Pragma("unroll") for (int n = 0; n < 2; ++n) _Pragma("unroll") for (int k = 0; k < 2; ++k) \
;         acc[ai][bj][m][n] = __builtin_amdgcn_mfma_f32_16x16x32_bf16(Bt[n][k], At[m][k], acc[ai][bj][m][n], 0, 0, 0); __builtin_amdgcn_s_setprio(0); } while (0)
; #define PG8_WAIT_V(n) asm volatile("s_waitcnt vmcnt(" #n ")" ::: "memory")
; #define PG8_WAIT_L(n) asm volatile("s_waitcnt lgkmcnt(" #n ")" ::: "memory")
; #define PG8_BAR __builtin_amdgcn_s_barrier()
; #define PG8_SCHED __builtin_amdgcn_sched_barrier(0)
; template <class Epi, class Sched, bool ALIGN_EPI = false, bool SP2 = false>
; __device__ __forceinline__ void gemm_phase(PG8_LAS unsigned char* lds, const Gemm g, const Sched& S, const Epi& E) {
;     ...
;             PG8_WAIT_V(8); PG8_WAIT_L(0); PG8_BAR; PG8_MMA(1, 0, At, B0); PG8_MMA(1, 1, At, B1); PG8_BAR; PG8_SCHED;
;             PG8_LDB(B0, 1, 0); PG8_LDB(B1, 1, 1); PG8_SCHED; PG8_LDA(At, 1, 0); PG8_STAGE(PG8_SA(0, 1), a2 + hstepA, voffA);
;             PG8_WAIT_V(8); PG8_WAIT_L(0); PG8_BAR; PG8_MMA(0, 0, At, B0); PG8_MMA(0, 1, At, B1); PG8_BAR; PG8_SCHED;
	s_setprio 1
	v_mfma_f32_16x16x32_bf16 v[62:65], v[148:151], v[200:203], v[62:65]
	v_mfma_f32_16x16x32_bf16 v[58:61], v[166:169], v[200:203], v[58:61]
	v_mfma_f32_16x16x32_bf16 v[50:53], v[148:151], v[208:211], v[50:53]
	v_mfma_f32_16x16x32_bf16 v[42:45], v[166:169], v[208:211], v[42:45]
	v_mfma_f32_16x16x32_bf16 v[34:37], v[148:151], v[216:219], v[34:37]
	v_mfma_f32_16x16x32_bf16 v[26:29], v[166:169], v[216:219], v[26:29]
	v_mfma_f32_16x16x32_bf16 v[18:21], v[148:151], v[224:227], v[18:21]
	v_mfma_f32_16x16x32_bf16 v[10:13], v[166:169], v[224:227], v[10:13]
	v_mfma_f32_16x16x32_bf16 v[62:65], v[162:165], v[204:207], v[62:65]
	v_mfma_f32_16x16x32_bf16 v[58:61], v[170:173], v[204:207], v[58:61]
	v_mfma_f32_16x16x32_bf16 v[50:53], v[162:165], v[212:215], v[50:53]
	v_mfma_f32_16x16x32_bf16 v[42:45], v[170:173], v[212:215], v[42:45]
	v_mfma_f32_16x16x32_bf16 v[34:37], v[162:165], v[220:223], v[34:37]
	v_mfma_f32_16x16x32_bf16 v[26:29], v[170:173], v[220:223], v[26:29]
	v_mfma_f32_16x16x32_bf16 v[18:21], v[162:165], v[228:231], v[18:21]
	v_mfma_f32_16x16x32_bf16 v[10:13], v[170:173], v[228:231], v[10:13]
	s_setprio 0
	s_setprio 1
	v_mfma_f32_16x16x32_bf16 v[54:57], v[174:177], v[200:203], v[54:57]
	v_mfma_f32_16x16x32_bf16 v[46:49], v[182:185], v[200:203], v[46:49]
	v_mfma_f32_16x16x32_bf16 v[38:41], v[174:177], v[208:211], v[38:41]
	v_mfma_f32_16x16x32_bf16 v[30:33], v[182:185], v[208:211], v[30:33]
	v_mfma_f32_16x16x32_bf16 v[22:25], v[174:177], v[216:219], v[22:25]
	v_mfma_f32_16x16x32_bf16 v[14:17], v[182:185], v[216:219], v[14:17]
	v_mfma_f32_16x16x32_bf16 v[6:9], v[174:177], v[224:227], v[6:9]
	v_mfma_f32_16x16x32_bf16 v[2:5], v[182:185], v[224:227], v[2:5]
	v_mfma_f32_16x16x32_bf16 v[54:57], v[178:181], v[204:207], v[54:57]
	v_mfma_f32_16x16x32_bf16 v[46:49], v[196:199], v[204:207], v[46:49]
	v_mfma_f32_16x16x32_bf16 v[38:41], v[178:181], v[212:215], v[38:41]
	v_mfma_f32_16x16x32_bf16 v[30:33], v[196:199], v[212:215], v[30:33]
	v_mfma_f32_16x16x32_bf16 v[22:25], v[178:181], v[220:223], v[22:25]
	v_mfma_f32_16x16x32_bf16 v[14:17], v[196:199], v[220:223], v[14:17]
	v_mfma_f32_16x16x32_bf16 v[6:9], v[178:181], v[228:231], v[6:9]
	v_mfma_f32_16x16x32_bf16 v[2:5], v[196:199], v[228:231], v[2:5]
	s_setprio 0
	s_barrier
	s_add_i32 s68, 0, 0x18000
	v_add_u32_e32 v138, s68, v154
	s_add_i32 s69, 0, 0x1c000
	ds_read_b128 v[148:151], v138
	ds_read_b128 v[162:165], v138 offset:1024
	ds_read_b128 v[166:169], v138 offset:2048
	ds_read_b128 v[170:173], v138 offset:3072
	v_add_u32_e32 v138, s69, v154
	ds_read_b128 v[174:177], v138
	ds_read_b128 v[178:181], v138 offset:1024
	ds_read_b128 v[182:185], v138 offset:2048
	ds_read_b128 v[196:199], v138 offset:3072
	s_add_u32 s42, s42, 0x100000
	s_addc_u32 s43, s43, 0
	s_mov_b32 m0, s50
	v_lshl_add_u64 v[238:239], s[42:43], 0, v[130:131]
	ds_read_b128 v[200:203], v160 offset:32768
	ds_read_b128 v[204:207], v160 offset:33792
	ds_read_b128 v[208:211], v160 offset:34816
	ds_read_b128 v[212:215], v160 offset:35840
	ds_read_b128 v[216:219], v160 offset:36864
	ds_read_b128 v[220:223], v160 offset:37888
	ds_read_b128 v[224:227], v160 offset:38912
	ds_read_b128 v[228:231], v160 offset:39936
	global_load_lds_dwordx4 v[238:239], off
	v_lshl_add_u64 v[238:239], s[42:43], 0, v[134:135]
	s_mov_b32 m0, s51
	s_nop 0
	global_load_lds_dwordx4 v[238:239], off
	s_waitcnt vmcnt(8)
	s_waitcnt lgkmcnt(0)
	s_barrier
	s_setprio 1
	v_mfma_f32_16x16x32_bf16 v[126:129], v[148:151], v[200:203], v[126:129]
	v_mfma_f32_16x16x32_bf16 v[122:125], v[166:169], v[200:203], v[122:125]
	v_mfma_f32_16x16x32_bf16 v[110:113], v[148:151], v[208:211], v[110:113]
	v_mfma_f32_16x16x32_bf16 v[106:109], v[166:169], v[208:211], v[106:109]
	v_mfma_f32_16x16x32_bf16 v[94:97], v[148:151], v[216:219], v[94:97]
	v_mfma_f32_16x16x32_bf16 v[90:93], v[166:169], v[216:219], v[90:93]
	v_mfma_f32_16x16x32_bf16 v[78:81], v[148:151], v[224:227], v[78:81]
	v_mfma_f32_16x16x32_bf16 v[74:77], v[166:169], v[224:227], v[74:77]
	v_mfma_f32_16x16x32_bf16 v[126:129], v[162:165], v[204:207], v[126:129]
	v_mfma_f32_16x16x32_bf16 v[122:125], v[170:173], v[204:207], v[122:125]
	v_mfma_f32_16x16x32_bf16 v[110:113], v[162:165], v[212:215], v[110:113]
	v_mfma_f32_16x16x32_bf16 v[106:109], v[170:173], v[212:215], v[106:109]
	v_mfma_f32_16x16x32_bf16 v[94:97], v[162:165], v[220:223], v[94:97]
	v_mfma_f32_16x16x32_bf16 v[90:93], v[170:173], v[220:223], v[90:93]
	v_mfma_f32_16x16x32_bf16 v[78:81], v[162:165], v[228:231], v[78:81]
	v_mfma_f32_16x16x32_bf16 v[74:77], v[170:173], v[228:231], v[74:77]
	s_setprio 0
	s_setprio 1
	v_mfma_f32_16x16x32_bf16 v[118:121], v[174:177], v[200:203], v[118:121]
	v_mfma_f32_16x16x32_bf16 v[114:117], v[182:185], v[200:203], v[114:117]
	v_mfma_f32_16x16x32_bf16 v[102:105], v[174:177], v[208:211], v[102:105]
	v_mfma_f32_16x16x32_bf16 v[98:101], v[182:185], v[208:211], v[98:101]
	v_mfma_f32_16x16x32_bf16 v[86:89], v[174:177], v[216:219], v[86:89]
	v_mfma_f32_16x16x32_bf16 v[82:85], v[182:185], v[216:219], v[82:85]
	v_mfma_f32_16x16x32_bf16 v[70:73], v[174:177], v[224:227], v[70:73]
	v_mfma_f32_16x16x32_bf16 v[66:69], v[182:185], v[224:227], v[66:69]
	v_mfma_f32_16x16x32_bf16 v[118:121], v[178:181], v[204:207], v[118:121]
	v_mfma_f32_16x16x32_bf16 v[114:117], v[196:199], v[204:207], v[114:117]
	v_mfma_f32_16x16x32_bf16 v[102:105], v[178:181], v[212:215], v[102:105]
	v_mfma_f32_16x16x32_bf16 v[98:101], v[196:199], v[212:215], v[98:101]
	v_mfma_f32_16x16x32_bf16 v[86:89], v[178:181], v[220:223], v[86:89]
	v_mfma_f32_16x16x32_bf16 v[82:85], v[196:199], v[220:223], v[82:85]
	v_mfma_f32_16x16x32_bf16 v[70:73], v[178:181], v[228:231], v[70:73]
	v_mfma_f32_16x16x32_bf16 v[66:69], v[196:199], v[228:231], v[66:69]
	s_setprio 0
	s_barrier
; #define PG8_STAGE(bufoff, gbase, voff) do { _Pragma("unroll") for (int _i = 0; _i < 2; ++_i) \
;         __builtin_amdgcn_global_load_lds((const unsigned*)((const char*)(gbase) + (voff)[_i]), (PG8_LAS unsigned*)(lds + (bufoff) + ldsw + _i * 8192), 16, 0, 0); } while (0)
; #define PG8_LDA(dst, b, h) do { _Pragma("unroll") for (int m = 0; m < 4; ++m) _Pragma("unroll") for (int k = 0; k < 2; ++k) dst[m][k] = *(const PG8_LAS bf16x8*)(lds + PG8_SA(b, h) + aoff + m * 2048 + k * 1024); } while (0)
; #define PG8_MMA(ai, bj, At, Bt) do { __builtin_amdgcn_s_setprio(1); _Pragma("unroll") for (int m = 0; m < 4; ++m) _Pragma("unroll") for (int n = 0; n < 2; ++n) _Pragma("unroll") for (int k = 0; k < 2; ++k) \
;         acc[ai][bj][m][n] = __builtin_amdgcn_mfma_f32_16x16x32_bf16(Bt[n][k], At[m][k], acc[ai][bj][m][n], 0, 0, 0); __builtin_amdgcn_s_setprio(0); } while (0)
; #define PG8_WAIT_V(n) asm volatile("s_waitcnt vmcnt(" #n ")" ::: "memory")
; #define PG8_WAIT_L(n) asm volatile("s_waitcnt lgkmcnt(" #n ")" ::: "memory")
; #define PG8_BAR __builtin_amdgcn_s_barrier()
; #define PG8_SCHED __builtin_amdgcn_sched_barrier(0)
; template <class Epi, class Sched, bool ALIGN_EPI = false, bool SP2 = false>
; __device__ __forceinline__ void gemm_phase(PG8_LAS unsigned char* lds, const Gemm g, const Sched& S, const Epi& E) {
;     ...
;             PG8_LDA(At, 1, 1); PG8_STAGE(PG8_SB(1, 0), b3, voffB); PG8_STAGE(PG8_SB(1, 1), b3 + hstepB, voffB); PG8_STAGE(PG8_SA(1, 0), a3, voffA);
;             PG8_WAIT_V(8); PG8_WAIT_L(0); PG8_BAR; PG8_MMA(1, 0, At, B0); PG8_MMA(1, 1, At, B1); PG8_BAR; PG8_SCHED;
;     ...
;         if constexpr (ALIGN_EPI) { if (wr == 0) PG8_BAR; }
	s_add_i32 s42, s68, s37
	v_lshl_add_u64 v[152:153], v[152:153], 0, s[12:13]
	s_mov_b32 m0, s42
	ds_read_b128 v[200:203], v160 offset:49152
	ds_read_b128 v[204:207], v160 offset:50176
	ds_read_b128 v[208:211], v160 offset:51200
	ds_read_b128 v[212:215], v160 offset:52224
	ds_read_b128 v[216:219], v160 offset:53248
	ds_read_b128 v[220:223], v160 offset:54272
	ds_read_b128 v[224:227], v160 offset:55296
	ds_read_b128 v[228:231], v160 offset:56320
	global_load_lds_dwordx4 v[152:153], off
	s_add_i32 m0, s42, 0x2000
	s_add_u32 s40, s40, 0x100080
	v_lshl_add_u64 v[152:153], v[232:233], 0, s[12:13]
	s_addc_u32 s41, s41, 0
	s_add_i32 s42, s69, s37
	global_load_lds_dwordx4 v[152:153], off
	v_lshl_add_u64 v[152:153], s[40:41], 0, v[132:133]
	s_mov_b32 m0, s42
	s_nop 0
	global_load_lds_dwordx4 v[152:153], off
	v_lshl_add_u64 v[152:153], s[40:41], 0, v[136:137]
	s_add_i32 m0, s42, 0x2000
	s_nop 0
	global_load_lds_dwordx4 v[152:153], off
	v_lshl_add_u64 v[152:153], v[234:235], 0, s[12:13]
	s_mov_b32 m0, s52
	s_nop 0
	global_load_lds_dwordx4 v[152:153], off
	v_lshl_add_u64 v[152:153], v[236:237], 0, s[12:13]
	s_mov_b32 m0, s53
	s_nop 0
	global_load_lds_dwordx4 v[152:153], off
	s_waitcnt vmcnt(8)
	s_waitcnt lgkmcnt(0)
	s_barrier
	s_setprio 1
	v_mfma_f32_16x16x32_bf16 v[62:65], v[148:151], v[200:203], v[62:65]
	v_mfma_f32_16x16x32_bf16 v[58:61], v[166:169], v[200:203], v[58:61]
	v_mfma_f32_16x16x32_bf16 v[50:53], v[148:151], v[208:211], v[50:53]
	v_mfma_f32_16x16x32_bf16 v[42:45], v[166:169], v[208:211], v[42:45]
	v_mfma_f32_16x16x32_bf16 v[34:37], v[148:151], v[216:219], v[34:37]
	v_mfma_f32_16x16x32_bf16 v[26:29], v[166:169], v[216:219], v[26:29]
	v_mfma_f32_16x16x32_bf16 v[18:21], v[148:151], v[224:227], v[18:21]
	v_mfma_f32_16x16x32_bf16 v[10:13], v[166:169], v[224:227], v[10:13]
	v_mfma_f32_16x16x32_bf16 v[62:65], v[162:165], v[204:207], v[62:65]
	v_mfma_f32_16x16x32_bf16 v[58:61], v[170:173], v[204:207], v[58:61]
	v_mfma_f32_16x16x32_bf16 v[50:53], v[162:165], v[212:215], v[50:53]
	v_mfma_f32_16x16x32_bf16 v[42:45], v[170:173], v[212:215], v[42:45]
	v_mfma_f32_16x16x32_bf16 v[34:37], v[162:165], v[220:223], v[34:37]
	v_mfma_f32_16x16x32_bf16 v[26:29], v[170:173], v[220:223], v[26:29]
	v_mfma_f32_16x16x32_bf16 v[18:21], v[162:165], v[228:231], v[18:21]
	v_mfma_f32_16x16x32_bf16 v[10:13], v[170:173], v[228:231], v[10:13]
	s_setprio 0
	s_setprio 1
	v_mfma_f32_16x16x32_bf16 v[54:57], v[174:177], v[200:203], v[54:57]
	v_mfma_f32_16x16x32_bf16 v[46:49], v[182:185], v[200:203], v[46:49]
	v_mfma_f32_16x16x32_bf16 v[38:41], v[174:177], v[208:211], v[38:41]
	v_mfma_f32_16x16x32_bf16 v[30:33], v[182:185], v[208:211], v[30:33]
	v_mfma_f32_16x16x32_bf16 v[22:25], v[174:177], v[216:219], v[22:25]
	v_mfma_f32_16x16x32_bf16 v[14:17], v[182:185], v[216:219], v[14:17]
	v_mfma_f32_16x16x32_bf16 v[6:9], v[174:177], v[224:227], v[6:9]
	v_mfma_f32_16x16x32_bf16 v[2:5], v[182:185], v[224:227], v[2:5]
	v_mfma_f32_16x16x32_bf16 v[54:57], v[178:181], v[204:207], v[54:57]
	v_mfma_f32_16x16x32_bf16 v[46:49], v[196:199], v[204:207], v[46:49]
	v_mfma_f32_16x16x32_bf16 v[38:41], v[178:181], v[212:215], v[38:41]
	v_mfma_f32_16x16x32_bf16 v[30:33], v[196:199], v[212:215], v[30:33]
	v_mfma_f32_16x16x32_bf16 v[22:25], v[178:181], v[220:223], v[22:25]
	v_mfma_f32_16x16x32_bf16 v[14:17], v[196:199], v[220:223], v[14:17]
	v_mfma_f32_16x16x32_bf16 v[6:9], v[178:181], v[228:231], v[6:9]
	v_mfma_f32_16x16x32_bf16 v[2:5], v[196:199], v[228:231], v[2:5]
	s_setprio 0
	s_barrier
	s_add_i32 s67, s67, 2
	s_add_u32 s38, s38, 0x100
	s_addc_u32 s39, s39, 0
	s_add_u32 s65, s65, 0x100
	s_addc_u32 s66, s66, 0
	s_cmp_gt_u32 s67, 61
	s_cbranch_scc0 .LBB0_741
	s_and_b64 vcc, exec, s[14:15]
	s_cbranch_vccz .LBB0_744
	s_barrier

; #define PG8_STAGE(bufoff, gbase, voff) do { _Pragma("unroll") for (int _i = 0; _i < 2; ++_i) \
;         __builtin_amdgcn_global_load_lds((const unsigned*)((const char*)(gbase) + (voff)[_i]), (PG8_LAS unsigned*)(lds + (bufoff) + ldsw + _i * 8192), 16, 0, 0); } while (0)
; #define PG8_LDA(dst, b, h) do { _Pragma("unroll") for (int m = 0; m < 4; ++m) _Pragma("unroll") for (int k = 0; k < 2; ++k) dst[m][k] = *(const PG8_LAS bf16x8*)(lds + PG8_SA(b, h) + aoff + m * 2048 + k * 1024); } while (0)
; #define PG8_LDB(dst, b, h) do { _Pragma("unroll") for (int n = 0; n < 2; ++n) _Pragma("unroll") for (int k = 0; k < 2; ++k) dst[n][k] = *(const PG8_LAS bf16x8*)(lds + PG8_SB(b, h) + boff + n * 2048 + k * 1024); } while (0)
; #define PG8_MMA(ai, bj, At, Bt) do { __builtin_amdgcn_s_setprio(1); _Pragma("unroll") for (int m = 0; m < 4; ++m) _Pragma("unroll") for (int n = 0; n < 2; ++n) _Pragma("unroll") for (int k = 0; k < 2; ++k) \
;         acc[ai][bj][m][n] = __builtin_amdgcn_mfma_f32_16x16x32_bf16(Bt[n][k], At[m][k], acc[ai][bj][m][n], 0, 0, 0); __builtin_amdgcn_s_setprio(0); } while (0)
; #define PG8_WAIT_V(n) asm volatile("s_waitcnt vmcnt(" #n ")" ::: "memory")
; #define PG8_WAIT_L(n) asm volatile("s_waitcnt lgkmcnt(" #n ")" ::: "memory")
; #define PG8_BAR __builtin_amdgcn_s_barrier()
; template <class Epi, class Sched, bool ALIGN_EPI = false, bool SP2 = false>
; __device__ __forceinline__ void gemm_phase(PG8_LAS unsigned char* lds, const Gemm g, const Sched& S, const Epi& E) {
;     ...
;             const char* a1 = cA + (size_t)(t + 1) * kstep;
;             const char* a2 = last ? nA : cA + (size_t)(t + 2) * kstep; const char* b2 = last ? nB : cB + (size_t)(t + 2) * kstep;
;             const char* a3 = a2 + kstep; const char* b3 = b2 + kstep;
;             if (last && has_next) S.a_ready(nxt);
;             if constexpr (SP2) {
;             PG8_LDB(B0, 0, 0); PG8_LDB(B1, 0, 1); PG8_SCHED; PG8_LDA(At, 0, 0); PG8_STAGE(PG8_SA(1, 1), a1 + hstepA, voffA);
;             PG8_WAIT_V(8); PG8_WAIT_L(0); PG8_BAR; PG8_MMA(0, 0, At, B0); PG8_MMA(0, 1, At, B1); PG8_BAR; PG8_SCHED;
;             PG8_LDA(At, 0, 1); PG8_STAGE(PG8_SB(0, 0), b2, voffB); PG8_STAGE(PG8_SB(0, 1), b2 + hstepB, voffB); PG8_STAGE(PG8_SA(0, 0), a2, voffA);
;             PG8_WAIT_V(8); PG8_WAIT_L(0); PG8_BAR; PG8_MMA(1, 0, At, B0); PG8_MMA(1, 1, At, B1); PG8_BAR; PG8_SCHED;
.LBB0_1050:
	ds_read_b128 v[58:61], v191
	ds_read_b128 v[62:65], v191 offset:1024
	ds_read_b128 v[66:69], v191 offset:2048
	ds_read_b128 v[70:73], v191 offset:3072
	ds_read_b128 v[74:77], v193
	ds_read_b128 v[78:81], v193 offset:1024
	ds_read_b128 v[86:89], v193 offset:2048
	ds_read_b128 v[90:93], v193 offset:3072
	s_add_u32 s34, s2, 0xffe00080
	s_addc_u32 s35, s3, -1
	s_cmp_eq_u32 s56, 28
	s_cselect_b32 s37, s27, s35
	s_cselect_b32 s36, s26, s34
	s_cselect_b32 s35, s23, s55
	s_cselect_b32 s34, s25, s54
	v_lshl_add_u64 v[220:221], s[2:3], 0, v[204:205]
	s_add_i32 m0, s31, 0xc000
	ds_read_b128 v[158:161], v195
	ds_read_b128 v[166:169], v195 offset:1024
	ds_read_b128 v[170:173], v195 offset:2048
	ds_read_b128 v[174:177], v195 offset:3072
	ds_read_b128 v[178:181], v195 offset:4096
	ds_read_b128 v[182:185], v195 offset:5120
	ds_read_b128 v[212:215], v195 offset:6144
	ds_read_b128 v[216:219], v195 offset:7168
	global_load_lds_dwordx4 v[220:221], off
	v_lshl_add_u64 v[220:221], s[2:3], 0, v[206:207]
	s_add_i32 m0, s31, 0xe000
	s_nop 0
	global_load_lds_dwordx4 v[220:221], off
	s_waitcnt vmcnt(8)
	s_waitcnt lgkmcnt(0)
	s_barrier
	s_setprio 1
	v_mfma_f32_16x16x32_bf16 v[162:165], v[58:61], v[158:161], v[162:165]
	v_mfma_f32_16x16x32_bf16 v[154:157], v[66:69], v[158:161], v[154:157]
	v_mfma_f32_16x16x32_bf16 v[142:145], v[58:61], v[170:173], v[142:145]
	v_mfma_f32_16x16x32_bf16 v[138:141], v[66:69], v[170:173], v[138:141]
	v_mfma_f32_16x16x32_bf16 v[126:129], v[58:61], v[178:181], v[126:129]
	v_mfma_f32_16x16x32_bf16 v[122:125], v[66:69], v[178:181], v[122:125]
	v_mfma_f32_16x16x32_bf16 v[110:113], v[58:61], v[212:215], v[110:113]
	v_mfma_f32_16x16x32_bf16 v[106:109], v[66:69], v[212:215], v[106:109]
	v_mfma_f32_16x16x32_bf16 v[162:165], v[62:65], v[166:169], v[162:165]
	v_mfma_f32_16x16x32_bf16 v[154:157], v[70:73], v[166:169], v[154:157]
	v_mfma_f32_16x16x32_bf16 v[142:145], v[62:65], v[174:177], v[142:145]
	v_mfma_f32_16x16x32_bf16 v[138:141], v[70:73], v[174:177], v[138:141]
	v_mfma_f32_16x16x32_bf16 v[126:129], v[62:65], v[182:185], v[126:129]
	v_mfma_f32_16x16x32_bf16 v[122:125], v[70:73], v[182:185], v[122:125]
	v_mfma_f32_16x16x32_bf16 v[110:113], v[62:65], v[216:219], v[110:113]
	v_mfma_f32_16x16x32_bf16 v[106:109], v[70:73], v[216:219], v[106:109]
	s_setprio 0
	s_setprio 1
	v_mfma_f32_16x16x32_bf16 v[150:153], v[74:77], v[158:161], v[150:153]
	v_mfma_f32_16x16x32_bf16 v[146:149], v[86:89], v[158:161], v[146:149]
	v_mfma_f32_16x16x32_bf16 v[134:137], v[74:77], v[170:173], v[134:137]
	v_mfma_f32_16x16x32_bf16 v[130:133], v[86:89], v[170:173], v[130:133]
	v_mfma_f32_16x16x32_bf16 v[118:121], v[74:77], v[178:181], v[118:121]
	v_mfma_f32_16x16x32_bf16 v[114:117], v[86:89], v[178:181], v[114:117]
	v_mfma_f32_16x16x32_bf16 v[102:105], v[74:77], v[212:215], v[102:105]
	v_mfma_f32_16x16x32_bf16 v[98:101], v[86:89], v[212:215], v[98:101]
	v_mfma_f32_16x16x32_bf16 v[150:153], v[78:81], v[166:169], v[150:153]
	v_mfma_f32_16x16x32_bf16 v[146:149], v[90:93], v[166:169], v[146:149]
	v_mfma_f32_16x16x32_bf16 v[134:137], v[78:81], v[174:177], v[134:137]
	v_mfma_f32_16x16x32_bf16 v[130:133], v[90:93], v[174:177], v[130:133]
	v_mfma_f32_16x16x32_bf16 v[118:121], v[78:81], v[182:185], v[118:121]
	v_mfma_f32_16x16x32_bf16 v[114:117], v[90:93], v[182:185], v[114:117]
	v_mfma_f32_16x16x32_bf16 v[102:105], v[78:81], v[216:219], v[102:105]
	v_mfma_f32_16x16x32_bf16 v[98:101], v[90:93], v[216:219], v[98:101]
	s_setprio 0
	s_barrier
	s_add_i32 s57, s51, s42
	v_lshl_add_u64 v[220:221], s[34:35], 0, v[198:199]
	s_mov_b32 m0, s57
	ds_read_b128 v[158:161], v195 offset:16384
	ds_read_b128 v[166:169], v195 offset:17408
	ds_read_b128 v[170:173], v195 offset:18432
	ds_read_b128 v[174:177], v195 offset:19456
	ds_read_b128 v[178:181], v195 offset:20480
	ds_read_b128 v[182:185], v195 offset:21504
	ds_read_b128 v[212:215], v195 offset:22528
	ds_read_b128 v[216:219], v195 offset:23552
	global_load_lds_dwordx4 v[220:221], off
	s_add_i32 m0, s57, 0x2000
	s_add_u32 s58, s34, 0x80000
	v_lshl_add_u64 v[222:223], s[34:35], 0, v[202:203]
	s_addc_u32 s59, s35, 0
	s_add_i32 s57, s52, s42
	global_load_lds_dwordx4 v[222:223], off
	v_lshl_add_u64 v[224:225], s[58:59], 0, v[198:199]
	s_mov_b32 m0, s57
	v_lshl_add_u64 v[226:227], s[36:37], 0, v[200:201]
	global_load_lds_dwordx4 v[224:225], off
	v_lshl_add_u64 v[224:225], s[58:59], 0, v[202:203]
	s_add_i32 m0, s57, 0x2000
	s_nop 0
	global_load_lds_dwordx4 v[224:225], off
	v_lshl_add_u64 v[224:225], s[36:37], 0, v[196:197]
	s_mov_b32 m0, s31
	s_nop 0
	global_load_lds_dwordx4 v[224:225], off
	s_mov_b32 m0, s43
	s_nop 0
	global_load_lds_dwordx4 v[226:227], off
	s_waitcnt vmcnt(8)
	s_waitcnt lgkmcnt(0)
	s_barrier
; #define PG8_STAGE(bufoff, gbase, voff) do { _Pragma("unroll") for (int _i = 0; _i < 2; ++_i) \
;         __builtin_amdgcn_global_load_lds((const unsigned*)((const char*)(gbase) + (voff)[_i]), (PG8_LAS unsigned*)(lds + (bufoff) + ldsw + _i * 8192), 16, 0, 0); } while (0)
; #define PG8_LDA(dst, b, h) do { _Pragma("unroll") for (int m = 0; m < 4; ++m) _Pragma("unroll") for (int k = 0; k < 2; ++k) dst[m][k] = *(const PG8_LAS bf16x8*)(lds + PG8_SA(b, h) + aoff + m * 2048 + k * 1024); } while (0)
; #define PG8_LDB(dst, b, h) do { _Pragma("unroll") for (int n = 0; n < 2; ++n) _Pragma("unroll") for (int k = 0; k < 2; ++k) dst[n][k] = *(const PG8_LAS bf16x8*)(lds + PG8_SB(b, h) + boff + n * 2048 + k * 1024); } while (0)
; #define PG8_MMA(ai, bj, At, Bt) do { __builtin_amdgcn_s_setprio(1); _Pragma("unroll") for (int m = 0; m < 4; ++m) _Pragma("unroll") for (int n = 0; n < 2; ++n) _Pragma("unroll") for (int k = 0; k < 2; ++k) \
;         acc[ai][bj][m][n] = __builtin_amdgcn_mfma_f32_16x16x32_bf16(Bt[n][k], At[m][k], acc[ai][bj][m][n], 0, 0, 0); __builtin_amdgcn_s_setprio(0); } while (0)
; #define PG8_WAIT_V(n) asm volatile("s_waitcnt vmcnt(" #n ")" ::: "memory")
; #define PG8_WAIT_L(n) asm volatile("s_waitcnt lgkmcnt(" #n ")" ::: "memory")
; #define PG8_BAR __builtin_amdgcn_s_barrier()
; #define PG8_SCHED __builtin_amdgcn_sched_barrier(0)
; template <class Epi, class Sched, bool ALIGN_EPI = false, bool SP2 = false>
; __device__ __forceinline__ void gemm_phase(PG8_LAS unsigned char* lds, const Gemm g, const Sched& S, const Epi& E) {
;     ...
;             PG8_WAIT_V(8); PG8_WAIT_L(0); PG8_BAR; PG8_MMA(1, 0, At, B0); PG8_MMA(1, 1, At, B1); PG8_BAR; PG8_SCHED;
;             PG8_LDB(B0, 1, 0); PG8_LDB(B1, 1, 1); PG8_SCHED; PG8_LDA(At, 1, 0); PG8_STAGE(PG8_SA(0, 1), a2 + hstepA, voffA);
;             PG8_WAIT_V(8); PG8_WAIT_L(0); PG8_BAR; PG8_MMA(0, 0, At, B0); PG8_MMA(0, 1, At, B1); PG8_BAR; PG8_SCHED;
	s_setprio 1
	v_mfma_f32_16x16x32_bf16 v[94:97], v[58:61], v[158:161], v[94:97]
	v_mfma_f32_16x16x32_bf16 v[82:85], v[66:69], v[158:161], v[82:85]
	v_mfma_f32_16x16x32_bf16 v[46:49], v[58:61], v[170:173], v[46:49]
	v_mfma_f32_16x16x32_bf16 v[42:45], v[66:69], v[170:173], v[42:45]
	v_mfma_f32_16x16x32_bf16 v[30:33], v[58:61], v[178:181], v[30:33]
	v_mfma_f32_16x16x32_bf16 v[26:29], v[66:69], v[178:181], v[26:29]
	v_mfma_f32_16x16x32_bf16 v[14:17], v[58:61], v[212:215], v[14:17]
	v_mfma_f32_16x16x32_bf16 v[10:13], v[66:69], v[212:215], v[10:13]
	v_mfma_f32_16x16x32_bf16 v[94:97], v[62:65], v[166:169], v[94:97]
	v_mfma_f32_16x16x32_bf16 v[82:85], v[70:73], v[166:169], v[82:85]
	v_mfma_f32_16x16x32_bf16 v[46:49], v[62:65], v[174:177], v[46:49]
	v_mfma_f32_16x16x32_bf16 v[42:45], v[70:73], v[174:177], v[42:45]
	v_mfma_f32_16x16x32_bf16 v[30:33], v[62:65], v[182:185], v[30:33]
	v_mfma_f32_16x16x32_bf16 v[26:29], v[70:73], v[182:185], v[26:29]
	v_mfma_f32_16x16x32_bf16 v[14:17], v[62:65], v[216:219], v[14:17]
	v_mfma_f32_16x16x32_bf16 v[10:13], v[70:73], v[216:219], v[10:13]
	s_setprio 0
	s_setprio 1
	v_mfma_f32_16x16x32_bf16 v[54:57], v[74:77], v[158:161], v[54:57]
	v_mfma_f32_16x16x32_bf16 v[50:53], v[86:89], v[158:161], v[50:53]
	v_mfma_f32_16x16x32_bf16 v[38:41], v[74:77], v[170:173], v[38:41]
	v_mfma_f32_16x16x32_bf16 v[34:37], v[86:89], v[170:173], v[34:37]
	v_mfma_f32_16x16x32_bf16 v[22:25], v[74:77], v[178:181], v[22:25]
	v_mfma_f32_16x16x32_bf16 v[18:21], v[86:89], v[178:181], v[18:21]
	v_mfma_f32_16x16x32_bf16 v[6:9], v[74:77], v[212:215], v[6:9]
	v_mfma_f32_16x16x32_bf16 v[2:5], v[86:89], v[212:215], v[2:5]
	v_mfma_f32_16x16x32_bf16 v[54:57], v[78:81], v[166:169], v[54:57]
	v_mfma_f32_16x16x32_bf16 v[50:53], v[90:93], v[166:169], v[50:53]
	v_mfma_f32_16x16x32_bf16 v[38:41], v[78:81], v[174:177], v[38:41]
	v_mfma_f32_16x16x32_bf16 v[34:37], v[90:93], v[174:177], v[34:37]
	v_mfma_f32_16x16x32_bf16 v[22:25], v[78:81], v[182:185], v[22:25]
	v_mfma_f32_16x16x32_bf16 v[18:21], v[90:93], v[182:185], v[18:21]
	v_mfma_f32_16x16x32_bf16 v[6:9], v[78:81], v[216:219], v[6:9]
	v_mfma_f32_16x16x32_bf16 v[2:5], v[90:93], v[216:219], v[2:5]
	s_setprio 0
	s_barrier
	s_add_i32 s57, 0, 0x18000
	s_add_i32 s58, 0, 0x1c000
	v_add_u32_e32 v70, s57, v187
	v_add_u32_e32 v90, s58, v187
	ds_read_b128 v[58:61], v70
	ds_read_b128 v[62:65], v70 offset:1024
	ds_read_b128 v[66:69], v70 offset:2048
	ds_read_b128 v[70:73], v70 offset:3072
	ds_read_b128 v[74:77], v90
	ds_read_b128 v[78:81], v90 offset:1024
	ds_read_b128 v[86:89], v90 offset:2048
	ds_read_b128 v[90:93], v90 offset:3072
	s_add_u32 s36, s36, 0x200000
	s_addc_u32 s37, s37, 0
	s_mov_b32 m0, s44
	v_lshl_add_u64 v[228:229], s[36:37], 0, v[196:197]
	ds_read_b128 v[158:161], v195 offset:32768
	ds_read_b128 v[166:169], v195 offset:33792
	ds_read_b128 v[170:173], v195 offset:34816
	ds_read_b128 v[174:177], v195 offset:35840
	ds_read_b128 v[178:181], v195 offset:36864
	ds_read_b128 v[182:185], v195 offset:37888
	ds_read_b128 v[212:215], v195 offset:38912
	ds_read_b128 v[216:219], v195 offset:39936
	global_load_lds_dwordx4 v[228:229], off
	v_lshl_add_u64 v[228:229], s[36:37], 0, v[200:201]
	s_mov_b32 m0, s45
	s_nop 0
	global_load_lds_dwordx4 v[228:229], off
	s_waitcnt vmcnt(8)
	s_waitcnt lgkmcnt(0)
	s_barrier
	s_setprio 1
	v_mfma_f32_16x16x32_bf16 v[162:165], v[58:61], v[158:161], v[162:165]
	v_mfma_f32_16x16x32_bf16 v[154:157], v[66:69], v[158:161], v[154:157]
	v_mfma_f32_16x16x32_bf16 v[142:145], v[58:61], v[170:173], v[142:145]
	v_mfma_f32_16x16x32_bf16 v[138:141], v[66:69], v[170:173], v[138:141]
	v_mfma_f32_16x16x32_bf16 v[126:129], v[58:61], v[178:181], v[126:129]
	v_mfma_f32_16x16x32_bf16 v[122:125], v[66:69], v[178:181], v[122:125]
	v_mfma_f32_16x16x32_bf16 v[110:113], v[58:61], v[212:215], v[110:113]
	v_mfma_f32_16x16x32_bf16 v[106:109], v[66:69], v[212:215], v[106:109]
	v_mfma_f32_16x16x32_bf16 v[162:165], v[62:65], v[166:169], v[162:165]
	v_mfma_f32_16x16x32_bf16 v[154:157], v[70:73], v[166:169], v[154:157]
	v_mfma_f32_16x16x32_bf16 v[142:145], v[62:65], v[174:177], v[142:145]
	v_mfma_f32_16x16x32_bf16 v[138:141], v[70:73], v[174:177], v[138:141]
	v_mfma_f32_16x16x32_bf16 v[126:129], v[62:65], v[182:185], v[126:129]
	v_mfma_f32_16x16x32_bf16 v[122:125], v[70:73], v[182:185], v[122:125]
	v_mfma_f32_16x16x32_bf16 v[110:113], v[62:65], v[216:219], v[110:113]
	v_mfma_f32_16x16x32_bf16 v[106:109], v[70:73], v[216:219], v[106:109]
	s_setprio 0
	s_setprio 1
	v_mfma_f32_16x16x32_bf16 v[150:153], v[74:77], v[158:161], v[150:153]
	v_mfma_f32_16x16x32_bf16 v[146:149], v[86:89], v[158:161], v[146:149]
	v_mfma_f32_16x16x32_bf16 v[134:137], v[74:77], v[170:173], v[134:137]
	v_mfma_f32_16x16x32_bf16 v[130:133], v[86:89], v[170:173], v[130:133]
	v_mfma_f32_16x16x32_bf16 v[118:121], v[74:77], v[178:181], v[118:121]
	v_mfma_f32_16x16x32_bf16 v[114:117], v[86:89], v[178:181], v[114:117]
	v_mfma_f32_16x16x32_bf16 v[102:105], v[74:77], v[212:215], v[102:105]
	v_mfma_f32_16x16x32_bf16 v[98:101], v[86:89], v[212:215], v[98:101]
	v_mfma_f32_16x16x32_bf16 v[150:153], v[78:81], v[166:169], v[150:153]
	v_mfma_f32_16x16x32_bf16 v[146:149], v[90:93], v[166:169], v[146:149]
	v_mfma_f32_16x16x32_bf16 v[134:137], v[78:81], v[174:177], v[134:137]
	v_mfma_f32_16x16x32_bf16 v[130:133], v[90:93], v[174:177], v[130:133]
	v_mfma_f32_16x16x32_bf16 v[118:121], v[78:81], v[182:185], v[118:121]
	v_mfma_f32_16x16x32_bf16 v[114:117], v[90:93], v[182:185], v[114:117]
	v_mfma_f32_16x16x32_bf16 v[102:105], v[78:81], v[216:219], v[102:105]
	v_mfma_f32_16x16x32_bf16 v[98:101], v[90:93], v[216:219], v[98:101]
	s_setprio 0
	s_barrier
; #define PG8_STAGE(bufoff, gbase, voff) do { _Pragma("unroll") for (int _i = 0; _i < 2; ++_i) \
;         __builtin_amdgcn_global_load_lds((const unsigned*)((const char*)(gbase) + (voff)[_i]), (PG8_LAS unsigned*)(lds + (bufoff) + ldsw + _i * 8192), 16, 0, 0); } while (0)
; #define PG8_LDA(dst, b, h) do { _Pragma("unroll") for (int m = 0; m < 4; ++m) _Pragma("unroll") for (int k = 0; k < 2; ++k) dst[m][k] = *(const PG8_LAS bf16x8*)(lds + PG8_SA(b, h) + aoff + m * 2048 + k * 1024); } while (0)
; #define PG8_MMA(ai, bj, At, Bt) do { __builtin_amdgcn_s_setprio(1); _Pragma("unroll") for (int m = 0; m < 4; ++m) _Pragma("unroll") for (int n = 0; n < 2; ++n) _Pragma("unroll") for (int k = 0; k < 2; ++k) \
;         acc[ai][bj][m][n] = __builtin_amdgcn_mfma_f32_16x16x32_bf16(Bt[n][k], At[m][k], acc[ai][bj][m][n], 0, 0, 0); __builtin_amdgcn_s_setprio(0); } while (0)
; #define PG8_WAIT_V(n) asm volatile("s_waitcnt vmcnt(" #n ")" ::: "memory")
; #define PG8_WAIT_L(n) asm volatile("s_waitcnt lgkmcnt(" #n ")" ::: "memory")
; #define PG8_BAR __builtin_amdgcn_s_barrier()
; #define PG8_SCHED __builtin_amdgcn_sched_barrier(0)
; template <class Epi, class Sched, bool ALIGN_EPI = false, bool SP2 = false>
; __device__ __forceinline__ void gemm_phase(PG8_LAS unsigned char* lds, const Gemm g, const Sched& S, const Epi& E) {
;     ...
;             PG8_LDA(At, 1, 1); PG8_STAGE(PG8_SB(1, 0), b3, voffB); PG8_STAGE(PG8_SB(1, 1), b3 + hstepB, voffB); PG8_STAGE(PG8_SA(1, 0), a3, voffA);
;             PG8_WAIT_V(8); PG8_WAIT_L(0); PG8_BAR; PG8_MMA(1, 0, At, B0); PG8_MMA(1, 1, At, B1); PG8_BAR; PG8_SCHED;
;     ...
;         if constexpr (ALIGN_EPI) { if (wr == 0) PG8_BAR; }
	s_add_i32 s36, s57, s42
	v_lshl_add_u64 v[220:221], v[220:221], 0, s[16:17]
	s_mov_b32 m0, s36
	ds_read_b128 v[158:161], v195 offset:49152
	ds_read_b128 v[166:169], v195 offset:50176
	ds_read_b128 v[170:173], v195 offset:51200
	ds_read_b128 v[174:177], v195 offset:52224
	ds_read_b128 v[178:181], v195 offset:53248
	ds_read_b128 v[182:185], v195 offset:54272
	ds_read_b128 v[212:215], v195 offset:55296
	ds_read_b128 v[216:219], v195 offset:56320
	global_load_lds_dwordx4 v[220:221], off
	s_add_i32 m0, s36, 0x2000
	s_add_u32 s34, s34, 0x80080
	v_lshl_add_u64 v[220:221], v[222:223], 0, s[16:17]
	s_addc_u32 s35, s35, 0
	s_add_i32 s36, s58, s42
	global_load_lds_dwordx4 v[220:221], off
	v_lshl_add_u64 v[220:221], s[34:35], 0, v[198:199]
	s_mov_b32 m0, s36
	s_nop 0
	global_load_lds_dwordx4 v[220:221], off
	v_lshl_add_u64 v[220:221], s[34:35], 0, v[202:203]
	s_add_i32 m0, s36, 0x2000
	s_nop 0
	global_load_lds_dwordx4 v[220:221], off
	v_lshl_add_u64 v[220:221], v[224:225], 0, s[16:17]
	s_mov_b32 m0, s48
	s_nop 0
	global_load_lds_dwordx4 v[220:221], off
	v_lshl_add_u64 v[220:221], v[226:227], 0, s[16:17]
	s_mov_b32 m0, s49
	s_nop 0
	global_load_lds_dwordx4 v[220:221], off
	s_waitcnt vmcnt(8)
	s_waitcnt lgkmcnt(0)
	s_barrier
	s_setprio 1
	v_mfma_f32_16x16x32_bf16 v[94:97], v[58:61], v[158:161], v[94:97]
	v_mfma_f32_16x16x32_bf16 v[82:85], v[66:69], v[158:161], v[82:85]
	v_mfma_f32_16x16x32_bf16 v[46:49], v[58:61], v[170:173], v[46:49]
	v_mfma_f32_16x16x32_bf16 v[42:45], v[66:69], v[170:173], v[42:45]
	v_mfma_f32_16x16x32_bf16 v[30:33], v[58:61], v[178:181], v[30:33]
	v_mfma_f32_16x16x32_bf16 v[26:29], v[66:69], v[178:181], v[26:29]
	v_mfma_f32_16x16x32_bf16 v[14:17], v[58:61], v[212:215], v[14:17]
	v_mfma_f32_16x16x32_bf16 v[10:13], v[66:69], v[212:215], v[10:13]
	v_mfma_f32_16x16x32_bf16 v[94:97], v[62:65], v[166:169], v[94:97]
	v_mfma_f32_16x16x32_bf16 v[82:85], v[70:73], v[166:169], v[82:85]
	v_mfma_f32_16x16x32_bf16 v[46:49], v[62:65], v[174:177], v[46:49]
	v_mfma_f32_16x16x32_bf16 v[42:45], v[70:73], v[174:177], v[42:45]
	v_mfma_f32_16x16x32_bf16 v[30:33], v[62:65], v[182:185], v[30:33]
	v_mfma_f32_16x16x32_bf16 v[26:29], v[70:73], v[182:185], v[26:29]
	v_mfma_f32_16x16x32_bf16 v[14:17], v[62:65], v[216:219], v[14:17]
	v_mfma_f32_16x16x32_bf16 v[10:13], v[70:73], v[216:219], v[10:13]
	s_setprio 0
	s_setprio 1
	v_mfma_f32_16x16x32_bf16 v[54:57], v[74:77], v[158:161], v[54:57]
	v_mfma_f32_16x16x32_bf16 v[50:53], v[86:89], v[158:161], v[50:53]
	v_mfma_f32_16x16x32_bf16 v[38:41], v[74:77], v[170:173], v[38:41]
	v_mfma_f32_16x16x32_bf16 v[34:37], v[86:89], v[170:173], v[34:37]
	v_mfma_f32_16x16x32_bf16 v[22:25], v[74:77], v[178:181], v[22:25]
	v_mfma_f32_16x16x32_bf16 v[18:21], v[86:89], v[178:181], v[18:21]
	v_mfma_f32_16x16x32_bf16 v[6:9], v[74:77], v[212:215], v[6:9]
	v_mfma_f32_16x16x32_bf16 v[2:5], v[86:89], v[212:215], v[2:5]
	v_mfma_f32_16x16x32_bf16 v[54:57], v[78:81], v[166:169], v[54:57]
	v_mfma_f32_16x16x32_bf16 v[50:53], v[90:93], v[166:169], v[50:53]
	v_mfma_f32_16x16x32_bf16 v[38:41], v[78:81], v[174:177], v[38:41]
	v_mfma_f32_16x16x32_bf16 v[34:37], v[90:93], v[174:177], v[34:37]
	v_mfma_f32_16x16x32_bf16 v[22:25], v[78:81], v[182:185], v[22:25]
	v_mfma_f32_16x16x32_bf16 v[18:21], v[90:93], v[182:185], v[18:21]
	v_mfma_f32_16x16x32_bf16 v[6:9], v[78:81], v[216:219], v[6:9]
	v_mfma_f32_16x16x32_bf16 v[2:5], v[90:93], v[216:219], v[2:5]
	s_setprio 0
	s_barrier
	s_add_i32 s56, s56, 2
	s_add_u32 s2, s2, 0x100
	s_addc_u32 s3, s3, 0
	s_add_u32 s54, s54, 0x100
	s_addc_u32 s55, s55, 0
	s_cmp_gt_u32 s56, 29
	s_cbranch_scc0 .LBB0_1050
	s_and_b64 vcc, exec, s[18:19]
	s_cbranch_vccz .LBB0_1053
	s_barrier

; #define PG8_STAGE(bufoff, gbase, voff) do { _Pragma("unroll") for (int _i = 0; _i < 2; ++_i) \
;         __builtin_amdgcn_global_load_lds((const unsigned*)((const char*)(gbase) + (voff)[_i]), (PG8_LAS unsigned*)(lds + (bufoff) + ldsw + _i * 8192), 16, 0, 0); } while (0)
; #define PG8_LDA(dst, b, h) do { _Pragma("unroll") for (int m = 0; m < 4; ++m) _Pragma("unroll") for (int k = 0; k < 2; ++k) dst[m][k] = *(const PG8_LAS bf16x8*)(lds + PG8_SA(b, h) + aoff + m * 2048 + k * 1024); } while (0)
; #define PG8_LDB(dst, b, h) do { _Pragma("unroll") for (int n = 0; n < 2; ++n) _Pragma("unroll") for (int k = 0; k < 2; ++k) dst[n][k] = *(const PG8_LAS bf16x8*)(lds + PG8_SB(b, h) + boff + n * 2048 + k * 1024); } while (0)
; #define PG8_MMA(ai, bj, At, Bt) do { __builtin_amdgcn_s_setprio(1); _Pragma("unroll") for (int m = 0; m < 4; ++m) _Pragma("unroll") for (int n = 0; n < 2; ++n) _Pragma("unroll") for (int k = 0; k < 2; ++k) \
;         acc[ai][bj][m][n] = __builtin_amdgcn_mfma_f32_16x16x32_bf16(Bt[n][k], At[m][k], acc[ai][bj][m][n], 0, 0, 0); __builtin_amdgcn_s_setprio(0); } while (0)
; #define PG8_WAIT_V(n) asm volatile("s_waitcnt vmcnt(" #n ")" ::: "memory")
; #define PG8_WAIT_L(n) asm volatile("s_waitcnt lgkmcnt(" #n ")" ::: "memory")
; #define PG8_BAR __builtin_amdgcn_s_barrier()
; template <class Epi, class Sched, bool ALIGN_EPI = false, bool SP2 = false>
; __device__ __forceinline__ void gemm_phase(PG8_LAS unsigned char* lds, const Gemm g, const Sched& S, const Epi& E) {
;     ...
;             const char* a1 = cA + (size_t)(t + 1) * kstep;
;             const char* a2 = last ? nA : cA + (size_t)(t + 2) * kstep; const char* b2 = last ? nB : cB + (size_t)(t + 2) * kstep;
;             const char* a3 = a2 + kstep; const char* b3 = b2 + kstep;
;             if (last && has_next) S.a_ready(nxt);
;             if constexpr (SP2) {
;             PG8_LDB(B0, 0, 0); PG8_LDB(B1, 0, 1); PG8_SCHED; PG8_LDA(At, 0, 0); PG8_STAGE(PG8_SA(1, 1), a1 + hstepA, voffA);
;             PG8_WAIT_V(8); PG8_WAIT_L(0); PG8_BAR; PG8_MMA(0, 0, At, B0); PG8_MMA(0, 1, At, B1); PG8_BAR; PG8_SCHED;
;             PG8_LDA(At, 0, 1); PG8_STAGE(PG8_SB(0, 0), b2, voffB); PG8_STAGE(PG8_SB(0, 1), b2 + hstepB, voffB); PG8_STAGE(PG8_SA(0, 0), a2, voffA);
;             PG8_WAIT_V(8); PG8_WAIT_L(0); PG8_BAR; PG8_MMA(1, 0, At, B0); PG8_MMA(1, 1, At, B1); PG8_BAR; PG8_SCHED;
.LBB0_1127:
	ds_read_b128 v[130:133], v191
	ds_read_b128 v[134:137], v191 offset:1024
	ds_read_b128 v[138:141], v191 offset:2048
	ds_read_b128 v[142:145], v191 offset:3072
	ds_read_b128 v[146:149], v193
	ds_read_b128 v[150:153], v193 offset:1024
	ds_read_b128 v[170:173], v193 offset:2048
	ds_read_b128 v[174:177], v193 offset:3072
	s_add_u32 s30, s28, 0xffe00080
	s_addc_u32 s31, s29, -1
	s_cmpk_eq_i32 s55, 0x7c
	s_cselect_b32 s35, s19, s31
	s_cselect_b32 s34, s25, s30
	s_cselect_b32 s31, s17, s54
	s_cselect_b32 s30, s52, s53
	v_lshl_add_u64 v[220:221], s[28:29], 0, v[162:163]
	s_add_i32 m0, s27, 0xc000
	ds_read_b128 v[178:181], v195
	ds_read_b128 v[182:185], v195 offset:1024
	ds_read_b128 v[196:199], v195 offset:2048
	ds_read_b128 v[200:203], v195 offset:3072
	ds_read_b128 v[204:207], v195 offset:4096
	ds_read_b128 v[208:211], v195 offset:5120
	ds_read_b128 v[212:215], v195 offset:6144
	ds_read_b128 v[216:219], v195 offset:7168
	global_load_lds_dwordx4 v[220:221], off
	v_lshl_add_u64 v[220:221], s[28:29], 0, v[164:165]
	s_add_i32 m0, s27, 0xe000
	s_nop 0
	global_load_lds_dwordx4 v[220:221], off
	s_waitcnt vmcnt(8)
	s_waitcnt lgkmcnt(0)
	s_barrier
	s_setprio 1
	v_mfma_f32_16x16x32_bf16 v[126:129], v[130:133], v[178:181], v[126:129]
	v_mfma_f32_16x16x32_bf16 v[122:125], v[138:141], v[178:181], v[122:125]
	v_mfma_f32_16x16x32_bf16 v[110:113], v[130:133], v[196:199], v[110:113]
	v_mfma_f32_16x16x32_bf16 v[106:109], v[138:141], v[196:199], v[106:109]
	v_mfma_f32_16x16x32_bf16 v[94:97], v[130:133], v[204:207], v[94:97]
	v_mfma_f32_16x16x32_bf16 v[90:93], v[138:141], v[204:207], v[90:93]
	v_mfma_f32_16x16x32_bf16 v[78:81], v[130:133], v[212:215], v[78:81]
	v_mfma_f32_16x16x32_bf16 v[74:77], v[138:141], v[212:215], v[74:77]
	v_mfma_f32_16x16x32_bf16 v[126:129], v[134:137], v[182:185], v[126:129]
	v_mfma_f32_16x16x32_bf16 v[122:125], v[142:145], v[182:185], v[122:125]
	v_mfma_f32_16x16x32_bf16 v[110:113], v[134:137], v[200:203], v[110:113]
	v_mfma_f32_16x16x32_bf16 v[106:109], v[142:145], v[200:203], v[106:109]
	v_mfma_f32_16x16x32_bf16 v[94:97], v[134:137], v[208:211], v[94:97]
	v_mfma_f32_16x16x32_bf16 v[90:93], v[142:145], v[208:211], v[90:93]
	v_mfma_f32_16x16x32_bf16 v[78:81], v[134:137], v[216:219], v[78:81]
	v_mfma_f32_16x16x32_bf16 v[74:77], v[142:145], v[216:219], v[74:77]
	s_setprio 0
	s_setprio 1
	v_mfma_f32_16x16x32_bf16 v[118:121], v[146:149], v[178:181], v[118:121]
	v_mfma_f32_16x16x32_bf16 v[114:117], v[170:173], v[178:181], v[114:117]
	v_mfma_f32_16x16x32_bf16 v[102:105], v[146:149], v[196:199], v[102:105]
	v_mfma_f32_16x16x32_bf16 v[98:101], v[170:173], v[196:199], v[98:101]
	v_mfma_f32_16x16x32_bf16 v[86:89], v[146:149], v[204:207], v[86:89]
	v_mfma_f32_16x16x32_bf16 v[82:85], v[170:173], v[204:207], v[82:85]
	v_mfma_f32_16x16x32_bf16 v[70:73], v[146:149], v[212:215], v[70:73]
	v_mfma_f32_16x16x32_bf16 v[66:69], v[170:173], v[212:215], v[66:69]
	v_mfma_f32_16x16x32_bf16 v[118:121], v[150:153], v[182:185], v[118:121]
	v_mfma_f32_16x16x32_bf16 v[114:117], v[174:177], v[182:185], v[114:117]
	v_mfma_f32_16x16x32_bf16 v[102:105], v[150:153], v[200:203], v[102:105]
	v_mfma_f32_16x16x32_bf16 v[98:101], v[174:177], v[200:203], v[98:101]
	v_mfma_f32_16x16x32_bf16 v[86:89], v[150:153], v[208:211], v[86:89]
	v_mfma_f32_16x16x32_bf16 v[82:85], v[174:177], v[208:211], v[82:85]
	v_mfma_f32_16x16x32_bf16 v[70:73], v[150:153], v[216:219], v[70:73]
	v_mfma_f32_16x16x32_bf16 v[66:69], v[174:177], v[216:219], v[66:69]
	s_setprio 0
	s_barrier
	s_add_i32 s56, s48, s39
	v_lshl_add_u64 v[220:221], s[30:31], 0, v[156:157]
	s_mov_b32 m0, s56
	ds_read_b128 v[178:181], v195 offset:16384
	ds_read_b128 v[182:185], v195 offset:17408
	ds_read_b128 v[196:199], v195 offset:18432
	ds_read_b128 v[200:203], v195 offset:19456
	ds_read_b128 v[204:207], v195 offset:20480
	ds_read_b128 v[208:211], v195 offset:21504
	ds_read_b128 v[212:215], v195 offset:22528
	ds_read_b128 v[216:219], v195 offset:23552
	global_load_lds_dwordx4 v[220:221], off
	s_add_i32 m0, s56, 0x2000
	s_add_u32 s56, s30, 0x200000
	v_lshl_add_u64 v[222:223], s[30:31], 0, v[160:161]
	s_addc_u32 s57, s31, 0
	s_add_i32 s58, s49, s39
	global_load_lds_dwordx4 v[222:223], off
	v_lshl_add_u64 v[224:225], s[56:57], 0, v[156:157]
	s_mov_b32 m0, s58
	v_lshl_add_u64 v[226:227], s[34:35], 0, v[158:159]
	global_load_lds_dwordx4 v[224:225], off
	v_lshl_add_u64 v[224:225], s[56:57], 0, v[160:161]
	s_add_i32 m0, s58, 0x2000
	s_nop 0
	global_load_lds_dwordx4 v[224:225], off
	v_lshl_add_u64 v[224:225], s[34:35], 0, v[154:155]
	s_mov_b32 m0, s27
	s_nop 0
	global_load_lds_dwordx4 v[224:225], off
	s_mov_b32 m0, s40
	s_nop 0
	global_load_lds_dwordx4 v[226:227], off
	s_waitcnt vmcnt(8)
	s_waitcnt lgkmcnt(0)
	s_barrier
; #define PG8_STAGE(bufoff, gbase, voff) do { _Pragma("unroll") for (int _i = 0; _i < 2; ++_i) \
;         __builtin_amdgcn_global_load_lds((const unsigned*)((const char*)(gbase) + (voff)[_i]), (PG8_LAS unsigned*)(lds + (bufoff) + ldsw + _i * 8192), 16, 0, 0); } while (0)
; #define PG8_LDA(dst, b, h) do { _Pragma("unroll") for (int m = 0; m < 4; ++m) _Pragma("unroll") for (int k = 0; k < 2; ++k) dst[m][k] = *(const PG8_LAS bf16x8*)(lds + PG8_SA(b, h) + aoff + m * 2048 + k * 1024); } while (0)
; #define PG8_LDB(dst, b, h) do { _Pragma("unroll") for (int n = 0; n < 2; ++n) _Pragma("unroll") for (int k = 0; k < 2; ++k) dst[n][k] = *(const PG8_LAS bf16x8*)(lds + PG8_SB(b, h) + boff + n * 2048 + k * 1024); } while (0)
; #define PG8_MMA(ai, bj, At, Bt) do { __builtin_amdgcn_s_setprio(1); _Pragma("unroll") for (int m = 0; m < 4; ++m) _Pragma("unroll") for (int n = 0; n < 2; ++n) _Pragma("unroll") for (int k = 0; k < 2; ++k) \
;         acc[ai][bj][m][n] = __builtin_amdgcn_mfma_f32_16x16x32_bf16(Bt[n][k], At[m][k], acc[ai][bj][m][n], 0, 0, 0); __builtin_amdgcn_s_setprio(0); } while (0)
; #define PG8_WAIT_V(n) asm volatile("s_waitcnt vmcnt(" #n ")" ::: "memory")
; #define PG8_WAIT_L(n) asm volatile("s_waitcnt lgkmcnt(" #n ")" ::: "memory")
; #define PG8_BAR __builtin_amdgcn_s_barrier()
; #define PG8_SCHED __builtin_amdgcn_sched_barrier(0)
; template <class Epi, class Sched, bool ALIGN_EPI = false, bool SP2 = false>
; __device__ __forceinline__ void gemm_phase(PG8_LAS unsigned char* lds, const Gemm g, const Sched& S, const Epi& E) {
;     ...
;             PG8_WAIT_V(8); PG8_WAIT_L(0); PG8_BAR; PG8_MMA(1, 0, At, B0); PG8_MMA(1, 1, At, B1); PG8_BAR; PG8_SCHED;
;             PG8_LDB(B0, 1, 0); PG8_LDB(B1, 1, 1); PG8_SCHED; PG8_LDA(At, 1, 0); PG8_STAGE(PG8_SA(0, 1), a2 + hstepA, voffA);
;             PG8_WAIT_V(8); PG8_WAIT_L(0); PG8_BAR; PG8_MMA(0, 0, At, B0); PG8_MMA(0, 1, At, B1); PG8_BAR; PG8_SCHED;
	s_setprio 1
	v_mfma_f32_16x16x32_bf16 v[62:65], v[130:133], v[178:181], v[62:65]
	v_mfma_f32_16x16x32_bf16 v[58:61], v[138:141], v[178:181], v[58:61]
	v_mfma_f32_16x16x32_bf16 v[46:49], v[130:133], v[196:199], v[46:49]
	v_mfma_f32_16x16x32_bf16 v[42:45], v[138:141], v[196:199], v[42:45]
	v_mfma_f32_16x16x32_bf16 v[30:33], v[130:133], v[204:207], v[30:33]
	v_mfma_f32_16x16x32_bf16 v[26:29], v[138:141], v[204:207], v[26:29]
	v_mfma_f32_16x16x32_bf16 v[14:17], v[130:133], v[212:215], v[14:17]
	v_mfma_f32_16x16x32_bf16 v[10:13], v[138:141], v[212:215], v[10:13]
	v_mfma_f32_16x16x32_bf16 v[62:65], v[134:137], v[182:185], v[62:65]
	v_mfma_f32_16x16x32_bf16 v[58:61], v[142:145], v[182:185], v[58:61]
	v_mfma_f32_16x16x32_bf16 v[46:49], v[134:137], v[200:203], v[46:49]
	v_mfma_f32_16x16x32_bf16 v[42:45], v[142:145], v[200:203], v[42:45]
	v_mfma_f32_16x16x32_bf16 v[30:33], v[134:137], v[208:211], v[30:33]
	v_mfma_f32_16x16x32_bf16 v[26:29], v[142:145], v[208:211], v[26:29]
	v_mfma_f32_16x16x32_bf16 v[14:17], v[134:137], v[216:219], v[14:17]
	v_mfma_f32_16x16x32_bf16 v[10:13], v[142:145], v[216:219], v[10:13]
	s_setprio 0
	s_setprio 1
	v_mfma_f32_16x16x32_bf16 v[54:57], v[146:149], v[178:181], v[54:57]
	v_mfma_f32_16x16x32_bf16 v[50:53], v[170:173], v[178:181], v[50:53]
	v_mfma_f32_16x16x32_bf16 v[38:41], v[146:149], v[196:199], v[38:41]
	v_mfma_f32_16x16x32_bf16 v[34:37], v[170:173], v[196:199], v[34:37]
	v_mfma_f32_16x16x32_bf16 v[22:25], v[146:149], v[204:207], v[22:25]
	v_mfma_f32_16x16x32_bf16 v[18:21], v[170:173], v[204:207], v[18:21]
	v_mfma_f32_16x16x32_bf16 v[6:9], v[146:149], v[212:215], v[6:9]
	v_mfma_f32_16x16x32_bf16 v[2:5], v[170:173], v[212:215], v[2:5]
	v_mfma_f32_16x16x32_bf16 v[54:57], v[150:153], v[182:185], v[54:57]
	v_mfma_f32_16x16x32_bf16 v[50:53], v[174:177], v[182:185], v[50:53]
	v_mfma_f32_16x16x32_bf16 v[38:41], v[150:153], v[200:203], v[38:41]
	v_mfma_f32_16x16x32_bf16 v[34:37], v[174:177], v[200:203], v[34:37]
	v_mfma_f32_16x16x32_bf16 v[22:25], v[150:153], v[208:211], v[22:25]
	v_mfma_f32_16x16x32_bf16 v[18:21], v[174:177], v[208:211], v[18:21]
	v_mfma_f32_16x16x32_bf16 v[6:9], v[150:153], v[216:219], v[6:9]
	v_mfma_f32_16x16x32_bf16 v[2:5], v[174:177], v[216:219], v[2:5]
	s_setprio 0
	s_barrier
	s_add_i32 s56, 0, 0x18000
	s_add_i32 s57, 0, 0x1c000
	v_add_u32_e32 v142, s56, v187
	v_add_u32_e32 v174, s57, v187
	ds_read_b128 v[130:133], v142
	ds_read_b128 v[134:137], v142 offset:1024
	ds_read_b128 v[138:141], v142 offset:2048
	ds_read_b128 v[142:145], v142 offset:3072
	ds_read_b128 v[146:149], v174
	ds_read_b128 v[150:153], v174 offset:1024
	ds_read_b128 v[170:173], v174 offset:2048
	ds_read_b128 v[174:177], v174 offset:3072
	s_add_u32 s34, s34, 0x200000
	s_addc_u32 s35, s35, 0
	s_mov_b32 m0, s41
	v_lshl_add_u64 v[228:229], s[34:35], 0, v[154:155]
	ds_read_b128 v[178:181], v195 offset:32768
	ds_read_b128 v[182:185], v195 offset:33792
	ds_read_b128 v[196:199], v195 offset:34816
	ds_read_b128 v[200:203], v195 offset:35840
	ds_read_b128 v[204:207], v195 offset:36864
	ds_read_b128 v[208:211], v195 offset:37888
	ds_read_b128 v[212:215], v195 offset:38912
	ds_read_b128 v[216:219], v195 offset:39936
	global_load_lds_dwordx4 v[228:229], off
	v_lshl_add_u64 v[228:229], s[34:35], 0, v[158:159]
	s_mov_b32 m0, s42
	s_nop 0
	global_load_lds_dwordx4 v[228:229], off
	s_waitcnt vmcnt(8)
	s_waitcnt lgkmcnt(0)
	s_barrier
	s_setprio 1
	v_mfma_f32_16x16x32_bf16 v[126:129], v[130:133], v[178:181], v[126:129]
	v_mfma_f32_16x16x32_bf16 v[122:125], v[138:141], v[178:181], v[122:125]
	v_mfma_f32_16x16x32_bf16 v[110:113], v[130:133], v[196:199], v[110:113]
	v_mfma_f32_16x16x32_bf16 v[106:109], v[138:141], v[196:199], v[106:109]
	v_mfma_f32_16x16x32_bf16 v[94:97], v[130:133], v[204:207], v[94:97]
	v_mfma_f32_16x16x32_bf16 v[90:93], v[138:141], v[204:207], v[90:93]
	v_mfma_f32_16x16x32_bf16 v[78:81], v[130:133], v[212:215], v[78:81]
	v_mfma_f32_16x16x32_bf16 v[74:77], v[138:141], v[212:215], v[74:77]
	v_mfma_f32_16x16x32_bf16 v[126:129], v[134:137], v[182:185], v[126:129]
	v_mfma_f32_16x16x32_bf16 v[122:125], v[142:145], v[182:185], v[122:125]
	v_mfma_f32_16x16x32_bf16 v[110:113], v[134:137], v[200:203], v[110:113]
	v_mfma_f32_16x16x32_bf16 v[106:109], v[142:145], v[200:203], v[106:109]
	v_mfma_f32_16x16x32_bf16 v[94:97], v[134:137], v[208:211], v[94:97]
	v_mfma_f32_16x16x32_bf16 v[90:93], v[142:145], v[208:211], v[90:93]
	v_mfma_f32_16x16x32_bf16 v[78:81], v[134:137], v[216:219], v[78:81]
	v_mfma_f32_16x16x32_bf16 v[74:77], v[142:145], v[216:219], v[74:77]
	s_setprio 0
	s_setprio 1
	v_mfma_f32_16x16x32_bf16 v[118:121], v[146:149], v[178:181], v[118:121]
	v_mfma_f32_16x16x32_bf16 v[114:117], v[170:173], v[178:181], v[114:117]
	v_mfma_f32_16x16x32_bf16 v[102:105], v[146:149], v[196:199], v[102:105]
	v_mfma_f32_16x16x32_bf16 v[98:101], v[170:173], v[196:199], v[98:101]
	v_mfma_f32_16x16x32_bf16 v[86:89], v[146:149], v[204:207], v[86:89]
	v_mfma_f32_16x16x32_bf16 v[82:85], v[170:173], v[204:207], v[82:85]
	v_mfma_f32_16x16x32_bf16 v[70:73], v[146:149], v[212:215], v[70:73]
	v_mfma_f32_16x16x32_bf16 v[66:69], v[170:173], v[212:215], v[66:69]
	v_mfma_f32_16x16x32_bf16 v[118:121], v[150:153], v[182:185], v[118:121]
	v_mfma_f32_16x16x32_bf16 v[114:117], v[174:177], v[182:185], v[114:117]
	v_mfma_f32_16x16x32_bf16 v[102:105], v[150:153], v[200:203], v[102:105]
	v_mfma_f32_16x16x32_bf16 v[98:101], v[174:177], v[200:203], v[98:101]
	v_mfma_f32_16x16x32_bf16 v[86:89], v[150:153], v[208:211], v[86:89]
	v_mfma_f32_16x16x32_bf16 v[82:85], v[174:177], v[208:211], v[82:85]
	v_mfma_f32_16x16x32_bf16 v[70:73], v[150:153], v[216:219], v[70:73]
	v_mfma_f32_16x16x32_bf16 v[66:69], v[174:177], v[216:219], v[66:69]
	s_setprio 0
	s_barrier
; #define PG8_STAGE(bufoff, gbase, voff) do { _Pragma("unroll") for (int _i = 0; _i < 2; ++_i) \
;         __builtin_amdgcn_global_load_lds((const unsigned*)((const char*)(gbase) + (voff)[_i]), (PG8_LAS unsigned*)(lds + (bufoff) + ldsw + _i * 8192), 16, 0, 0); } while (0)
; #define PG8_LDA(dst, b, h) do { _Pragma("unroll") for (int m = 0; m < 4; ++m) _Pragma("unroll") for (int k = 0; k < 2; ++k) dst[m][k] = *(const PG8_LAS bf16x8*)(lds + PG8_SA(b, h) + aoff + m * 2048 + k * 1024); } while (0)
; #define PG8_MMA(ai, bj, At, Bt) do { __builtin_amdgcn_s_setprio(1); _Pragma("unroll") for (int m = 0; m < 4; ++m) _Pragma("unroll") for (int n = 0; n < 2; ++n) _Pragma("unroll") for (int k = 0; k < 2; ++k) \
;         acc[ai][bj][m][n] = __builtin_amdgcn_mfma_f32_16x16x32_bf16(Bt[n][k], At[m][k], acc[ai][bj][m][n], 0, 0, 0); __builtin_amdgcn_s_setprio(0); } while (0)
; #define PG8_WAIT_V(n) asm volatile("s_waitcnt vmcnt(" #n ")" ::: "memory")
; #define PG8_WAIT_L(n) asm volatile("s_waitcnt lgkmcnt(" #n ")" ::: "memory")
; #define PG8_BAR __builtin_amdgcn_s_barrier()
; #define PG8_SCHED __builtin_amdgcn_sched_barrier(0)
; template <class Epi, class Sched, bool ALIGN_EPI = false, bool SP2 = false>
; __device__ __forceinline__ void gemm_phase(PG8_LAS unsigned char* lds, const Gemm g, const Sched& S, const Epi& E) {
;     ...
;             PG8_LDA(At, 1, 1); PG8_STAGE(PG8_SB(1, 0), b3, voffB); PG8_STAGE(PG8_SB(1, 1), b3 + hstepB, voffB); PG8_STAGE(PG8_SA(1, 0), a3, voffA);
;             PG8_WAIT_V(8); PG8_WAIT_L(0); PG8_BAR; PG8_MMA(1, 0, At, B0); PG8_MMA(1, 1, At, B1); PG8_BAR; PG8_SCHED;
;     ...
;         if constexpr (ALIGN_EPI) { if (wr == 0) PG8_BAR; }
	s_add_i32 s34, s56, s39
	v_lshl_add_u64 v[220:221], v[220:221], 0, s[12:13]
	s_mov_b32 m0, s34
	ds_read_b128 v[178:181], v195 offset:49152
	ds_read_b128 v[182:185], v195 offset:50176
	ds_read_b128 v[196:199], v195 offset:51200
	ds_read_b128 v[200:203], v195 offset:52224
	ds_read_b128 v[204:207], v195 offset:53248
	ds_read_b128 v[208:211], v195 offset:54272
	ds_read_b128 v[212:215], v195 offset:55296
	ds_read_b128 v[216:219], v195 offset:56320
	global_load_lds_dwordx4 v[220:221], off
	s_add_i32 m0, s34, 0x2000
	s_add_u32 s30, s30, 0x200080
	v_lshl_add_u64 v[220:221], v[222:223], 0, s[12:13]
	s_addc_u32 s31, s31, 0
	s_add_i32 s34, s57, s39
	global_load_lds_dwordx4 v[220:221], off
	v_lshl_add_u64 v[220:221], s[30:31], 0, v[156:157]
	s_mov_b32 m0, s34
	s_nop 0
	global_load_lds_dwordx4 v[220:221], off
	v_lshl_add_u64 v[220:221], s[30:31], 0, v[160:161]
	s_add_i32 m0, s34, 0x2000
	s_nop 0
	global_load_lds_dwordx4 v[220:221], off
	v_lshl_add_u64 v[220:221], v[224:225], 0, s[12:13]
	s_mov_b32 m0, s44
	s_nop 0
	global_load_lds_dwordx4 v[220:221], off
	v_lshl_add_u64 v[220:221], v[226:227], 0, s[12:13]
	s_mov_b32 m0, s45
	s_nop 0
	global_load_lds_dwordx4 v[220:221], off
	s_waitcnt vmcnt(8)
	s_waitcnt lgkmcnt(0)
	s_barrier
	s_setprio 1
	v_mfma_f32_16x16x32_bf16 v[62:65], v[130:133], v[178:181], v[62:65]
	v_mfma_f32_16x16x32_bf16 v[58:61], v[138:141], v[178:181], v[58:61]
	v_mfma_f32_16x16x32_bf16 v[46:49], v[130:133], v[196:199], v[46:49]
	v_mfma_f32_16x16x32_bf16 v[42:45], v[138:141], v[196:199], v[42:45]
	v_mfma_f32_16x16x32_bf16 v[30:33], v[130:133], v[204:207], v[30:33]
	v_mfma_f32_16x16x32_bf16 v[26:29], v[138:141], v[204:207], v[26:29]
	v_mfma_f32_16x16x32_bf16 v[14:17], v[130:133], v[212:215], v[14:17]
	v_mfma_f32_16x16x32_bf16 v[10:13], v[138:141], v[212:215], v[10:13]
	v_mfma_f32_16x16x32_bf16 v[62:65], v[134:137], v[182:185], v[62:65]
	v_mfma_f32_16x16x32_bf16 v[58:61], v[142:145], v[182:185], v[58:61]
	v_mfma_f32_16x16x32_bf16 v[46:49], v[134:137], v[200:203], v[46:49]
	v_mfma_f32_16x16x32_bf16 v[42:45], v[142:145], v[200:203], v[42:45]
	v_mfma_f32_16x16x32_bf16 v[30:33], v[134:137], v[208:211], v[30:33]
	v_mfma_f32_16x16x32_bf16 v[26:29], v[142:145], v[208:211], v[26:29]
	v_mfma_f32_16x16x32_bf16 v[14:17], v[134:137], v[216:219], v[14:17]
	v_mfma_f32_16x16x32_bf16 v[10:13], v[142:145], v[216:219], v[10:13]
	s_setprio 0
	s_setprio 1
	v_mfma_f32_16x16x32_bf16 v[54:57], v[146:149], v[178:181], v[54:57]
	v_mfma_f32_16x16x32_bf16 v[50:53], v[170:173], v[178:181], v[50:53]
	v_mfma_f32_16x16x32_bf16 v[38:41], v[146:149], v[196:199], v[38:41]
	v_mfma_f32_16x16x32_bf16 v[34:37], v[170:173], v[196:199], v[34:37]
	v_mfma_f32_16x16x32_bf16 v[22:25], v[146:149], v[204:207], v[22:25]
	v_mfma_f32_16x16x32_bf16 v[18:21], v[170:173], v[204:207], v[18:21]
	v_mfma_f32_16x16x32_bf16 v[6:9], v[146:149], v[212:215], v[6:9]
	v_mfma_f32_16x16x32_bf16 v[2:5], v[170:173], v[212:215], v[2:5]
	v_mfma_f32_16x16x32_bf16 v[54:57], v[150:153], v[182:185], v[54:57]
	v_mfma_f32_16x16x32_bf16 v[50:53], v[174:177], v[182:185], v[50:53]
	v_mfma_f32_16x16x32_bf16 v[38:41], v[150:153], v[200:203], v[38:41]
	v_mfma_f32_16x16x32_bf16 v[34:37], v[174:177], v[200:203], v[34:37]
	v_mfma_f32_16x16x32_bf16 v[22:25], v[150:153], v[208:211], v[22:25]
	v_mfma_f32_16x16x32_bf16 v[18:21], v[174:177], v[208:211], v[18:21]
	v_mfma_f32_16x16x32_bf16 v[6:9], v[150:153], v[216:219], v[6:9]
	v_mfma_f32_16x16x32_bf16 v[2:5], v[174:177], v[216:219], v[2:5]
	s_setprio 0
	s_barrier
	s_add_i32 s55, s55, 2
	s_add_u32 s28, s28, 0x100
	s_addc_u32 s29, s29, 0
	s_add_u32 s53, s53, 0x100
	s_addc_u32 s54, s54, 0
	s_cmpk_gt_u32 s55, 0x7d
	s_cbranch_scc0 .LBB0_1127
	s_and_b64 vcc, exec, s[14:15]
	s_cbranch_vccz .LBB0_1130
	s_barrier

; #define PG8_STAGE(bufoff, gbase, voff) do { _Pragma("unroll") for (int _i = 0; _i < 2; ++_i) \
;         __builtin_amdgcn_global_load_lds((const unsigned*)((const char*)(gbase) + (voff)[_i]), (PG8_LAS unsigned*)(lds + (bufoff) + ldsw + _i * 8192), 16, 0, 0); } while (0)
; #define PG8_LDA(dst, b, h) do { _Pragma("unroll") for (int m = 0; m < 4; ++m) _Pragma("unroll") for (int k = 0; k < 2; ++k) dst[m][k] = *(const PG8_LAS bf16x8*)(lds + PG8_SA(b, h) + aoff + m * 2048 + k * 1024); } while (0)
; #define PG8_LDB(dst, b, h) do { _Pragma("unroll") for (int n = 0; n < 2; ++n) _Pragma("unroll") for (int k = 0; k < 2; ++k) dst[n][k] = *(const PG8_LAS bf16x8*)(lds + PG8_SB(b, h) + boff + n * 2048 + k * 1024); } while (0)
; #define PG8_MMA(ai, bj, At, Bt) do { __builtin_amdgcn_s_setprio(1); _Pragma("unroll") for (int m = 0; m < 4; ++m) _Pragma("unroll") for (int n = 0; n < 2; ++n) _Pragma("unroll") for (int k = 0; k < 2; ++k) \
;         acc[ai][bj][m][n] = __builtin_amdgcn_mfma_f32_16x16x32_bf16(Bt[n][k], At[m][k], acc[ai][bj][m][n], 0, 0, 0); __builtin_amdgcn_s_setprio(0); } while (0)
; #define PG8_WAIT_V(n) asm volatile("s_waitcnt vmcnt(" #n ")" ::: "memory")
; #define PG8_WAIT_L(n) asm volatile("s_waitcnt lgkmcnt(" #n ")" ::: "memory")
; #define PG8_BAR __builtin_amdgcn_s_barrier()
; template <class Epi, class Sched, bool ALIGN_EPI = false, bool SP2 = false>
; __device__ __forceinline__ void gemm_phase(PG8_LAS unsigned char* lds, const Gemm g, const Sched& S, const Epi& E) {
;     ...
;             const char* a1 = cA + (size_t)(t + 1) * kstep;
;             const char* a2 = last ? nA : cA + (size_t)(t + 2) * kstep; const char* b2 = last ? nB : cB + (size_t)(t + 2) * kstep;
;             const char* a3 = a2 + kstep; const char* b3 = b2 + kstep;
;             if (last && has_next) S.a_ready(nxt);
;             if constexpr (SP2) {
;             PG8_LDB(B0, 0, 0); PG8_LDB(B1, 0, 1); PG8_SCHED; PG8_LDA(At, 0, 0); PG8_STAGE(PG8_SA(1, 1), a1 + hstepA, voffA);
;             PG8_WAIT_V(8); PG8_WAIT_L(0); PG8_BAR; PG8_MMA(0, 0, At, B0); PG8_MMA(0, 1, At, B1); PG8_BAR; PG8_SCHED;
;             PG8_LDA(At, 0, 1); PG8_STAGE(PG8_SB(0, 0), b2, voffB); PG8_STAGE(PG8_SB(0, 1), b2 + hstepB, voffB); PG8_STAGE(PG8_SA(0, 0), a2, voffA);
;             PG8_WAIT_V(8); PG8_WAIT_L(0); PG8_BAR; PG8_MMA(1, 0, At, B0); PG8_MMA(1, 1, At, B1); PG8_BAR; PG8_SCHED;
.LBB0_1810:
	ds_read_b128 v[130:133], v191
	ds_read_b128 v[134:137], v191 offset:1024
	ds_read_b128 v[138:141], v191 offset:2048
	ds_read_b128 v[142:145], v191 offset:3072
	ds_read_b128 v[146:149], v193
	ds_read_b128 v[150:153], v193 offset:1024
	ds_read_b128 v[170:173], v193 offset:2048
	ds_read_b128 v[174:177], v193 offset:3072
	s_add_u32 s30, s28, 0xfff00080
	s_addc_u32 s31, s29, -1
	s_cmp_eq_u32 s55, 60
	s_cselect_b32 s35, s19, s31
	s_cselect_b32 s34, s25, s30
	s_cselect_b32 s31, s17, s54
	s_cselect_b32 s30, s52, s53
	v_lshl_add_u64 v[220:221], s[28:29], 0, v[162:163]
	s_add_i32 m0, s27, 0xc000
	ds_read_b128 v[178:181], v195
	ds_read_b128 v[182:185], v195 offset:1024
	ds_read_b128 v[196:199], v195 offset:2048
	ds_read_b128 v[200:203], v195 offset:3072
	ds_read_b128 v[204:207], v195 offset:4096
	ds_read_b128 v[208:211], v195 offset:5120
	ds_read_b128 v[212:215], v195 offset:6144
	ds_read_b128 v[216:219], v195 offset:7168
	global_load_lds_dwordx4 v[220:221], off
	v_lshl_add_u64 v[220:221], s[28:29], 0, v[164:165]
	s_add_i32 m0, s27, 0xe000
	s_nop 0
	global_load_lds_dwordx4 v[220:221], off
	s_waitcnt vmcnt(8)
	s_waitcnt lgkmcnt(0)
	s_barrier
	s_setprio 1
	v_mfma_f32_16x16x32_bf16 v[126:129], v[130:133], v[178:181], v[126:129]
	v_mfma_f32_16x16x32_bf16 v[122:125], v[138:141], v[178:181], v[122:125]
	v_mfma_f32_16x16x32_bf16 v[110:113], v[130:133], v[196:199], v[110:113]
	v_mfma_f32_16x16x32_bf16 v[106:109], v[138:141], v[196:199], v[106:109]
	v_mfma_f32_16x16x32_bf16 v[94:97], v[130:133], v[204:207], v[94:97]
	v_mfma_f32_16x16x32_bf16 v[90:93], v[138:141], v[204:207], v[90:93]
	v_mfma_f32_16x16x32_bf16 v[78:81], v[130:133], v[212:215], v[78:81]
	v_mfma_f32_16x16x32_bf16 v[74:77], v[138:141], v[212:215], v[74:77]
	v_mfma_f32_16x16x32_bf16 v[126:129], v[134:137], v[182:185], v[126:129]
	v_mfma_f32_16x16x32_bf16 v[122:125], v[142:145], v[182:185], v[122:125]
	v_mfma_f32_16x16x32_bf16 v[110:113], v[134:137], v[200:203], v[110:113]
	v_mfma_f32_16x16x32_bf16 v[106:109], v[142:145], v[200:203], v[106:109]
	v_mfma_f32_16x16x32_bf16 v[94:97], v[134:137], v[208:211], v[94:97]
	v_mfma_f32_16x16x32_bf16 v[90:93], v[142:145], v[208:211], v[90:93]
	v_mfma_f32_16x16x32_bf16 v[78:81], v[134:137], v[216:219], v[78:81]
	v_mfma_f32_16x16x32_bf16 v[74:77], v[142:145], v[216:219], v[74:77]
	s_setprio 0
	s_setprio 1
	v_mfma_f32_16x16x32_bf16 v[118:121], v[146:149], v[178:181], v[118:121]
	v_mfma_f32_16x16x32_bf16 v[114:117], v[170:173], v[178:181], v[114:117]
	v_mfma_f32_16x16x32_bf16 v[102:105], v[146:149], v[196:199], v[102:105]
	v_mfma_f32_16x16x32_bf16 v[98:101], v[170:173], v[196:199], v[98:101]
	v_mfma_f32_16x16x32_bf16 v[86:89], v[146:149], v[204:207], v[86:89]
	v_mfma_f32_16x16x32_bf16 v[82:85], v[170:173], v[204:207], v[82:85]
	v_mfma_f32_16x16x32_bf16 v[70:73], v[146:149], v[212:215], v[70:73]
	v_mfma_f32_16x16x32_bf16 v[66:69], v[170:173], v[212:215], v[66:69]
	v_mfma_f32_16x16x32_bf16 v[118:121], v[150:153], v[182:185], v[118:121]
	v_mfma_f32_16x16x32_bf16 v[114:117], v[174:177], v[182:185], v[114:117]
	v_mfma_f32_16x16x32_bf16 v[102:105], v[150:153], v[200:203], v[102:105]
	v_mfma_f32_16x16x32_bf16 v[98:101], v[174:177], v[200:203], v[98:101]
	v_mfma_f32_16x16x32_bf16 v[86:89], v[150:153], v[208:211], v[86:89]
	v_mfma_f32_16x16x32_bf16 v[82:85], v[174:177], v[208:211], v[82:85]
	v_mfma_f32_16x16x32_bf16 v[70:73], v[150:153], v[216:219], v[70:73]
	v_mfma_f32_16x16x32_bf16 v[66:69], v[174:177], v[216:219], v[66:69]
	s_setprio 0
	s_barrier
	s_add_i32 s56, s48, s39
	v_lshl_add_u64 v[220:221], s[30:31], 0, v[156:157]
	s_mov_b32 m0, s56
	ds_read_b128 v[178:181], v195 offset:16384
	ds_read_b128 v[182:185], v195 offset:17408
	ds_read_b128 v[196:199], v195 offset:18432
	ds_read_b128 v[200:203], v195 offset:19456
	ds_read_b128 v[204:207], v195 offset:20480
	ds_read_b128 v[208:211], v195 offset:21504
	ds_read_b128 v[212:215], v195 offset:22528
	ds_read_b128 v[216:219], v195 offset:23552
	global_load_lds_dwordx4 v[220:221], off
	s_add_i32 m0, s56, 0x2000
	s_add_u32 s56, s30, 0x100000
	v_lshl_add_u64 v[222:223], s[30:31], 0, v[160:161]
	s_addc_u32 s57, s31, 0
	s_add_i32 s58, s49, s39
	global_load_lds_dwordx4 v[222:223], off
	v_lshl_add_u64 v[224:225], s[56:57], 0, v[156:157]
	s_mov_b32 m0, s58
	v_lshl_add_u64 v[226:227], s[34:35], 0, v[158:159]
	global_load_lds_dwordx4 v[224:225], off
	v_lshl_add_u64 v[224:225], s[56:57], 0, v[160:161]
	s_add_i32 m0, s58, 0x2000
	s_nop 0
	global_load_lds_dwordx4 v[224:225], off
	v_lshl_add_u64 v[224:225], s[34:35], 0, v[154:155]
	s_mov_b32 m0, s27
	s_nop 0
	global_load_lds_dwordx4 v[224:225], off
	s_mov_b32 m0, s40
	s_nop 0
	global_load_lds_dwordx4 v[226:227], off
	s_waitcnt vmcnt(8)
	s_waitcnt lgkmcnt(0)
	s_barrier
; #define PG8_STAGE(bufoff, gbase, voff) do { _Pragma("unroll") for (int _i = 0; _i < 2; ++_i) \
;         __builtin_amdgcn_global_load_lds((const unsigned*)((const char*)(gbase) + (voff)[_i]), (PG8_LAS unsigned*)(lds + (bufoff) + ldsw + _i * 8192), 16, 0, 0); } while (0)
; #define PG8_LDA(dst, b, h) do { _Pragma("unroll") for (int m = 0; m < 4; ++m) _Pragma("unroll") for (int k = 0; k < 2; ++k) dst[m][k] = *(const PG8_LAS bf16x8*)(lds + PG8_SA(b, h) + aoff + m * 2048 + k * 1024); } while (0)
; #define PG8_LDB(dst, b, h) do { _Pragma("unroll") for (int n = 0; n < 2; ++n) _Pragma("unroll") for (int k = 0; k < 2; ++k) dst[n][k] = *(const PG8_LAS bf16x8*)(lds + PG8_SB(b, h) + boff + n * 2048 + k * 1024); } while (0)
; #define PG8_MMA(ai, bj, At, Bt) do { __builtin_amdgcn_s_setprio(1); _Pragma("unroll") for (int m = 0; m < 4; ++m) _Pragma("unroll") for (int n = 0; n < 2; ++n) _Pragma("unroll") for (int k = 0; k < 2; ++k) \
;         acc[ai][bj][m][n] = __builtin_amdgcn_mfma_f32_16x16x32_bf16(Bt[n][k], At[m][k], acc[ai][bj][m][n], 0, 0, 0); __builtin_amdgcn_s_setprio(0); } while (0)
; #define PG8_WAIT_V(n) asm volatile("s_waitcnt vmcnt(" #n ")" ::: "memory")
; #define PG8_WAIT_L(n) asm volatile("s_waitcnt lgkmcnt(" #n ")" ::: "memory")
; #define PG8_BAR __builtin_amdgcn_s_barrier()
; #define PG8_SCHED __builtin_amdgcn_sched_barrier(0)
; template <class Epi, class Sched, bool ALIGN_EPI = false, bool SP2 = false>
; __device__ __forceinline__ void gemm_phase(PG8_LAS unsigned char* lds, const Gemm g, const Sched& S, const Epi& E) {
;     ...
;             PG8_WAIT_V(8); PG8_WAIT_L(0); PG8_BAR; PG8_MMA(1, 0, At, B0); PG8_MMA(1, 1, At, B1); PG8_BAR; PG8_SCHED;
;             PG8_LDB(B0, 1, 0); PG8_LDB(B1, 1, 1); PG8_SCHED; PG8_LDA(At, 1, 0); PG8_STAGE(PG8_SA(0, 1), a2 + hstepA, voffA);
;             PG8_WAIT_V(8); PG8_WAIT_L(0); PG8_BAR; PG8_MMA(0, 0, At, B0); PG8_MMA(0, 1, At, B1); PG8_BAR; PG8_SCHED;
	s_setprio 1
	v_mfma_f32_16x16x32_bf16 v[62:65], v[130:133], v[178:181], v[62:65]
	v_mfma_f32_16x16x32_bf16 v[58:61], v[138:141], v[178:181], v[58:61]
	v_mfma_f32_16x16x32_bf16 v[46:49], v[130:133], v[196:199], v[46:49]
	v_mfma_f32_16x16x32_bf16 v[42:45], v[138:141], v[196:199], v[42:45]
	v_mfma_f32_16x16x32_bf16 v[30:33], v[130:133], v[204:207], v[30:33]
	v_mfma_f32_16x16x32_bf16 v[26:29], v[138:141], v[204:207], v[26:29]
	v_mfma_f32_16x16x32_bf16 v[14:17], v[130:133], v[212:215], v[14:17]
	v_mfma_f32_16x16x32_bf16 v[10:13], v[138:141], v[212:215], v[10:13]
	v_mfma_f32_16x16x32_bf16 v[62:65], v[134:137], v[182:185], v[62:65]
	v_mfma_f32_16x16x32_bf16 v[58:61], v[142:145], v[182:185], v[58:61]
	v_mfma_f32_16x16x32_bf16 v[46:49], v[134:137], v[200:203], v[46:49]
	v_mfma_f32_16x16x32_bf16 v[42:45], v[142:145], v[200:203], v[42:45]
	v_mfma_f32_16x16x32_bf16 v[30:33], v[134:137], v[208:211], v[30:33]
	v_mfma_f32_16x16x32_bf16 v[26:29], v[142:145], v[208:211], v[26:29]
	v_mfma_f32_16x16x32_bf16 v[14:17], v[134:137], v[216:219], v[14:17]
	v_mfma_f32_16x16x32_bf16 v[10:13], v[142:145], v[216:219], v[10:13]
	s_setprio 0
	s_setprio 1
	v_mfma_f32_16x16x32_bf16 v[54:57], v[146:149], v[178:181], v[54:57]
	v_mfma_f32_16x16x32_bf16 v[50:53], v[170:173], v[178:181], v[50:53]
	v_mfma_f32_16x16x32_bf16 v[38:41], v[146:149], v[196:199], v[38:41]
	v_mfma_f32_16x16x32_bf16 v[34:37], v[170:173], v[196:199], v[34:37]
	v_mfma_f32_16x16x32_bf16 v[22:25], v[146:149], v[204:207], v[22:25]
	v_mfma_f32_16x16x32_bf16 v[18:21], v[170:173], v[204:207], v[18:21]
	v_mfma_f32_16x16x32_bf16 v[6:9], v[146:149], v[212:215], v[6:9]
	v_mfma_f32_16x16x32_bf16 v[2:5], v[170:173], v[212:215], v[2:5]
	v_mfma_f32_16x16x32_bf16 v[54:57], v[150:153], v[182:185], v[54:57]
	v_mfma_f32_16x16x32_bf16 v[50:53], v[174:177], v[182:185], v[50:53]
	v_mfma_f32_16x16x32_bf16 v[38:41], v[150:153], v[200:203], v[38:41]
	v_mfma_f32_16x16x32_bf16 v[34:37], v[174:177], v[200:203], v[34:37]
	v_mfma_f32_16x16x32_bf16 v[22:25], v[150:153], v[208:211], v[22:25]
	v_mfma_f32_16x16x32_bf16 v[18:21], v[174:177], v[208:211], v[18:21]
	v_mfma_f32_16x16x32_bf16 v[6:9], v[150:153], v[216:219], v[6:9]
	v_mfma_f32_16x16x32_bf16 v[2:5], v[174:177], v[216:219], v[2:5]
	s_setprio 0
	s_barrier
	s_add_i32 s56, 0, 0x18000
	s_add_i32 s57, 0, 0x1c000
	v_add_u32_e32 v142, s56, v187
	v_add_u32_e32 v174, s57, v187
	ds_read_b128 v[130:133], v142
	ds_read_b128 v[134:137], v142 offset:1024
	ds_read_b128 v[138:141], v142 offset:2048
	ds_read_b128 v[142:145], v142 offset:3072
	ds_read_b128 v[146:149], v174
	ds_read_b128 v[150:153], v174 offset:1024
	ds_read_b128 v[170:173], v174 offset:2048
	ds_read_b128 v[174:177], v174 offset:3072
	s_add_u32 s34, s34, 0x100000
	s_addc_u32 s35, s35, 0
	s_mov_b32 m0, s41
	v_lshl_add_u64 v[228:229], s[34:35], 0, v[154:155]
	ds_read_b128 v[178:181], v195 offset:32768
	ds_read_b128 v[182:185], v195 offset:33792
	ds_read_b128 v[196:199], v195 offset:34816
	ds_read_b128 v[200:203], v195 offset:35840
	ds_read_b128 v[204:207], v195 offset:36864
	ds_read_b128 v[208:211], v195 offset:37888
	ds_read_b128 v[212:215], v195 offset:38912
	ds_read_b128 v[216:219], v195 offset:39936
	global_load_lds_dwordx4 v[228:229], off
	v_lshl_add_u64 v[228:229], s[34:35], 0, v[158:159]
	s_mov_b32 m0, s42
	s_nop 0
	global_load_lds_dwordx4 v[228:229], off
	s_waitcnt vmcnt(8)
	s_waitcnt lgkmcnt(0)
	s_barrier
	s_setprio 1
	v_mfma_f32_16x16x32_bf16 v[126:129], v[130:133], v[178:181], v[126:129]
	v_mfma_f32_16x16x32_bf16 v[122:125], v[138:141], v[178:181], v[122:125]
	v_mfma_f32_16x16x32_bf16 v[110:113], v[130:133], v[196:199], v[110:113]
	v_mfma_f32_16x16x32_bf16 v[106:109], v[138:141], v[196:199], v[106:109]
	v_mfma_f32_16x16x32_bf16 v[94:97], v[130:133], v[204:207], v[94:97]
	v_mfma_f32_16x16x32_bf16 v[90:93], v[138:141], v[204:207], v[90:93]
	v_mfma_f32_16x16x32_bf16 v[78:81], v[130:133], v[212:215], v[78:81]
	v_mfma_f32_16x16x32_bf16 v[74:77], v[138:141], v[212:215], v[74:77]
	v_mfma_f32_16x16x32_bf16 v[126:129], v[134:137], v[182:185], v[126:129]
	v_mfma_f32_16x16x32_bf16 v[122:125], v[142:145], v[182:185], v[122:125]
	v_mfma_f32_16x16x32_bf16 v[110:113], v[134:137], v[200:203], v[110:113]
	v_mfma_f32_16x16x32_bf16 v[106:109], v[142:145], v[200:203], v[106:109]
	v_mfma_f32_16x16x32_bf16 v[94:97], v[134:137], v[208:211], v[94:97]
	v_mfma_f32_16x16x32_bf16 v[90:93], v[142:145], v[208:211], v[90:93]
	v_mfma_f32_16x16x32_bf16 v[78:81], v[134:137], v[216:219], v[78:81]
	v_mfma_f32_16x16x32_bf16 v[74:77], v[142:145], v[216:219], v[74:77]
	s_setprio 0
	s_setprio 1
	v_mfma_f32_16x16x32_bf16 v[118:121], v[146:149], v[178:181], v[118:121]
	v_mfma_f32_16x16x32_bf16 v[114:117], v[170:173], v[178:181], v[114:117]
	v_mfma_f32_16x16x32_bf16 v[102:105], v[146:149], v[196:199], v[102:105]
	v_mfma_f32_16x16x32_bf16 v[98:101], v[170:173], v[196:199], v[98:101]
	v_mfma_f32_16x16x32_bf16 v[86:89], v[146:149], v[204:207], v[86:89]
	v_mfma_f32_16x16x32_bf16 v[82:85], v[170:173], v[204:207], v[82:85]
	v_mfma_f32_16x16x32_bf16 v[70:73], v[146:149], v[212:215], v[70:73]
	v_mfma_f32_16x16x32_bf16 v[66:69], v[170:173], v[212:215], v[66:69]
	v_mfma_f32_16x16x32_bf16 v[118:121], v[150:153], v[182:185], v[118:121]
	v_mfma_f32_16x16x32_bf16 v[114:117], v[174:177], v[182:185], v[114:117]
	v_mfma_f32_16x16x32_bf16 v[102:105], v[150:153], v[200:203], v[102:105]
	v_mfma_f32_16x16x32_bf16 v[98:101], v[174:177], v[200:203], v[98:101]
	v_mfma_f32_16x16x32_bf16 v[86:89], v[150:153], v[208:211], v[86:89]
	v_mfma_f32_16x16x32_bf16 v[82:85], v[174:177], v[208:211], v[82:85]
	v_mfma_f32_16x16x32_bf16 v[70:73], v[150:153], v[216:219], v[70:73]
	v_mfma_f32_16x16x32_bf16 v[66:69], v[174:177], v[216:219], v[66:69]
	s_setprio 0
	s_barrier
; #define PG8_STAGE(bufoff, gbase, voff) do { _Pragma("unroll") for (int _i = 0; _i < 2; ++_i) \
;         __builtin_amdgcn_global_load_lds((const unsigned*)((const char*)(gbase) + (voff)[_i]), (PG8_LAS unsigned*)(lds + (bufoff) + ldsw + _i * 8192), 16, 0, 0); } while (0)
; #define PG8_LDA(dst, b, h) do { _Pragma("unroll") for (int m = 0; m < 4; ++m) _Pragma("unroll") for (int k = 0; k < 2; ++k) dst[m][k] = *(const PG8_LAS bf16x8*)(lds + PG8_SA(b, h) + aoff + m * 2048 + k * 1024); } while (0)
; #define PG8_MMA(ai, bj, At, Bt) do { __builtin_amdgcn_s_setprio(1); _Pragma("unroll") for (int m = 0; m < 4; ++m) _Pragma("unroll") for (int n = 0; n < 2; ++n) _Pragma("unroll") for (int k = 0; k < 2; ++k) \
;         acc[ai][bj][m][n] = __builtin_amdgcn_mfma_f32_16x16x32_bf16(Bt[n][k], At[m][k], acc[ai][bj][m][n], 0, 0, 0); __builtin_amdgcn_s_setprio(0); } while (0)
; #define PG8_WAIT_V(n) asm volatile("s_waitcnt vmcnt(" #n ")" ::: "memory")
; #define PG8_WAIT_L(n) asm volatile("s_waitcnt lgkmcnt(" #n ")" ::: "memory")
; #define PG8_BAR __builtin_amdgcn_s_barrier()
; #define PG8_SCHED __builtin_amdgcn_sched_barrier(0)
; template <class Epi, class Sched, bool ALIGN_EPI = false, bool SP2 = false>
; __device__ __forceinline__ void gemm_phase(PG8_LAS unsigned char* lds, const Gemm g, const Sched& S, const Epi& E) {
;     ...
;             PG8_LDA(At, 1, 1); PG8_STAGE(PG8_SB(1, 0), b3, voffB); PG8_STAGE(PG8_SB(1, 1), b3 + hstepB, voffB); PG8_STAGE(PG8_SA(1, 0), a3, voffA);
;             PG8_WAIT_V(8); PG8_WAIT_L(0); PG8_BAR; PG8_MMA(1, 0, At, B0); PG8_MMA(1, 1, At, B1); PG8_BAR; PG8_SCHED;
;     ...
;         if constexpr (ALIGN_EPI) { if (wr == 0) PG8_BAR; }
	s_add_i32 s34, s56, s39
	v_lshl_add_u64 v[220:221], v[220:221], 0, s[12:13]
	s_mov_b32 m0, s34
	ds_read_b128 v[178:181], v195 offset:49152
	ds_read_b128 v[182:185], v195 offset:50176
	ds_read_b128 v[196:199], v195 offset:51200
	ds_read_b128 v[200:203], v195 offset:52224
	ds_read_b128 v[204:207], v195 offset:53248
	ds_read_b128 v[208:211], v195 offset:54272
	ds_read_b128 v[212:215], v195 offset:55296
	ds_read_b128 v[216:219], v195 offset:56320
	global_load_lds_dwordx4 v[220:221], off
	s_add_i32 m0, s34, 0x2000
	s_add_u32 s30, s30, 0x100080
	v_lshl_add_u64 v[220:221], v[222:223], 0, s[12:13]
	s_addc_u32 s31, s31, 0
	s_add_i32 s34, s57, s39
	global_load_lds_dwordx4 v[220:221], off
	v_lshl_add_u64 v[220:221], s[30:31], 0, v[156:157]
	s_mov_b32 m0, s34
	s_nop 0
	global_load_lds_dwordx4 v[220:221], off
	v_lshl_add_u64 v[220:221], s[30:31], 0, v[160:161]
	s_add_i32 m0, s34, 0x2000
	s_nop 0
	global_load_lds_dwordx4 v[220:221], off
	v_lshl_add_u64 v[220:221], v[224:225], 0, s[12:13]
	s_mov_b32 m0, s44
	s_nop 0
	global_load_lds_dwordx4 v[220:221], off
	v_lshl_add_u64 v[220:221], v[226:227], 0, s[12:13]
	s_mov_b32 m0, s45
	s_nop 0
	global_load_lds_dwordx4 v[220:221], off
	s_waitcnt vmcnt(8)
	s_waitcnt lgkmcnt(0)
	s_barrier
	s_setprio 1
	v_mfma_f32_16x16x32_bf16 v[62:65], v[130:133], v[178:181], v[62:65]
	v_mfma_f32_16x16x32_bf16 v[58:61], v[138:141], v[178:181], v[58:61]
	v_mfma_f32_16x16x32_bf16 v[46:49], v[130:133], v[196:199], v[46:49]
	v_mfma_f32_16x16x32_bf16 v[42:45], v[138:141], v[196:199], v[42:45]
	v_mfma_f32_16x16x32_bf16 v[30:33], v[130:133], v[204:207], v[30:33]
	v_mfma_f32_16x16x32_bf16 v[26:29], v[138:141], v[204:207], v[26:29]
	v_mfma_f32_16x16x32_bf16 v[14:17], v[130:133], v[212:215], v[14:17]
	v_mfma_f32_16x16x32_bf16 v[10:13], v[138:141], v[212:215], v[10:13]
	v_mfma_f32_16x16x32_bf16 v[62:65], v[134:137], v[182:185], v[62:65]
	v_mfma_f32_16x16x32_bf16 v[58:61], v[142:145], v[182:185], v[58:61]
	v_mfma_f32_16x16x32_bf16 v[46:49], v[134:137], v[200:203], v[46:49]
	v_mfma_f32_16x16x32_bf16 v[42:45], v[142:145], v[200:203], v[42:45]
	v_mfma_f32_16x16x32_bf16 v[30:33], v[134:137], v[208:211], v[30:33]
	v_mfma_f32_16x16x32_bf16 v[26:29], v[142:145], v[208:211], v[26:29]
	v_mfma_f32_16x16x32_bf16 v[14:17], v[134:137], v[216:219], v[14:17]
	v_mfma_f32_16x16x32_bf16 v[10:13], v[142:145], v[216:219], v[10:13]
	s_setprio 0
	s_setprio 1
	v_mfma_f32_16x16x32_bf16 v[54:57], v[146:149], v[178:181], v[54:57]
	v_mfma_f32_16x16x32_bf16 v[50:53], v[170:173], v[178:181], v[50:53]
	v_mfma_f32_16x16x32_bf16 v[38:41], v[146:149], v[196:199], v[38:41]
	v_mfma_f32_16x16x32_bf16 v[34:37], v[170:173], v[196:199], v[34:37]
	v_mfma_f32_16x16x32_bf16 v[22:25], v[146:149], v[204:207], v[22:25]
	v_mfma_f32_16x16x32_bf16 v[18:21], v[170:173], v[204:207], v[18:21]
	v_mfma_f32_16x16x32_bf16 v[6:9], v[146:149], v[212:215], v[6:9]
	v_mfma_f32_16x16x32_bf16 v[2:5], v[170:173], v[212:215], v[2:5]
	v_mfma_f32_16x16x32_bf16 v[54:57], v[150:153], v[182:185], v[54:57]
	v_mfma_f32_16x16x32_bf16 v[50:53], v[174:177], v[182:185], v[50:53]
	v_mfma_f32_16x16x32_bf16 v[38:41], v[150:153], v[200:203], v[38:41]
	v_mfma_f32_16x16x32_bf16 v[34:37], v[174:177], v[200:203], v[34:37]
	v_mfma_f32_16x16x32_bf16 v[22:25], v[150:153], v[208:211], v[22:25]
	v_mfma_f32_16x16x32_bf16 v[18:21], v[174:177], v[208:211], v[18:21]
	v_mfma_f32_16x16x32_bf16 v[6:9], v[150:153], v[216:219], v[6:9]
	v_mfma_f32_16x16x32_bf16 v[2:5], v[174:177], v[216:219], v[2:5]
	s_setprio 0
	s_barrier
	s_add_i32 s55, s55, 2
	s_add_u32 s28, s28, 0x100
	s_addc_u32 s29, s29, 0
	s_add_u32 s53, s53, 0x100
	s_addc_u32 s54, s54, 0
	s_cmp_gt_u32 s55, 61
	s_cbranch_scc0 .LBB0_1810
	s_and_b64 vcc, exec, s[14:15]
	s_cbranch_vccz .LBB0_1813
	s_barrier

; #define PG8_STAGE(bufoff, gbase, voff) do { _Pragma("unroll") for (int _i = 0; _i < 2; ++_i) \
;         __builtin_amdgcn_global_load_lds((const unsigned*)((const char*)(gbase) + (voff)[_i]), (PG8_LAS unsigned*)(lds + (bufoff) + ldsw + _i * 8192), 16, 0, 0); } while (0)
; #define PG8_LDA(dst, b, h) do { _Pragma("unroll") for (int m = 0; m < 4; ++m) _Pragma("unroll") for (int k = 0; k < 2; ++k) dst[m][k] = *(const PG8_LAS bf16x8*)(lds + PG8_SA(b, h) + aoff + m * 2048 + k * 1024); } while (0)
; #define PG8_LDB(dst, b, h) do { _Pragma("unroll") for (int n = 0; n < 2; ++n) _Pragma("unroll") for (int k = 0; k < 2; ++k) dst[n][k] = *(const PG8_LAS bf16x8*)(lds + PG8_SB(b, h) + boff + n * 2048 + k * 1024); } while (0)
; #define PG8_MMA(ai, bj, At, Bt) do { __builtin_amdgcn_s_setprio(1); _Pragma("unroll") for (int m = 0; m < 4; ++m) _Pragma("unroll") for (int n = 0; n < 2; ++n) _Pragma("unroll") for (int k = 0; k < 2; ++k) \
;         acc[ai][bj][m][n] = __builtin_amdgcn_mfma_f32_16x16x32_bf16(Bt[n][k], At[m][k], acc[ai][bj][m][n], 0, 0, 0); __builtin_amdgcn_s_setprio(0); } while (0)
; #define PG8_WAIT_V(n) asm volatile("s_waitcnt vmcnt(" #n ")" ::: "memory")
; #define PG8_WAIT_L(n) asm volatile("s_waitcnt lgkmcnt(" #n ")" ::: "memory")
; #define PG8_BAR __builtin_amdgcn_s_barrier()
; template <class Epi, class Sched, bool ALIGN_EPI = false, bool SP2 = false>
; __device__ __forceinline__ void gemm_phase(PG8_LAS unsigned char* lds, const Gemm g, const Sched& S, const Epi& E) {
;     ...
;             const char* a1 = cA + (size_t)(t + 1) * kstep;
;             const char* a2 = last ? nA : cA + (size_t)(t + 2) * kstep; const char* b2 = last ? nB : cB + (size_t)(t + 2) * kstep;
;             const char* a3 = a2 + kstep; const char* b3 = b2 + kstep;
;             if (last && has_next) S.a_ready(nxt);
;             if constexpr (SP2) {
;             PG8_LDB(B0, 0, 0); PG8_LDB(B1, 0, 1); PG8_SCHED; PG8_LDA(At, 0, 0); PG8_STAGE(PG8_SA(1, 1), a1 + hstepA, voffA);
;             PG8_WAIT_V(8); PG8_WAIT_L(0); PG8_BAR; PG8_MMA(0, 0, At, B0); PG8_MMA(0, 1, At, B1); PG8_BAR; PG8_SCHED;
;             PG8_LDA(At, 0, 1); PG8_STAGE(PG8_SB(0, 0), b2, voffB); PG8_STAGE(PG8_SB(0, 1), b2 + hstepB, voffB); PG8_STAGE(PG8_SA(0, 0), a2, voffA);
;             PG8_WAIT_V(8); PG8_WAIT_L(0); PG8_BAR; PG8_MMA(1, 0, At, B0); PG8_MMA(1, 1, At, B1); PG8_BAR; PG8_SCHED;
.LBB0_1895:
	ds_read_b128 v[148:151], v160
	ds_read_b128 v[152:155], v160 offset:1024
	ds_read_b128 v[164:167], v160 offset:2048
	ds_read_b128 v[168:171], v160 offset:3072
	ds_read_b128 v[172:175], v161
	ds_read_b128 v[176:179], v161 offset:1024
	ds_read_b128 v[180:183], v161 offset:2048
	ds_read_b128 v[196:199], v161 offset:3072
	s_add_u32 s30, s28, 0xfff00080
	s_addc_u32 s31, s29, -1
	s_cmp_eq_u32 s57, 60
	s_cselect_b32 s35, s15, s31
	s_cselect_b32 s34, s53, s30
	s_cselect_b32 s31, s13, s56
	s_cselect_b32 s30, s54, s55
	v_lshl_add_u64 v[184:185], s[28:29], 0, v[140:141]
	s_add_i32 m0, s40, 0xc000
	ds_read_b128 v[200:203], v162
	ds_read_b128 v[204:207], v162 offset:1024
	ds_read_b128 v[208:211], v162 offset:2048
	ds_read_b128 v[212:215], v162 offset:3072
	ds_read_b128 v[216:219], v162 offset:4096
	ds_read_b128 v[220:223], v162 offset:5120
	ds_read_b128 v[224:227], v162 offset:6144
	ds_read_b128 v[228:231], v162 offset:7168
	global_load_lds_dwordx4 v[184:185], off
	v_lshl_add_u64 v[184:185], s[28:29], 0, v[142:143]
	s_add_i32 m0, s40, 0xe000
	s_nop 0
	global_load_lds_dwordx4 v[184:185], off
	s_waitcnt vmcnt(8)
	s_waitcnt lgkmcnt(0)
	s_barrier
	s_setprio 1
	v_mfma_f32_16x16x32_bf16 v[126:129], v[148:151], v[200:203], v[126:129]
	v_mfma_f32_16x16x32_bf16 v[122:125], v[164:167], v[200:203], v[122:125]
	v_mfma_f32_16x16x32_bf16 v[114:117], v[148:151], v[208:211], v[114:117]
	v_mfma_f32_16x16x32_bf16 v[106:109], v[164:167], v[208:211], v[106:109]
	v_mfma_f32_16x16x32_bf16 v[98:101], v[148:151], v[216:219], v[98:101]
	v_mfma_f32_16x16x32_bf16 v[90:93], v[164:167], v[216:219], v[90:93]
	v_mfma_f32_16x16x32_bf16 v[82:85], v[148:151], v[224:227], v[82:85]
	v_mfma_f32_16x16x32_bf16 v[74:77], v[164:167], v[224:227], v[74:77]
	v_mfma_f32_16x16x32_bf16 v[126:129], v[152:155], v[204:207], v[126:129]
	v_mfma_f32_16x16x32_bf16 v[122:125], v[168:171], v[204:207], v[122:125]
	v_mfma_f32_16x16x32_bf16 v[114:117], v[152:155], v[212:215], v[114:117]
	v_mfma_f32_16x16x32_bf16 v[106:109], v[168:171], v[212:215], v[106:109]
	v_mfma_f32_16x16x32_bf16 v[98:101], v[152:155], v[220:223], v[98:101]
	v_mfma_f32_16x16x32_bf16 v[90:93], v[168:171], v[220:223], v[90:93]
	v_mfma_f32_16x16x32_bf16 v[82:85], v[152:155], v[228:231], v[82:85]
	v_mfma_f32_16x16x32_bf16 v[74:77], v[168:171], v[228:231], v[74:77]
	s_setprio 0
	s_setprio 1
	v_mfma_f32_16x16x32_bf16 v[118:121], v[172:175], v[200:203], v[118:121]
	v_mfma_f32_16x16x32_bf16 v[110:113], v[180:183], v[200:203], v[110:113]
	v_mfma_f32_16x16x32_bf16 v[102:105], v[172:175], v[208:211], v[102:105]
	v_mfma_f32_16x16x32_bf16 v[94:97], v[180:183], v[208:211], v[94:97]
	v_mfma_f32_16x16x32_bf16 v[86:89], v[172:175], v[216:219], v[86:89]
	v_mfma_f32_16x16x32_bf16 v[78:81], v[180:183], v[216:219], v[78:81]
	v_mfma_f32_16x16x32_bf16 v[70:73], v[172:175], v[224:227], v[70:73]
	v_mfma_f32_16x16x32_bf16 v[66:69], v[180:183], v[224:227], v[66:69]
	v_mfma_f32_16x16x32_bf16 v[118:121], v[176:179], v[204:207], v[118:121]
	v_mfma_f32_16x16x32_bf16 v[110:113], v[196:199], v[204:207], v[110:113]
	v_mfma_f32_16x16x32_bf16 v[102:105], v[176:179], v[212:215], v[102:105]
	v_mfma_f32_16x16x32_bf16 v[94:97], v[196:199], v[212:215], v[94:97]
	v_mfma_f32_16x16x32_bf16 v[86:89], v[176:179], v[220:223], v[86:89]
	v_mfma_f32_16x16x32_bf16 v[78:81], v[196:199], v[220:223], v[78:81]
	v_mfma_f32_16x16x32_bf16 v[70:73], v[176:179], v[228:231], v[70:73]
	v_mfma_f32_16x16x32_bf16 v[66:69], v[196:199], v[228:231], v[66:69]
	s_setprio 0
	s_barrier
	s_add_i32 s58, s48, s27
	v_lshl_add_u64 v[184:185], s[30:31], 0, v[132:133]
	s_mov_b32 m0, s58
	ds_read_b128 v[200:203], v162 offset:16384
	ds_read_b128 v[204:207], v162 offset:17408
	ds_read_b128 v[208:211], v162 offset:18432
	ds_read_b128 v[212:215], v162 offset:19456
	ds_read_b128 v[216:219], v162 offset:20480
	ds_read_b128 v[220:223], v162 offset:21504
	ds_read_b128 v[224:227], v162 offset:22528
	ds_read_b128 v[228:231], v162 offset:23552
	global_load_lds_dwordx4 v[184:185], off
	s_add_i32 m0, s58, 0x2000
	s_add_u32 s58, s30, 0x100000
	v_lshl_add_u64 v[232:233], s[30:31], 0, v[136:137]
	s_addc_u32 s59, s31, 0
	s_add_i32 s60, s49, s27
	global_load_lds_dwordx4 v[232:233], off
	v_lshl_add_u64 v[234:235], s[58:59], 0, v[132:133]
	s_mov_b32 m0, s60
	v_lshl_add_u64 v[236:237], s[34:35], 0, v[134:135]
	global_load_lds_dwordx4 v[234:235], off
	v_lshl_add_u64 v[234:235], s[58:59], 0, v[136:137]
	s_add_i32 m0, s60, 0x2000
	s_nop 0
	global_load_lds_dwordx4 v[234:235], off
	v_lshl_add_u64 v[234:235], s[34:35], 0, v[130:131]
	s_mov_b32 m0, s40
	s_nop 0
	global_load_lds_dwordx4 v[234:235], off
	s_mov_b32 m0, s41
	s_nop 0
	global_load_lds_dwordx4 v[236:237], off
	s_waitcnt vmcnt(8)
	s_waitcnt lgkmcnt(0)
	s_barrier
; #define PG8_STAGE(bufoff, gbase, voff) do { _Pragma("unroll") for (int _i = 0; _i < 2; ++_i) \
;         __builtin_amdgcn_global_load_lds((const unsigned*)((const char*)(gbase) + (voff)[_i]), (PG8_LAS unsigned*)(lds + (bufoff) + ldsw + _i * 8192), 16, 0, 0); } while (0)
; #define PG8_LDA(dst, b, h) do { _Pragma("unroll") for (int m = 0; m < 4; ++m) _Pragma("unroll") for (int k = 0; k < 2; ++k) dst[m][k] = *(const PG8_LAS bf16x8*)(lds + PG8_SA(b, h) + aoff + m * 2048 + k * 1024); } while (0)
; #define PG8_LDB(dst, b, h) do { _Pragma("unroll") for (int n = 0; n < 2; ++n) _Pragma("unroll") for (int k = 0; k < 2; ++k) dst[n][k] = *(const PG8_LAS bf16x8*)(lds + PG8_SB(b, h) + boff + n * 2048 + k * 1024); } while (0)
; #define PG8_MMA(ai, bj, At, Bt) do { __builtin_amdgcn_s_setprio(1); _Pragma("unroll") for (int m = 0; m < 4; ++m) _Pragma("unroll") for (int n = 0; n < 2; ++n) _Pragma("unroll") for (int k = 0; k < 2; ++k) \
;         acc[ai][bj][m][n] = __builtin_amdgcn_mfma_f32_16x16x32_bf16(Bt[n][k], At[m][k], acc[ai][bj][m][n], 0, 0, 0); __builtin_amdgcn_s_setprio(0); } while (0)
; #define PG8_WAIT_V(n) asm volatile("s_waitcnt vmcnt(" #n ")" ::: "memory")
; #define PG8_WAIT_L(n) asm volatile("s_waitcnt lgkmcnt(" #n ")" ::: "memory")
; #define PG8_BAR __builtin_amdgcn_s_barrier()
; #define PG8_SCHED __builtin_amdgcn_sched_barrier(0)
; template <class Epi, class Sched, bool ALIGN_EPI = false, bool SP2 = false>
; __device__ __forceinline__ void gemm_phase(PG8_LAS unsigned char* lds, const Gemm g, const Sched& S, const Epi& E) {
;     ...
;             PG8_WAIT_V(8); PG8_WAIT_L(0); PG8_BAR; PG8_MMA(1, 0, At, B0); PG8_MMA(1, 1, At, B1); PG8_BAR; PG8_SCHED;
;             PG8_LDB(B0, 1, 0); PG8_LDB(B1, 1, 1); PG8_SCHED; PG8_LDA(At, 1, 0); PG8_STAGE(PG8_SA(0, 1), a2 + hstepA, voffA);
;             PG8_WAIT_V(8); PG8_WAIT_L(0); PG8_BAR; PG8_MMA(0, 0, At, B0); PG8_MMA(0, 1, At, B1); PG8_BAR; PG8_SCHED;
	s_setprio 1
	v_mfma_f32_16x16x32_bf16 v[62:65], v[148:151], v[200:203], v[62:65]
	v_mfma_f32_16x16x32_bf16 v[58:61], v[164:167], v[200:203], v[58:61]
	v_mfma_f32_16x16x32_bf16 v[50:53], v[148:151], v[208:211], v[50:53]
	v_mfma_f32_16x16x32_bf16 v[42:45], v[164:167], v[208:211], v[42:45]
	v_mfma_f32_16x16x32_bf16 v[34:37], v[148:151], v[216:219], v[34:37]
	v_mfma_f32_16x16x32_bf16 v[26:29], v[164:167], v[216:219], v[26:29]
	v_mfma_f32_16x16x32_bf16 v[18:21], v[148:151], v[224:227], v[18:21]
	v_mfma_f32_16x16x32_bf16 v[10:13], v[164:167], v[224:227], v[10:13]
	v_mfma_f32_16x16x32_bf16 v[62:65], v[152:155], v[204:207], v[62:65]
	v_mfma_f32_16x16x32_bf16 v[58:61], v[168:171], v[204:207], v[58:61]
	v_mfma_f32_16x16x32_bf16 v[50:53], v[152:155], v[212:215], v[50:53]
	v_mfma_f32_16x16x32_bf16 v[42:45], v[168:171], v[212:215], v[42:45]
	v_mfma_f32_16x16x32_bf16 v[34:37], v[152:155], v[220:223], v[34:37]
	v_mfma_f32_16x16x32_bf16 v[26:29], v[168:171], v[220:223], v[26:29]
	v_mfma_f32_16x16x32_bf16 v[18:21], v[152:155], v[228:231], v[18:21]
	v_mfma_f32_16x16x32_bf16 v[10:13], v[168:171], v[228:231], v[10:13]
	s_setprio 0
	s_setprio 1
	v_mfma_f32_16x16x32_bf16 v[54:57], v[172:175], v[200:203], v[54:57]
	v_mfma_f32_16x16x32_bf16 v[46:49], v[180:183], v[200:203], v[46:49]
	v_mfma_f32_16x16x32_bf16 v[38:41], v[172:175], v[208:211], v[38:41]
	v_mfma_f32_16x16x32_bf16 v[30:33], v[180:183], v[208:211], v[30:33]
	v_mfma_f32_16x16x32_bf16 v[22:25], v[172:175], v[216:219], v[22:25]
	v_mfma_f32_16x16x32_bf16 v[14:17], v[180:183], v[216:219], v[14:17]
	v_mfma_f32_16x16x32_bf16 v[6:9], v[172:175], v[224:227], v[6:9]
	v_mfma_f32_16x16x32_bf16 v[2:5], v[180:183], v[224:227], v[2:5]
	v_mfma_f32_16x16x32_bf16 v[54:57], v[176:179], v[204:207], v[54:57]
	v_mfma_f32_16x16x32_bf16 v[46:49], v[196:199], v[204:207], v[46:49]
	v_mfma_f32_16x16x32_bf16 v[38:41], v[176:179], v[212:215], v[38:41]
	v_mfma_f32_16x16x32_bf16 v[30:33], v[196:199], v[212:215], v[30:33]
	v_mfma_f32_16x16x32_bf16 v[22:25], v[176:179], v[220:223], v[22:25]
	v_mfma_f32_16x16x32_bf16 v[14:17], v[196:199], v[220:223], v[14:17]
	v_mfma_f32_16x16x32_bf16 v[6:9], v[176:179], v[228:231], v[6:9]
	v_mfma_f32_16x16x32_bf16 v[2:5], v[196:199], v[228:231], v[2:5]
	s_setprio 0
	s_barrier
	s_add_i32 s58, 0, 0x18000
	v_add_u32_e32 v138, s58, v156
	s_add_i32 s59, 0, 0x1c000
	ds_read_b128 v[148:151], v138
	ds_read_b128 v[152:155], v138 offset:1024
	ds_read_b128 v[164:167], v138 offset:2048
	ds_read_b128 v[168:171], v138 offset:3072
	v_add_u32_e32 v138, s59, v156
	ds_read_b128 v[172:175], v138
	ds_read_b128 v[176:179], v138 offset:1024
	ds_read_b128 v[180:183], v138 offset:2048
	ds_read_b128 v[196:199], v138 offset:3072
	s_add_u32 s34, s34, 0x100000
	s_addc_u32 s35, s35, 0
	s_mov_b32 m0, s42
	v_lshl_add_u64 v[238:239], s[34:35], 0, v[130:131]
	ds_read_b128 v[200:203], v162 offset:32768
	ds_read_b128 v[204:207], v162 offset:33792
	ds_read_b128 v[208:211], v162 offset:34816
	ds_read_b128 v[212:215], v162 offset:35840
	ds_read_b128 v[216:219], v162 offset:36864
	ds_read_b128 v[220:223], v162 offset:37888
	ds_read_b128 v[224:227], v162 offset:38912
	ds_read_b128 v[228:231], v162 offset:39936
	global_load_lds_dwordx4 v[238:239], off
	v_lshl_add_u64 v[238:239], s[34:35], 0, v[134:135]
	s_mov_b32 m0, s43
	s_nop 0
	global_load_lds_dwordx4 v[238:239], off
	s_waitcnt vmcnt(8)
	s_waitcnt lgkmcnt(0)
	s_barrier
	s_setprio 1
	v_mfma_f32_16x16x32_bf16 v[126:129], v[148:151], v[200:203], v[126:129]
	v_mfma_f32_16x16x32_bf16 v[122:125], v[164:167], v[200:203], v[122:125]
	v_mfma_f32_16x16x32_bf16 v[114:117], v[148:151], v[208:211], v[114:117]
	v_mfma_f32_16x16x32_bf16 v[106:109], v[164:167], v[208:211], v[106:109]
	v_mfma_f32_16x16x32_bf16 v[98:101], v[148:151], v[216:219], v[98:101]
	v_mfma_f32_16x16x32_bf16 v[90:93], v[164:167], v[216:219], v[90:93]
	v_mfma_f32_16x16x32_bf16 v[82:85], v[148:151], v[224:227], v[82:85]
	v_mfma_f32_16x16x32_bf16 v[74:77], v[164:167], v[224:227], v[74:77]
	v_mfma_f32_16x16x32_bf16 v[126:129], v[152:155], v[204:207], v[126:129]
	v_mfma_f32_16x16x32_bf16 v[122:125], v[168:171], v[204:207], v[122:125]
	v_mfma_f32_16x16x32_bf16 v[114:117], v[152:155], v[212:215], v[114:117]
	v_mfma_f32_16x16x32_bf16 v[106:109], v[168:171], v[212:215], v[106:109]
	v_mfma_f32_16x16x32_bf16 v[98:101], v[152:155], v[220:223], v[98:101]
	v_mfma_f32_16x16x32_bf16 v[90:93], v[168:171], v[220:223], v[90:93]
	v_mfma_f32_16x16x32_bf16 v[82:85], v[152:155], v[228:231], v[82:85]
	v_mfma_f32_16x16x32_bf16 v[74:77], v[168:171], v[228:231], v[74:77]
	s_setprio 0
	s_setprio 1
	v_mfma_f32_16x16x32_bf16 v[118:121], v[172:175], v[200:203], v[118:121]
	v_mfma_f32_16x16x32_bf16 v[110:113], v[180:183], v[200:203], v[110:113]
	v_mfma_f32_16x16x32_bf16 v[102:105], v[172:175], v[208:211], v[102:105]
	v_mfma_f32_16x16x32_bf16 v[94:97], v[180:183], v[208:211], v[94:97]
	v_mfma_f32_16x16x32_bf16 v[86:89], v[172:175], v[216:219], v[86:89]
	v_mfma_f32_16x16x32_bf16 v[78:81], v[180:183], v[216:219], v[78:81]
	v_mfma_f32_16x16x32_bf16 v[70:73], v[172:175], v[224:227], v[70:73]
	v_mfma_f32_16x16x32_bf16 v[66:69], v[180:183], v[224:227], v[66:69]
	v_mfma_f32_16x16x32_bf16 v[118:121], v[176:179], v[204:207], v[118:121]
	v_mfma_f32_16x16x32_bf16 v[110:113], v[196:199], v[204:207], v[110:113]
	v_mfma_f32_16x16x32_bf16 v[102:105], v[176:179], v[212:215], v[102:105]
	v_mfma_f32_16x16x32_bf16 v[94:97], v[196:199], v[212:215], v[94:97]
	v_mfma_f32_16x16x32_bf16 v[86:89], v[176:179], v[220:223], v[86:89]
	v_mfma_f32_16x16x32_bf16 v[78:81], v[196:199], v[220:223], v[78:81]
	v_mfma_f32_16x16x32_bf16 v[70:73], v[176:179], v[228:231], v[70:73]
	v_mfma_f32_16x16x32_bf16 v[66:69], v[196:199], v[228:231], v[66:69]
	s_setprio 0
	s_barrier
; #define PG8_STAGE(bufoff, gbase, voff) do { _Pragma("unroll") for (int _i = 0; _i < 2; ++_i) \
;         __builtin_amdgcn_global_load_lds((const unsigned*)((const char*)(gbase) + (voff)[_i]), (PG8_LAS unsigned*)(lds + (bufoff) + ldsw + _i * 8192), 16, 0, 0); } while (0)
; #define PG8_LDA(dst, b, h) do { _Pragma("unroll") for (int m = 0; m < 4; ++m) _Pragma("unroll") for (int k = 0; k < 2; ++k) dst[m][k] = *(const PG8_LAS bf16x8*)(lds + PG8_SA(b, h) + aoff + m * 2048 + k * 1024); } while (0)
; #define PG8_MMA(ai, bj, At, Bt) do { __builtin_amdgcn_s_setprio(1); _Pragma("unroll") for (int m = 0; m < 4; ++m) _Pragma("unroll") for (int n = 0; n < 2; ++n) _Pragma("unroll") for (int k = 0; k < 2; ++k) \
;         acc[ai][bj][m][n] = __builtin_amdgcn_mfma_f32_16x16x32_bf16(Bt[n][k], At[m][k], acc[ai][bj][m][n], 0, 0, 0); __builtin_amdgcn_s_setprio(0); } while (0)
; #define PG8_WAIT_V(n) asm volatile("s_waitcnt vmcnt(" #n ")" ::: "memory")
; #define PG8_WAIT_L(n) asm volatile("s_waitcnt lgkmcnt(" #n ")" ::: "memory")
; #define PG8_BAR __builtin_amdgcn_s_barrier()
; #define PG8_SCHED __builtin_amdgcn_sched_barrier(0)
; template <class Epi, class Sched, bool ALIGN_EPI = false, bool SP2 = false>
; __device__ __forceinline__ void gemm_phase(PG8_LAS unsigned char* lds, const Gemm g, const Sched& S, const Epi& E) {
;     ...
;             PG8_LDA(At, 1, 1); PG8_STAGE(PG8_SB(1, 0), b3, voffB); PG8_STAGE(PG8_SB(1, 1), b3 + hstepB, voffB); PG8_STAGE(PG8_SA(1, 0), a3, voffA);
;             PG8_WAIT_V(8); PG8_WAIT_L(0); PG8_BAR; PG8_MMA(1, 0, At, B0); PG8_MMA(1, 1, At, B1); PG8_BAR; PG8_SCHED;
;     ...
;         if constexpr (ALIGN_EPI) { if (wr == 0) PG8_BAR; }
	s_add_i32 s34, s58, s27
	v_lshl_add_u64 v[184:185], v[184:185], 0, s[8:9]
	s_mov_b32 m0, s34
	ds_read_b128 v[200:203], v162 offset:49152
	ds_read_b128 v[204:207], v162 offset:50176
	ds_read_b128 v[208:211], v162 offset:51200
	ds_read_b128 v[212:215], v162 offset:52224
	ds_read_b128 v[216:219], v162 offset:53248
	ds_read_b128 v[220:223], v162 offset:54272
	ds_read_b128 v[224:227], v162 offset:55296
	ds_read_b128 v[228:231], v162 offset:56320
	global_load_lds_dwordx4 v[184:185], off
	s_add_i32 m0, s34, 0x2000
	s_add_u32 s30, s30, 0x100080
	v_lshl_add_u64 v[184:185], v[232:233], 0, s[8:9]
	s_addc_u32 s31, s31, 0
	s_add_i32 s34, s59, s27
	global_load_lds_dwordx4 v[184:185], off
	v_lshl_add_u64 v[184:185], s[30:31], 0, v[132:133]
	s_mov_b32 m0, s34
	s_nop 0
	global_load_lds_dwordx4 v[184:185], off
	v_lshl_add_u64 v[184:185], s[30:31], 0, v[136:137]
	s_add_i32 m0, s34, 0x2000
	s_nop 0
	global_load_lds_dwordx4 v[184:185], off
	v_lshl_add_u64 v[184:185], v[234:235], 0, s[8:9]
	s_mov_b32 m0, s44
	s_nop 0
	global_load_lds_dwordx4 v[184:185], off
	v_lshl_add_u64 v[184:185], v[236:237], 0, s[8:9]
	s_mov_b32 m0, s45
	s_nop 0
	global_load_lds_dwordx4 v[184:185], off
	s_waitcnt vmcnt(8)
	s_waitcnt lgkmcnt(0)
	s_barrier
	s_setprio 1
	v_mfma_f32_16x16x32_bf16 v[62:65], v[148:151], v[200:203], v[62:65]
	v_mfma_f32_16x16x32_bf16 v[58:61], v[164:167], v[200:203], v[58:61]
	v_mfma_f32_16x16x32_bf16 v[50:53], v[148:151], v[208:211], v[50:53]
	v_mfma_f32_16x16x32_bf16 v[42:45], v[164:167], v[208:211], v[42:45]
	v_mfma_f32_16x16x32_bf16 v[34:37], v[148:151], v[216:219], v[34:37]
	v_mfma_f32_16x16x32_bf16 v[26:29], v[164:167], v[216:219], v[26:29]
	v_mfma_f32_16x16x32_bf16 v[18:21], v[148:151], v[224:227], v[18:21]
	v_mfma_f32_16x16x32_bf16 v[10:13], v[164:167], v[224:227], v[10:13]
	v_mfma_f32_16x16x32_bf16 v[62:65], v[152:155], v[204:207], v[62:65]
	v_mfma_f32_16x16x32_bf16 v[58:61], v[168:171], v[204:207], v[58:61]
	v_mfma_f32_16x16x32_bf16 v[50:53], v[152:155], v[212:215], v[50:53]
	v_mfma_f32_16x16x32_bf16 v[42:45], v[168:171], v[212:215], v[42:45]
	v_mfma_f32_16x16x32_bf16 v[34:37], v[152:155], v[220:223], v[34:37]
	v_mfma_f32_16x16x32_bf16 v[26:29], v[168:171], v[220:223], v[26:29]
	v_mfma_f32_16x16x32_bf16 v[18:21], v[152:155], v[228:231], v[18:21]
	v_mfma_f32_16x16x32_bf16 v[10:13], v[168:171], v[228:231], v[10:13]
	s_setprio 0
	s_setprio 1
	v_mfma_f32_16x16x32_bf16 v[54:57], v[172:175], v[200:203], v[54:57]
	v_mfma_f32_16x16x32_bf16 v[46:49], v[180:183], v[200:203], v[46:49]
	v_mfma_f32_16x16x32_bf16 v[38:41], v[172:175], v[208:211], v[38:41]
	v_mfma_f32_16x16x32_bf16 v[30:33], v[180:183], v[208:211], v[30:33]
	v_mfma_f32_16x16x32_bf16 v[22:25], v[172:175], v[216:219], v[22:25]
	v_mfma_f32_16x16x32_bf16 v[14:17], v[180:183], v[216:219], v[14:17]
	v_mfma_f32_16x16x32_bf16 v[6:9], v[172:175], v[224:227], v[6:9]
	v_mfma_f32_16x16x32_bf16 v[2:5], v[180:183], v[224:227], v[2:5]
	v_mfma_f32_16x16x32_bf16 v[54:57], v[176:179], v[204:207], v[54:57]
	v_mfma_f32_16x16x32_bf16 v[46:49], v[196:199], v[204:207], v[46:49]
	v_mfma_f32_16x16x32_bf16 v[38:41], v[176:179], v[212:215], v[38:41]
	v_mfma_f32_16x16x32_bf16 v[30:33], v[196:199], v[212:215], v[30:33]
	v_mfma_f32_16x16x32_bf16 v[22:25], v[176:179], v[220:223], v[22:25]
	v_mfma_f32_16x16x32_bf16 v[14:17], v[196:199], v[220:223], v[14:17]
	v_mfma_f32_16x16x32_bf16 v[6:9], v[176:179], v[228:231], v[6:9]
	v_mfma_f32_16x16x32_bf16 v[2:5], v[196:199], v[228:231], v[2:5]
	s_setprio 0
	s_barrier
	s_add_i32 s57, s57, 2
	s_add_u32 s28, s28, 0x100
	s_addc_u32 s29, s29, 0
	s_add_u32 s55, s55, 0x100
	s_addc_u32 s56, s56, 0
	s_cmp_gt_u32 s57, 61
	s_cbranch_scc0 .LBB0_1895
	s_and_b64 vcc, exec, s[10:11]
	s_cbranch_vccz .LBB0_1898
	s_barrier

; #define PG8_STAGE(bufoff, gbase, voff) do { _Pragma("unroll") for (int _i = 0; _i < 2; ++_i) \
;         __builtin_amdgcn_global_load_lds((const unsigned*)((const char*)(gbase) + (voff)[_i]), (PG8_LAS unsigned*)(lds + (bufoff) + ldsw + _i * 8192), 16, 0, 0); } while (0)
; #define PG8_LDA(dst, b, h) do { _Pragma("unroll") for (int m = 0; m < 4; ++m) _Pragma("unroll") for (int k = 0; k < 2; ++k) dst[m][k] = *(const PG8_LAS bf16x8*)(lds + PG8_SA(b, h) + aoff + m * 2048 + k * 1024); } while (0)
; #define PG8_LDB(dst, b, h) do { _Pragma("unroll") for (int n = 0; n < 2; ++n) _Pragma("unroll") for (int k = 0; k < 2; ++k) dst[n][k] = *(const PG8_LAS bf16x8*)(lds + PG8_SB(b, h) + boff + n * 2048 + k * 1024); } while (0)
; #define PG8_MMA(ai, bj, At, Bt) do { __builtin_amdgcn_s_setprio(1); _Pragma("unroll") for (int m = 0; m < 4; ++m) _Pragma("unroll") for (int n = 0; n < 2; ++n) _Pragma("unroll") for (int k = 0; k < 2; ++k) \
;         acc[ai][bj][m][n] = __builtin_amdgcn_mfma_f32_16x16x32_bf16(Bt[n][k], At[m][k], acc[ai][bj][m][n], 0, 0, 0); __builtin_amdgcn_s_setprio(0); } while (0)
; #define PG8_WAIT_V(n) asm volatile("s_waitcnt vmcnt(" #n ")" ::: "memory")
; #define PG8_WAIT_L(n) asm volatile("s_waitcnt lgkmcnt(" #n ")" ::: "memory")
; #define PG8_BAR __builtin_amdgcn_s_barrier()
; template <class Epi, class Sched, bool ALIGN_EPI = false, bool SP2 = false>
; __device__ __forceinline__ void gemm_phase(PG8_LAS unsigned char* lds, const Gemm g, const Sched& S, const Epi& E) {
;     ...
;             const char* a1 = cA + (size_t)(t + 1) * kstep;
;             const char* a2 = last ? nA : cA + (size_t)(t + 2) * kstep; const char* b2 = last ? nB : cB + (size_t)(t + 2) * kstep;
;             const char* a3 = a2 + kstep; const char* b3 = b2 + kstep;
;             if (last && has_next) S.a_ready(nxt);
;             if constexpr (SP2) {
;             PG8_LDB(B0, 0, 0); PG8_LDB(B1, 0, 1); PG8_SCHED; PG8_LDA(At, 0, 0); PG8_STAGE(PG8_SA(1, 1), a1 + hstepA, voffA);
;             PG8_WAIT_V(8); PG8_WAIT_L(0); PG8_BAR; PG8_MMA(0, 0, At, B0); PG8_MMA(0, 1, At, B1); PG8_BAR; PG8_SCHED;
;             PG8_LDA(At, 0, 1); PG8_STAGE(PG8_SB(0, 0), b2, voffB); PG8_STAGE(PG8_SB(0, 1), b2 + hstepB, voffB); PG8_STAGE(PG8_SA(0, 0), a2, voffA);
;             PG8_WAIT_V(8); PG8_WAIT_L(0); PG8_BAR; PG8_MMA(1, 0, At, B0); PG8_MMA(1, 1, At, B1); PG8_BAR; PG8_SCHED;
.LBB0_2347:
	v_add_u32_e32 v3, s57, v161
	ds_read_b128 v[152:155], v3
	ds_read_b128 v[156:159], v3 offset:1024
	ds_read_b128 v[168:171], v3 offset:2048
	ds_read_b128 v[172:175], v3 offset:3072
	v_add_u32_e32 v3, s58, v161
	ds_read_b128 v[176:179], v3
	ds_read_b128 v[180:183], v3 offset:1024
	ds_read_b128 v[184:187], v3 offset:2048
	ds_read_b128 v[188:191], v3 offset:3072
	s_add_u32 s4, s40, 0xffe00080
	s_addc_u32 s5, s41, -1
	s_cmp_eq_u32 s67, 0
	s_cselect_b32 s6, s63, s4
	s_cselect_b32 s4, s64, s65
	s_cselect_b32 s7, s31, s5
	s_cselect_b32 s5, s29, s66
	v_lshl_add_u64 v[4:5], s[40:41], 0, v[142:143]
	s_add_i32 m0, s39, 0xc000
	ds_read_b128 v[192:195], v167
	ds_read_b128 v[196:199], v167 offset:1024
	ds_read_b128 v[200:203], v167 offset:2048
	ds_read_b128 v[204:207], v167 offset:3072
	ds_read_b128 v[208:211], v167 offset:4096
	ds_read_b128 v[212:215], v167 offset:5120
	ds_read_b128 v[216:219], v167 offset:6144
	ds_read_b128 v[220:223], v167 offset:7168
	global_load_lds_dwordx4 v[4:5], off
	v_lshl_add_u64 v[4:5], s[40:41], 0, v[144:145]
	s_add_i32 m0, s39, 0xe000
	s_nop 0
	global_load_lds_dwordx4 v[4:5], off
	s_waitcnt vmcnt(8)
	s_waitcnt lgkmcnt(0)
	s_barrier
	s_setprio 1
	v_mfma_f32_16x16x32_bf16 v[130:133], v[152:155], v[192:195], v[130:133]
	v_mfma_f32_16x16x32_bf16 v[126:129], v[168:171], v[192:195], v[126:129]
	v_mfma_f32_16x16x32_bf16 v[114:117], v[152:155], v[200:203], v[114:117]
	v_mfma_f32_16x16x32_bf16 v[110:113], v[168:171], v[200:203], v[110:113]
	v_mfma_f32_16x16x32_bf16 v[98:101], v[152:155], v[208:211], v[98:101]
	v_mfma_f32_16x16x32_bf16 v[94:97], v[168:171], v[208:211], v[94:97]
	v_mfma_f32_16x16x32_bf16 v[82:85], v[152:155], v[216:219], v[82:85]
	v_mfma_f32_16x16x32_bf16 v[78:81], v[168:171], v[216:219], v[78:81]
	v_mfma_f32_16x16x32_bf16 v[130:133], v[156:159], v[196:199], v[130:133]
	v_mfma_f32_16x16x32_bf16 v[126:129], v[172:175], v[196:199], v[126:129]
	v_mfma_f32_16x16x32_bf16 v[114:117], v[156:159], v[204:207], v[114:117]
	v_mfma_f32_16x16x32_bf16 v[110:113], v[172:175], v[204:207], v[110:113]
	v_mfma_f32_16x16x32_bf16 v[98:101], v[156:159], v[212:215], v[98:101]
	v_mfma_f32_16x16x32_bf16 v[94:97], v[172:175], v[212:215], v[94:97]
	v_mfma_f32_16x16x32_bf16 v[82:85], v[156:159], v[220:223], v[82:85]
	v_mfma_f32_16x16x32_bf16 v[78:81], v[172:175], v[220:223], v[78:81]
	s_setprio 0
	s_setprio 1
	v_mfma_f32_16x16x32_bf16 v[122:125], v[176:179], v[192:195], v[122:125]
	v_mfma_f32_16x16x32_bf16 v[118:121], v[184:187], v[192:195], v[118:121]
	v_mfma_f32_16x16x32_bf16 v[106:109], v[176:179], v[200:203], v[106:109]
	v_mfma_f32_16x16x32_bf16 v[102:105], v[184:187], v[200:203], v[102:105]
	v_mfma_f32_16x16x32_bf16 v[90:93], v[176:179], v[208:211], v[90:93]
	v_mfma_f32_16x16x32_bf16 v[86:89], v[184:187], v[208:211], v[86:89]
	v_mfma_f32_16x16x32_bf16 v[74:77], v[176:179], v[216:219], v[74:77]
	v_mfma_f32_16x16x32_bf16 v[70:73], v[184:187], v[216:219], v[70:73]
	v_mfma_f32_16x16x32_bf16 v[122:125], v[180:183], v[196:199], v[122:125]
	v_mfma_f32_16x16x32_bf16 v[118:121], v[188:191], v[196:199], v[118:121]
	v_mfma_f32_16x16x32_bf16 v[106:109], v[180:183], v[204:207], v[106:109]
	v_mfma_f32_16x16x32_bf16 v[102:105], v[188:191], v[204:207], v[102:105]
	v_mfma_f32_16x16x32_bf16 v[90:93], v[180:183], v[212:215], v[90:93]
	v_mfma_f32_16x16x32_bf16 v[86:89], v[188:191], v[212:215], v[86:89]
	v_mfma_f32_16x16x32_bf16 v[74:77], v[180:183], v[220:223], v[74:77]
	v_mfma_f32_16x16x32_bf16 v[70:73], v[188:191], v[220:223], v[70:73]
	s_setprio 0
	s_barrier
	s_add_i32 s42, s57, s48
	v_lshl_add_u64 v[224:225], s[4:5], 0, v[136:137]
	s_mov_b32 m0, s42
	ds_read_b128 v[192:195], v167 offset:16384
	ds_read_b128 v[196:199], v167 offset:17408
	ds_read_b128 v[200:203], v167 offset:18432
	ds_read_b128 v[204:207], v167 offset:19456
	ds_read_b128 v[208:211], v167 offset:20480
	ds_read_b128 v[212:215], v167 offset:21504
	ds_read_b128 v[216:219], v167 offset:22528
	ds_read_b128 v[220:223], v167 offset:23552
	global_load_lds_dwordx4 v[224:225], off
	s_add_i32 m0, s42, 0x2000
	s_add_u32 s42, s4, 0x200000
	v_lshl_add_u64 v[226:227], s[4:5], 0, v[140:141]
	s_addc_u32 s43, s5, 0
	s_add_i32 s69, s58, s48
	global_load_lds_dwordx4 v[226:227], off
	v_lshl_add_u64 v[4:5], s[42:43], 0, v[136:137]
	s_mov_b32 m0, s69
	v_lshl_add_u64 v[228:229], s[6:7], 0, v[134:135]
	global_load_lds_dwordx4 v[4:5], off
	v_lshl_add_u64 v[4:5], s[42:43], 0, v[140:141]
	s_add_i32 m0, s69, 0x2000
	v_lshl_add_u64 v[230:231], s[6:7], 0, v[138:139]
	global_load_lds_dwordx4 v[4:5], off
	s_mov_b32 m0, s39
	s_nop 0
	global_load_lds_dwordx4 v[228:229], off
	s_mov_b32 m0, s49
	s_nop 0
	global_load_lds_dwordx4 v[230:231], off
	s_waitcnt vmcnt(8)
	s_waitcnt lgkmcnt(0)
	s_barrier
; #define PG8_STAGE(bufoff, gbase, voff) do { _Pragma("unroll") for (int _i = 0; _i < 2; ++_i) \
;         __builtin_amdgcn_global_load_lds((const unsigned*)((const char*)(gbase) + (voff)[_i]), (PG8_LAS unsigned*)(lds + (bufoff) + ldsw + _i * 8192), 16, 0, 0); } while (0)
; #define PG8_LDA(dst, b, h) do { _Pragma("unroll") for (int m = 0; m < 4; ++m) _Pragma("unroll") for (int k = 0; k < 2; ++k) dst[m][k] = *(const PG8_LAS bf16x8*)(lds + PG8_SA(b, h) + aoff + m * 2048 + k * 1024); } while (0)
; #define PG8_LDB(dst, b, h) do { _Pragma("unroll") for (int n = 0; n < 2; ++n) _Pragma("unroll") for (int k = 0; k < 2; ++k) dst[n][k] = *(const PG8_LAS bf16x8*)(lds + PG8_SB(b, h) + boff + n * 2048 + k * 1024); } while (0)
; #define PG8_MMA(ai, bj, At, Bt) do { __builtin_amdgcn_s_setprio(1); _Pragma("unroll") for (int m = 0; m < 4; ++m) _Pragma("unroll") for (int n = 0; n < 2; ++n) _Pragma("unroll") for (int k = 0; k < 2; ++k) \
;         acc[ai][bj][m][n] = __builtin_amdgcn_mfma_f32_16x16x32_bf16(Bt[n][k], At[m][k], acc[ai][bj][m][n], 0, 0, 0); __builtin_amdgcn_s_setprio(0); } while (0)
; #define PG8_WAIT_V(n) asm volatile("s_waitcnt vmcnt(" #n ")" ::: "memory")
; #define PG8_WAIT_L(n) asm volatile("s_waitcnt lgkmcnt(" #n ")" ::: "memory")
; #define PG8_BAR __builtin_amdgcn_s_barrier()
; #define PG8_SCHED __builtin_amdgcn_sched_barrier(0)
; template <class Epi, class Sched, bool ALIGN_EPI = false, bool SP2 = false>
; __device__ __forceinline__ void gemm_phase(PG8_LAS unsigned char* lds, const Gemm g, const Sched& S, const Epi& E) {
;     ...
;             PG8_WAIT_V(8); PG8_WAIT_L(0); PG8_BAR; PG8_MMA(1, 0, At, B0); PG8_MMA(1, 1, At, B1); PG8_BAR; PG8_SCHED;
;             PG8_LDB(B0, 1, 0); PG8_LDB(B1, 1, 1); PG8_SCHED; PG8_LDA(At, 1, 0); PG8_STAGE(PG8_SA(0, 1), a2 + hstepA, voffA);
;             PG8_WAIT_V(8); PG8_WAIT_L(0); PG8_BAR; PG8_MMA(0, 0, At, B0); PG8_MMA(0, 1, At, B1); PG8_BAR; PG8_SCHED;
	s_setprio 1
	v_mfma_f32_16x16x32_bf16 v[66:69], v[152:155], v[192:195], v[66:69]
	v_mfma_f32_16x16x32_bf16 v[62:65], v[168:171], v[192:195], v[62:65]
	v_mfma_f32_16x16x32_bf16 v[50:53], v[152:155], v[200:203], v[50:53]
	v_mfma_f32_16x16x32_bf16 v[46:49], v[168:171], v[200:203], v[46:49]
	v_mfma_f32_16x16x32_bf16 v[34:37], v[152:155], v[208:211], v[34:37]
	v_mfma_f32_16x16x32_bf16 v[30:33], v[168:171], v[208:211], v[30:33]
	v_mfma_f32_16x16x32_bf16 v[18:21], v[152:155], v[216:219], v[18:21]
	v_mfma_f32_16x16x32_bf16 v[14:17], v[168:171], v[216:219], v[14:17]
	v_mfma_f32_16x16x32_bf16 v[66:69], v[156:159], v[196:199], v[66:69]
	v_mfma_f32_16x16x32_bf16 v[62:65], v[172:175], v[196:199], v[62:65]
	v_mfma_f32_16x16x32_bf16 v[50:53], v[156:159], v[204:207], v[50:53]
	v_mfma_f32_16x16x32_bf16 v[46:49], v[172:175], v[204:207], v[46:49]
	v_mfma_f32_16x16x32_bf16 v[34:37], v[156:159], v[212:215], v[34:37]
	v_mfma_f32_16x16x32_bf16 v[30:33], v[172:175], v[212:215], v[30:33]
	v_mfma_f32_16x16x32_bf16 v[18:21], v[156:159], v[220:223], v[18:21]
	v_mfma_f32_16x16x32_bf16 v[14:17], v[172:175], v[220:223], v[14:17]
	s_setprio 0
	s_setprio 1
	v_mfma_f32_16x16x32_bf16 v[58:61], v[176:179], v[192:195], v[58:61]
	v_mfma_f32_16x16x32_bf16 v[54:57], v[184:187], v[192:195], v[54:57]
	v_mfma_f32_16x16x32_bf16 v[42:45], v[176:179], v[200:203], v[42:45]
	v_mfma_f32_16x16x32_bf16 v[38:41], v[184:187], v[200:203], v[38:41]
	v_mfma_f32_16x16x32_bf16 v[26:29], v[176:179], v[208:211], v[26:29]
	v_mfma_f32_16x16x32_bf16 v[22:25], v[184:187], v[208:211], v[22:25]
	v_mfma_f32_16x16x32_bf16 v[10:13], v[176:179], v[216:219], v[10:13]
	v_mfma_f32_16x16x32_bf16 v[4:7], v[184:187], v[216:219], v[6:9]
	v_mfma_f32_16x16x32_bf16 v[58:61], v[180:183], v[196:199], v[58:61]
	v_mfma_f32_16x16x32_bf16 v[54:57], v[188:191], v[196:199], v[54:57]
	v_mfma_f32_16x16x32_bf16 v[42:45], v[180:183], v[204:207], v[42:45]
	v_mfma_f32_16x16x32_bf16 v[38:41], v[188:191], v[204:207], v[38:41]
	v_mfma_f32_16x16x32_bf16 v[26:29], v[180:183], v[212:215], v[26:29]
	v_mfma_f32_16x16x32_bf16 v[22:25], v[188:191], v[212:215], v[22:25]
	v_mfma_f32_16x16x32_bf16 v[10:13], v[180:183], v[220:223], v[10:13]
	v_mfma_f32_16x16x32_bf16 v[4:7], v[188:191], v[220:223], v[4:7]
	s_setprio 0
	s_barrier
	s_add_i32 s42, 0, 0x18000
	v_add_u32_e32 v3, s42, v161
	s_add_i32 s43, 0, 0x1c000
	ds_read_b128 v[152:155], v3
	ds_read_b128 v[156:159], v3 offset:1024
	ds_read_b128 v[168:171], v3 offset:2048
	ds_read_b128 v[172:175], v3 offset:3072
	v_add_u32_e32 v3, s43, v161
	ds_read_b128 v[176:179], v3
	ds_read_b128 v[180:183], v3 offset:1024
	ds_read_b128 v[184:187], v3 offset:2048
	ds_read_b128 v[188:191], v3 offset:3072
	s_add_u32 s6, s6, 0x200000
	s_addc_u32 s7, s7, 0
	s_mov_b32 m0, s50
	v_lshl_add_u64 v[8:9], s[6:7], 0, v[134:135]
	ds_read_b128 v[192:195], v167 offset:32768
	ds_read_b128 v[196:199], v167 offset:33792
	ds_read_b128 v[200:203], v167 offset:34816
	ds_read_b128 v[204:207], v167 offset:35840
	ds_read_b128 v[208:211], v167 offset:36864
	ds_read_b128 v[212:215], v167 offset:37888
	ds_read_b128 v[216:219], v167 offset:38912
	ds_read_b128 v[220:223], v167 offset:39936
	global_load_lds_dwordx4 v[8:9], off
	v_lshl_add_u64 v[8:9], s[6:7], 0, v[138:139]
	s_mov_b32 m0, s51
	s_nop 0
	global_load_lds_dwordx4 v[8:9], off
	s_waitcnt vmcnt(8)
	s_waitcnt lgkmcnt(0)
	s_barrier
	s_setprio 1
	v_mfma_f32_16x16x32_bf16 v[130:133], v[152:155], v[192:195], v[130:133]
	v_mfma_f32_16x16x32_bf16 v[126:129], v[168:171], v[192:195], v[126:129]
	v_mfma_f32_16x16x32_bf16 v[114:117], v[152:155], v[200:203], v[114:117]
	v_mfma_f32_16x16x32_bf16 v[110:113], v[168:171], v[200:203], v[110:113]
	v_mfma_f32_16x16x32_bf16 v[98:101], v[152:155], v[208:211], v[98:101]
	v_mfma_f32_16x16x32_bf16 v[94:97], v[168:171], v[208:211], v[94:97]
	v_mfma_f32_16x16x32_bf16 v[82:85], v[152:155], v[216:219], v[82:85]
	v_mfma_f32_16x16x32_bf16 v[78:81], v[168:171], v[216:219], v[78:81]
	v_mfma_f32_16x16x32_bf16 v[130:133], v[156:159], v[196:199], v[130:133]
	v_mfma_f32_16x16x32_bf16 v[126:129], v[172:175], v[196:199], v[126:129]
	v_mfma_f32_16x16x32_bf16 v[114:117], v[156:159], v[204:207], v[114:117]
	v_mfma_f32_16x16x32_bf16 v[110:113], v[172:175], v[204:207], v[110:113]
	v_mfma_f32_16x16x32_bf16 v[98:101], v[156:159], v[212:215], v[98:101]
	v_mfma_f32_16x16x32_bf16 v[94:97], v[172:175], v[212:215], v[94:97]
	v_mfma_f32_16x16x32_bf16 v[82:85], v[156:159], v[220:223], v[82:85]
	v_mfma_f32_16x16x32_bf16 v[78:81], v[172:175], v[220:223], v[78:81]
	s_setprio 0
	s_setprio 1
	v_mfma_f32_16x16x32_bf16 v[122:125], v[176:179], v[192:195], v[122:125]
	v_mfma_f32_16x16x32_bf16 v[118:121], v[184:187], v[192:195], v[118:121]
	v_mfma_f32_16x16x32_bf16 v[106:109], v[176:179], v[200:203], v[106:109]
	v_mfma_f32_16x16x32_bf16 v[102:105], v[184:187], v[200:203], v[102:105]
	v_mfma_f32_16x16x32_bf16 v[90:93], v[176:179], v[208:211], v[90:93]
	v_mfma_f32_16x16x32_bf16 v[86:89], v[184:187], v[208:211], v[86:89]
	v_mfma_f32_16x16x32_bf16 v[74:77], v[176:179], v[216:219], v[74:77]
	v_mfma_f32_16x16x32_bf16 v[70:73], v[184:187], v[216:219], v[70:73]
	v_mfma_f32_16x16x32_bf16 v[122:125], v[180:183], v[196:199], v[122:125]
	v_mfma_f32_16x16x32_bf16 v[118:121], v[188:191], v[196:199], v[118:121]
	v_mfma_f32_16x16x32_bf16 v[106:109], v[180:183], v[204:207], v[106:109]
	v_mfma_f32_16x16x32_bf16 v[102:105], v[188:191], v[204:207], v[102:105]
	v_mfma_f32_16x16x32_bf16 v[90:93], v[180:183], v[212:215], v[90:93]
	v_mfma_f32_16x16x32_bf16 v[86:89], v[188:191], v[212:215], v[86:89]
	v_mfma_f32_16x16x32_bf16 v[74:77], v[180:183], v[220:223], v[74:77]
	v_mfma_f32_16x16x32_bf16 v[70:73], v[188:191], v[220:223], v[70:73]
	s_setprio 0
	s_barrier
; #define PG8_STAGE(bufoff, gbase, voff) do { _Pragma("unroll") for (int _i = 0; _i < 2; ++_i) \
;         __builtin_amdgcn_global_load_lds((const unsigned*)((const char*)(gbase) + (voff)[_i]), (PG8_LAS unsigned*)(lds + (bufoff) + ldsw + _i * 8192), 16, 0, 0); } while (0)
; #define PG8_LDA(dst, b, h) do { _Pragma("unroll") for (int m = 0; m < 4; ++m) _Pragma("unroll") for (int k = 0; k < 2; ++k) dst[m][k] = *(const PG8_LAS bf16x8*)(lds + PG8_SA(b, h) + aoff + m * 2048 + k * 1024); } while (0)
; #define PG8_MMA(ai, bj, At, Bt) do { __builtin_amdgcn_s_setprio(1); _Pragma("unroll") for (int m = 0; m < 4; ++m) _Pragma("unroll") for (int n = 0; n < 2; ++n) _Pragma("unroll") for (int k = 0; k < 2; ++k) \
;         acc[ai][bj][m][n] = __builtin_amdgcn_mfma_f32_16x16x32_bf16(Bt[n][k], At[m][k], acc[ai][bj][m][n], 0, 0, 0); __builtin_amdgcn_s_setprio(0); } while (0)
; #define PG8_WAIT_V(n) asm volatile("s_waitcnt vmcnt(" #n ")" ::: "memory")
; #define PG8_WAIT_L(n) asm volatile("s_waitcnt lgkmcnt(" #n ")" ::: "memory")
; #define PG8_BAR __builtin_amdgcn_s_barrier()
; #define PG8_SCHED __builtin_amdgcn_sched_barrier(0)
; template <class Epi, class Sched, bool ALIGN_EPI = false, bool SP2 = false>
; __device__ __forceinline__ void gemm_phase(PG8_LAS unsigned char* lds, const Gemm g, const Sched& S, const Epi& E) {
;     ...
;         for (int t = 0; t < nt; t += 2) {
;             const bool last = (t == nt - 2);
;             if constexpr (Epi::KHOOK) {
;                 if (t == 2) E.fill(cur);
;                 if (t > 0 && (t & 15) == 0) E.khook(acc, (t >> 4) - 1, wr, fr);
;     ...
;             PG8_LDA(At, 1, 1); PG8_STAGE(PG8_SB(1, 0), b3, voffB); PG8_STAGE(PG8_SB(1, 1), b3 + hstepB, voffB); PG8_STAGE(PG8_SA(1, 0), a3, voffA);
;             PG8_WAIT_V(8); PG8_WAIT_L(0); PG8_BAR; PG8_MMA(1, 0, At, B0); PG8_MMA(1, 1, At, B1); PG8_BAR; PG8_SCHED;
	s_add_i32 s6, s42, s48
	v_lshl_add_u64 v[8:9], v[224:225], 0, s[16:17]
	s_mov_b32 m0, s6
	ds_read_b128 v[192:195], v167 offset:49152
	ds_read_b128 v[196:199], v167 offset:50176
	ds_read_b128 v[200:203], v167 offset:51200
	ds_read_b128 v[204:207], v167 offset:52224
	ds_read_b128 v[208:211], v167 offset:53248
	ds_read_b128 v[212:215], v167 offset:54272
	ds_read_b128 v[216:219], v167 offset:55296
	ds_read_b128 v[220:223], v167 offset:56320
	global_load_lds_dwordx4 v[8:9], off
	s_add_i32 m0, s6, 0x2000
	s_add_u32 s4, s4, 0x200080
	v_lshl_add_u64 v[8:9], v[226:227], 0, s[16:17]
	s_addc_u32 s5, s5, 0
	s_add_i32 s6, s43, s48
	global_load_lds_dwordx4 v[8:9], off
	v_lshl_add_u64 v[8:9], s[4:5], 0, v[136:137]
	s_mov_b32 m0, s6
	s_nop 0
	global_load_lds_dwordx4 v[8:9], off
	v_lshl_add_u64 v[8:9], s[4:5], 0, v[140:141]
	s_add_i32 m0, s6, 0x2000
	s_nop 0
	global_load_lds_dwordx4 v[8:9], off
	v_lshl_add_u64 v[8:9], v[228:229], 0, s[16:17]
	s_mov_b32 m0, s53
	s_nop 0
	global_load_lds_dwordx4 v[8:9], off
	v_lshl_add_u64 v[8:9], v[230:231], 0, s[16:17]
	s_mov_b32 m0, s54
	s_nop 0
	global_load_lds_dwordx4 v[8:9], off
	s_waitcnt vmcnt(8)
	s_waitcnt lgkmcnt(0)
	s_barrier
	s_setprio 1
	v_mfma_f32_16x16x32_bf16 v[66:69], v[152:155], v[192:195], v[66:69]
	v_mfma_f32_16x16x32_bf16 v[62:65], v[168:171], v[192:195], v[62:65]
	v_mfma_f32_16x16x32_bf16 v[50:53], v[152:155], v[200:203], v[50:53]
	v_mfma_f32_16x16x32_bf16 v[46:49], v[168:171], v[200:203], v[46:49]
	v_mfma_f32_16x16x32_bf16 v[34:37], v[152:155], v[208:211], v[34:37]
	v_mfma_f32_16x16x32_bf16 v[30:33], v[168:171], v[208:211], v[30:33]
	v_mfma_f32_16x16x32_bf16 v[18:21], v[152:155], v[216:219], v[18:21]
	v_mfma_f32_16x16x32_bf16 v[14:17], v[168:171], v[216:219], v[14:17]
	v_mfma_f32_16x16x32_bf16 v[66:69], v[156:159], v[196:199], v[66:69]
	v_mfma_f32_16x16x32_bf16 v[62:65], v[172:175], v[196:199], v[62:65]
	v_mfma_f32_16x16x32_bf16 v[50:53], v[156:159], v[204:207], v[50:53]
	v_mfma_f32_16x16x32_bf16 v[46:49], v[172:175], v[204:207], v[46:49]
	v_mfma_f32_16x16x32_bf16 v[34:37], v[156:159], v[212:215], v[34:37]
	v_mfma_f32_16x16x32_bf16 v[30:33], v[172:175], v[212:215], v[30:33]
	v_mfma_f32_16x16x32_bf16 v[18:21], v[156:159], v[220:223], v[18:21]
	v_mfma_f32_16x16x32_bf16 v[14:17], v[172:175], v[220:223], v[14:17]
	s_setprio 0
	s_setprio 1
	v_mfma_f32_16x16x32_bf16 v[58:61], v[176:179], v[192:195], v[58:61]
	v_mfma_f32_16x16x32_bf16 v[54:57], v[184:187], v[192:195], v[54:57]
	v_mfma_f32_16x16x32_bf16 v[42:45], v[176:179], v[200:203], v[42:45]
	v_mfma_f32_16x16x32_bf16 v[38:41], v[184:187], v[200:203], v[38:41]
	v_mfma_f32_16x16x32_bf16 v[26:29], v[176:179], v[208:211], v[26:29]
	v_mfma_f32_16x16x32_bf16 v[22:25], v[184:187], v[208:211], v[22:25]
	v_mfma_f32_16x16x32_bf16 v[8:11], v[176:179], v[216:219], v[10:13]
	v_mfma_f32_16x16x32_bf16 v[4:7], v[184:187], v[216:219], v[4:7]
	v_mfma_f32_16x16x32_bf16 v[58:61], v[180:183], v[196:199], v[58:61]
	v_mfma_f32_16x16x32_bf16 v[54:57], v[188:191], v[196:199], v[54:57]
	v_mfma_f32_16x16x32_bf16 v[42:45], v[180:183], v[204:207], v[42:45]
	v_mfma_f32_16x16x32_bf16 v[38:41], v[188:191], v[204:207], v[38:41]
	v_mfma_f32_16x16x32_bf16 v[26:29], v[180:183], v[212:215], v[26:29]
	v_mfma_f32_16x16x32_bf16 v[22:25], v[188:191], v[212:215], v[22:25]
	v_mfma_f32_16x16x32_bf16 v[10:13], v[180:183], v[220:223], v[8:11]
	v_mfma_f32_16x16x32_bf16 v[6:9], v[188:191], v[220:223], v[4:7]
	s_setprio 0
	s_barrier
	s_add_i32 s4, s68, 2
	s_addk_i32 s67, 0x80
	s_add_u32 s40, s40, 0x100
	s_addc_u32 s41, s41, 0
	s_add_u32 s65, s65, 0x100
	s_addc_u32 s66, s66, 0
	s_cmpk_gt_u32 s68, 0x7d
	s_cbranch_scc1 .LBB0_2354
	s_mov_b32 s68, s4
	s_cmp_lt_i32 s68, 2
	s_cbranch_scc1 .LBB0_2342
